# v12 + MFMA pair order grouped by weight fragment, no snake at group turns
# speedup vs baseline: 1.0066x; 1.0002x over previous
; #define PG8_STAGE(bufoff, gbase, voff) do { _Pragma("unroll") for (int _i = 0; _i < 2; ++_i) \
;         __builtin_amdgcn_global_load_lds((const unsigned*)((const char*)(gbase) + (voff)[_i]), (PG8_LAS unsigned*)(lds + (bufoff) + ldsw + _i * 8192), 16, 0, 0); } while (0)
; #define PG8_LDA(dst, b, h) do { _Pragma("unroll") for (int m = 0; m < 4; ++m) _Pragma("unroll") for (int k = 0; k < 2; ++k) dst[m][k] = *(const PG8_LAS bf16x8*)(lds + PG8_SA(b, h) + aoff + m * 2048 + k * 1024); } while (0)
; #define PG8_LDB(dst, b, h) do { _Pragma("unroll") for (int n = 0; n < 2; ++n) _Pragma("unroll") for (int k = 0; k < 2; ++k) dst[n][k] = *(const PG8_LAS bf16x8*)(lds + PG8_SB(b, h) + boff + n * 2048 + k * 1024); } while (0)
; #define PG8_MMA(ai, bj, At, Bt) do { __builtin_amdgcn_s_setprio(1); _Pragma("unroll") for (int m = 0; m < 4; ++m) _Pragma("unroll") for (int n = 0; n < 2; ++n) _Pragma("unroll") for (int k = 0; k < 2; ++k) \
;         acc[ai][bj][m][n] = __builtin_amdgcn_mfma_f32_16x16x32_bf16(Bt[n][k], At[m][k], acc[ai][bj][m][n], 0, 0, 0); __builtin_amdgcn_s_setprio(0); } while (0)
; #define PG8_WAIT_V(n) asm volatile("s_waitcnt vmcnt(" #n ")" ::: "memory")
; #define PG8_WAIT_L(n) asm volatile("s_waitcnt lgkmcnt(" #n ")" ::: "memory")
; template <class Epi, class Sched, bool ALIGN_EPI = false, bool SP2 = false>
; __device__ __forceinline__ void gemm_phase(PG8_LAS unsigned char* lds, const Gemm g, const Sched& S, const Epi& E) {
;     ...
;             const bool last = (t == nt - 2);
;             const char* a1 = cA + (size_t)(t + 1) * kstep;
;             const char* a2 = last ? nA : cA + (size_t)(t + 2) * kstep; const char* b2 = last ? nB : cB + (size_t)(t + 2) * kstep;
;             const char* a3 = a2 + kstep; const char* b3 = b2 + kstep;
;             if (last && has_next) S.a_ready(nxt);
;             if constexpr (SP2) {
;             PG8_LDB(B0, 0, 0); PG8_LDB(B1, 0, 1); PG8_SCHED; PG8_LDA(At, 0, 0); PG8_STAGE(PG8_SA(1, 1), a1 + hstep, voffA);
;             PG8_WAIT_V(8); PG8_WAIT_L(0); PG8_BAR; PG8_MMA(0, 0, At, B0); PG8_MMA(0, 1, At, B1); PG8_BAR; PG8_SCHED;
;             PG8_LDA(At, 0, 1); PG8_STAGE(PG8_SB(0, 0), b2, voffB); PG8_STAGE(PG8_SB(0, 1), b2 + hstep, voffB); PG8_STAGE(PG8_SA(0, 0), a2, voffA);
;             PG8_WAIT_V(8); PG8_WAIT_L(0); PG8_BAR; PG8_MMA(1, 0, At, B0); PG8_MMA(1, 1, At, B1); PG8_BAR; PG8_SCHED;
.LBB0_202:
	s_add_i32 s78, s38, 2
	s_add_u32 s79, s22, 0x80
	s_addc_u32 s39, s23, 0
	s_cmp_eq_u32 s33, s38
	s_cselect_b32 s39, s7, s39
	s_cselect_b32 s38, s6, s79
	v_add_u32_e32 v0, s19, v150
	s_cselect_b32 s81, s17, s77
	s_cselect_b32 s80, s16, s76
	s_add_i32 s79, 0, 0x14000
	ds_read_b128 v[152:155], v0
	ds_read_b128 v[156:159], v0 offset:1024
	ds_read_b128 v[160:163], v0 offset:2048
	ds_read_b128 v[164:167], v0 offset:3072
	v_add_u32_e32 v0, s79, v150
	ds_read_b128 v[168:171], v0
	ds_read_b128 v[172:175], v0 offset:1024
	ds_read_b128 v[176:179], v0 offset:2048
	ds_read_b128 v[184:187], v0 offset:3072
	v_lshl_add_u64 v[2:3], s[22:23], 0, v[144:145]
	s_add_i32 m0, s42, 0xc000
	ds_read_b128 v[188:191], v151
	ds_read_b128 v[192:195], v151 offset:1024
	ds_read_b128 v[196:199], v151 offset:2048
	ds_read_b128 v[200:203], v151 offset:3072
	ds_read_b128 v[204:207], v151 offset:4096
	ds_read_b128 v[230:233], v151 offset:5120
	ds_read_b128 v[234:237], v151 offset:6144
	ds_read_b128 v[238:241], v151 offset:7168
	global_load_lds_dwordx4 v[2:3], off
	v_lshl_add_u64 v[2:3], s[22:23], 0, v[146:147]
	s_add_i32 m0, s42, 0xe000
	s_nop 0
	global_load_lds_dwordx4 v[2:3], off
	s_waitcnt vmcnt(8)
	s_waitcnt lgkmcnt(0)
	s_barrier
	s_setprio 1
	s_waitcnt lgkmcnt(0)
	v_mfma_f32_16x16x32_bf16 v[132:135], v[152:155], v[188:191], v[132:135]
	v_mfma_f32_16x16x32_bf16 v[132:135], v[156:159], v[192:195], v[132:135]
	v_mfma_f32_16x16x32_bf16 v[116:119], v[152:155], v[196:199], v[116:119]
	v_mfma_f32_16x16x32_bf16 v[116:119], v[156:159], v[200:203], v[116:119]
	v_mfma_f32_16x16x32_bf16 v[100:103], v[152:155], v[204:207], v[100:103]
	v_mfma_f32_16x16x32_bf16 v[100:103], v[156:159], v[230:233], v[100:103]
	v_mfma_f32_16x16x32_bf16 v[84:87], v[152:155], v[234:237], v[84:87]
	v_mfma_f32_16x16x32_bf16 v[84:87], v[156:159], v[238:241], v[84:87]
	v_mfma_f32_16x16x32_bf16 v[128:131], v[160:163], v[188:191], v[128:131]
	v_mfma_f32_16x16x32_bf16 v[128:131], v[164:167], v[192:195], v[128:131]
	v_mfma_f32_16x16x32_bf16 v[112:115], v[160:163], v[196:199], v[112:115]
	v_mfma_f32_16x16x32_bf16 v[112:115], v[164:167], v[200:203], v[112:115]
	v_mfma_f32_16x16x32_bf16 v[96:99], v[160:163], v[204:207], v[96:99]
	v_mfma_f32_16x16x32_bf16 v[96:99], v[164:167], v[230:233], v[96:99]
	v_mfma_f32_16x16x32_bf16 v[80:83], v[160:163], v[234:237], v[80:83]
	v_mfma_f32_16x16x32_bf16 v[80:83], v[164:167], v[238:241], v[80:83]
	s_setprio 0
	s_setprio 1
	v_mfma_f32_16x16x32_bf16 v[124:127], v[168:171], v[188:191], v[124:127]
	v_mfma_f32_16x16x32_bf16 v[124:127], v[172:175], v[192:195], v[124:127]
	v_mfma_f32_16x16x32_bf16 v[108:111], v[168:171], v[196:199], v[108:111]
	v_mfma_f32_16x16x32_bf16 v[108:111], v[172:175], v[200:203], v[108:111]
	v_mfma_f32_16x16x32_bf16 v[92:95], v[168:171], v[204:207], v[92:95]
	v_mfma_f32_16x16x32_bf16 v[92:95], v[172:175], v[230:233], v[92:95]
	v_mfma_f32_16x16x32_bf16 v[76:79], v[168:171], v[234:237], v[76:79]
	v_mfma_f32_16x16x32_bf16 v[76:79], v[172:175], v[238:241], v[76:79]
	v_mfma_f32_16x16x32_bf16 v[120:123], v[176:179], v[188:191], v[120:123]
	v_mfma_f32_16x16x32_bf16 v[120:123], v[184:187], v[192:195], v[120:123]
	v_mfma_f32_16x16x32_bf16 v[104:107], v[176:179], v[196:199], v[104:107]
	v_mfma_f32_16x16x32_bf16 v[104:107], v[184:187], v[200:203], v[104:107]
	v_mfma_f32_16x16x32_bf16 v[88:91], v[176:179], v[204:207], v[88:91]
	v_mfma_f32_16x16x32_bf16 v[88:91], v[184:187], v[230:233], v[88:91]
	v_mfma_f32_16x16x32_bf16 v[72:75], v[176:179], v[234:237], v[72:75]
	v_mfma_f32_16x16x32_bf16 v[72:75], v[184:187], v[238:241], v[72:75]
	s_setprio 0
	s_barrier
	s_add_i32 s82, s19, s20
	v_lshl_add_u64 v[2:3], s[80:81], 0, v[140:141]
	s_mov_b32 m0, s82
	ds_read_b128 v[188:191], v151 offset:16384
	ds_read_b128 v[192:195], v151 offset:17408
	ds_read_b128 v[196:199], v151 offset:18432
	ds_read_b128 v[200:203], v151 offset:19456
	ds_read_b128 v[204:207], v151 offset:20480
	ds_read_b128 v[230:233], v151 offset:21504
	ds_read_b128 v[234:237], v151 offset:22528
	ds_read_b128 v[238:241], v151 offset:23552
	global_load_lds_dwordx4 v[2:3], off
	s_add_i32 m0, s82, 0x2000
	v_lshl_add_u64 v[180:181], s[80:81], 0, v[136:137]
	s_add_u32 s80, s80, s48
	s_addc_u32 s81, s81, s49
	s_add_i32 s79, s79, s20
	global_load_lds_dwordx4 v[180:181], off
	v_lshl_add_u64 v[208:209], s[80:81], 0, v[140:141]
	s_mov_b32 m0, s79
	v_lshl_add_u64 v[216:217], s[80:81], 0, v[136:137]
	global_load_lds_dwordx4 v[208:209], off
	s_add_i32 m0, s79, 0x2000
	v_lshl_add_u64 v[224:225], s[38:39], 0, v[142:143]
	global_load_lds_dwordx4 v[216:217], off
	s_mov_b32 m0, s42
	v_lshl_add_u64 v[226:227], s[38:39], 0, v[138:139]
	global_load_lds_dwordx4 v[224:225], off
	s_mov_b32 m0, s45
	s_nop 0
	global_load_lds_dwordx4 v[226:227], off
	s_waitcnt vmcnt(8)
	s_waitcnt lgkmcnt(0)
	s_barrier
; #define PG8_STAGE(bufoff, gbase, voff) do { _Pragma("unroll") for (int _i = 0; _i < 2; ++_i) \
;         __builtin_amdgcn_global_load_lds((const unsigned*)((const char*)(gbase) + (voff)[_i]), (PG8_LAS unsigned*)(lds + (bufoff) + ldsw + _i * 8192), 16, 0, 0); } while (0)
; #define PG8_LDA(dst, b, h) do { _Pragma("unroll") for (int m = 0; m < 4; ++m) _Pragma("unroll") for (int k = 0; k < 2; ++k) dst[m][k] = *(const PG8_LAS bf16x8*)(lds + PG8_SA(b, h) + aoff + m * 2048 + k * 1024); } while (0)
; #define PG8_LDB(dst, b, h) do { _Pragma("unroll") for (int n = 0; n < 2; ++n) _Pragma("unroll") for (int k = 0; k < 2; ++k) dst[n][k] = *(const PG8_LAS bf16x8*)(lds + PG8_SB(b, h) + boff + n * 2048 + k * 1024); } while (0)
; #define PG8_MMA(ai, bj, At, Bt) do { __builtin_amdgcn_s_setprio(1); _Pragma("unroll") for (int m = 0; m < 4; ++m) _Pragma("unroll") for (int n = 0; n < 2; ++n) _Pragma("unroll") for (int k = 0; k < 2; ++k) \
;         acc[ai][bj][m][n] = __builtin_amdgcn_mfma_f32_16x16x32_bf16(Bt[n][k], At[m][k], acc[ai][bj][m][n], 0, 0, 0); __builtin_amdgcn_s_setprio(0); } while (0)
; #define PG8_WAIT_V(n) asm volatile("s_waitcnt vmcnt(" #n ")" ::: "memory")
; #define PG8_WAIT_L(n) asm volatile("s_waitcnt lgkmcnt(" #n ")" ::: "memory")
; #define PG8_BAR __builtin_amdgcn_s_barrier()
; #define PG8_SCHED __builtin_amdgcn_sched_barrier(0)
; template <class Epi, class Sched, bool ALIGN_EPI = false, bool SP2 = false>
; __device__ __forceinline__ void gemm_phase(PG8_LAS unsigned char* lds, const Gemm g, const Sched& S, const Epi& E) {
;     ...
;             PG8_WAIT_V(8); PG8_WAIT_L(0); PG8_BAR; PG8_MMA(1, 0, At, B0); PG8_MMA(1, 1, At, B1); PG8_BAR; PG8_SCHED;
;             PG8_LDB(B0, 1, 0); PG8_LDB(B1, 1, 1); PG8_SCHED; PG8_LDA(At, 1, 0); PG8_STAGE(PG8_SA(0, 1), a2 + hstep, voffA);
;             PG8_WAIT_V(8); PG8_WAIT_L(0); PG8_BAR; PG8_MMA(0, 0, At, B0); PG8_MMA(0, 1, At, B1); PG8_BAR; PG8_SCHED;
	s_setprio 1
	s_waitcnt lgkmcnt(0)
	v_mfma_f32_16x16x32_bf16 v[68:71], v[152:155], v[188:191], v[68:71]
	v_mfma_f32_16x16x32_bf16 v[68:71], v[156:159], v[192:195], v[68:71]
	v_mfma_f32_16x16x32_bf16 v[52:55], v[152:155], v[196:199], v[52:55]
	v_mfma_f32_16x16x32_bf16 v[52:55], v[156:159], v[200:203], v[52:55]
	v_mfma_f32_16x16x32_bf16 v[36:39], v[152:155], v[204:207], v[36:39]
	v_mfma_f32_16x16x32_bf16 v[36:39], v[156:159], v[230:233], v[36:39]
	v_mfma_f32_16x16x32_bf16 v[20:23], v[152:155], v[234:237], v[20:23]
	v_mfma_f32_16x16x32_bf16 v[20:23], v[156:159], v[238:241], v[20:23]
	v_mfma_f32_16x16x32_bf16 v[64:67], v[160:163], v[188:191], v[64:67]
	v_mfma_f32_16x16x32_bf16 v[64:67], v[164:167], v[192:195], v[64:67]
	v_mfma_f32_16x16x32_bf16 v[48:51], v[160:163], v[196:199], v[48:51]
	v_mfma_f32_16x16x32_bf16 v[48:51], v[164:167], v[200:203], v[48:51]
	v_mfma_f32_16x16x32_bf16 v[32:35], v[160:163], v[204:207], v[32:35]
	v_mfma_f32_16x16x32_bf16 v[32:35], v[164:167], v[230:233], v[32:35]
	v_mfma_f32_16x16x32_bf16 v[16:19], v[160:163], v[234:237], v[16:19]
	v_mfma_f32_16x16x32_bf16 v[16:19], v[164:167], v[238:241], v[16:19]
	s_setprio 0
	s_setprio 1
	v_mfma_f32_16x16x32_bf16 v[60:63], v[168:171], v[188:191], v[60:63]
	v_mfma_f32_16x16x32_bf16 v[60:63], v[172:175], v[192:195], v[60:63]
	v_mfma_f32_16x16x32_bf16 v[44:47], v[168:171], v[196:199], v[44:47]
	v_mfma_f32_16x16x32_bf16 v[44:47], v[172:175], v[200:203], v[44:47]
	v_mfma_f32_16x16x32_bf16 v[28:31], v[168:171], v[204:207], v[28:31]
	v_mfma_f32_16x16x32_bf16 v[28:31], v[172:175], v[230:233], v[28:31]
	v_mfma_f32_16x16x32_bf16 v[12:15], v[168:171], v[234:237], v[12:15]
	v_mfma_f32_16x16x32_bf16 v[12:15], v[172:175], v[238:241], v[12:15]
	v_mfma_f32_16x16x32_bf16 v[56:59], v[176:179], v[188:191], v[56:59]
	v_mfma_f32_16x16x32_bf16 v[56:59], v[184:187], v[192:195], v[56:59]
	v_mfma_f32_16x16x32_bf16 v[40:43], v[176:179], v[196:199], v[40:43]
	v_mfma_f32_16x16x32_bf16 v[40:43], v[184:187], v[200:203], v[40:43]
	v_mfma_f32_16x16x32_bf16 v[24:27], v[176:179], v[204:207], v[24:27]
	v_mfma_f32_16x16x32_bf16 v[24:27], v[184:187], v[230:233], v[24:27]
	v_mfma_f32_16x16x32_bf16 v[8:11], v[176:179], v[234:237], v[8:11]
	v_mfma_f32_16x16x32_bf16 v[8:11], v[184:187], v[238:241], v[8:11]
	s_setprio 0
	s_barrier
	v_add_u32_e32 v0, s91, v150
	s_add_i32 s79, 0, 0x1c000
	ds_read_b128 v[152:155], v0
	ds_read_b128 v[156:159], v0 offset:1024
	ds_read_b128 v[160:163], v0 offset:2048
	ds_read_b128 v[164:167], v0 offset:3072
	v_add_u32_e32 v0, s79, v150
	ds_read_b128 v[168:171], v0
	ds_read_b128 v[172:175], v0 offset:1024
	ds_read_b128 v[176:179], v0 offset:2048
	ds_read_b128 v[184:187], v0 offset:3072
	s_add_u32 s38, s38, s48
	s_addc_u32 s39, s39, s49
	s_mov_b32 m0, s46
	v_lshl_add_u64 v[228:229], s[38:39], 0, v[142:143]
	ds_read_b128 v[188:191], v151 offset:32768
	ds_read_b128 v[192:195], v151 offset:33792
	ds_read_b128 v[196:199], v151 offset:34816
	ds_read_b128 v[200:203], v151 offset:35840
	ds_read_b128 v[204:207], v151 offset:36864
	ds_read_b128 v[230:233], v151 offset:37888
	ds_read_b128 v[234:237], v151 offset:38912
	ds_read_b128 v[238:241], v151 offset:39936
	global_load_lds_dwordx4 v[228:229], off
	v_lshl_add_u64 v[228:229], s[38:39], 0, v[138:139]
	s_mov_b32 m0, s47
	s_nop 0
	global_load_lds_dwordx4 v[228:229], off
	s_waitcnt vmcnt(8)
	s_waitcnt lgkmcnt(0)
	s_barrier
	s_setprio 1
	s_waitcnt lgkmcnt(0)
	v_mfma_f32_16x16x32_bf16 v[132:135], v[152:155], v[188:191], v[132:135]
	v_mfma_f32_16x16x32_bf16 v[132:135], v[156:159], v[192:195], v[132:135]
	v_mfma_f32_16x16x32_bf16 v[116:119], v[152:155], v[196:199], v[116:119]
	v_mfma_f32_16x16x32_bf16 v[116:119], v[156:159], v[200:203], v[116:119]
	v_mfma_f32_16x16x32_bf16 v[100:103], v[152:155], v[204:207], v[100:103]
	v_mfma_f32_16x16x32_bf16 v[100:103], v[156:159], v[230:233], v[100:103]
	v_mfma_f32_16x16x32_bf16 v[84:87], v[152:155], v[234:237], v[84:87]
	v_mfma_f32_16x16x32_bf16 v[84:87], v[156:159], v[238:241], v[84:87]
	v_mfma_f32_16x16x32_bf16 v[128:131], v[160:163], v[188:191], v[128:131]
	v_mfma_f32_16x16x32_bf16 v[128:131], v[164:167], v[192:195], v[128:131]
	v_mfma_f32_16x16x32_bf16 v[112:115], v[160:163], v[196:199], v[112:115]
	v_mfma_f32_16x16x32_bf16 v[112:115], v[164:167], v[200:203], v[112:115]
	v_mfma_f32_16x16x32_bf16 v[96:99], v[160:163], v[204:207], v[96:99]
	v_mfma_f32_16x16x32_bf16 v[96:99], v[164:167], v[230:233], v[96:99]
	v_mfma_f32_16x16x32_bf16 v[80:83], v[160:163], v[234:237], v[80:83]
	v_mfma_f32_16x16x32_bf16 v[80:83], v[164:167], v[238:241], v[80:83]
	s_setprio 0
	s_setprio 1
	v_mfma_f32_16x16x32_bf16 v[124:127], v[168:171], v[188:191], v[124:127]
	v_mfma_f32_16x16x32_bf16 v[124:127], v[172:175], v[192:195], v[124:127]
	v_mfma_f32_16x16x32_bf16 v[108:111], v[168:171], v[196:199], v[108:111]
	v_mfma_f32_16x16x32_bf16 v[108:111], v[172:175], v[200:203], v[108:111]
	v_mfma_f32_16x16x32_bf16 v[92:95], v[168:171], v[204:207], v[92:95]
	v_mfma_f32_16x16x32_bf16 v[92:95], v[172:175], v[230:233], v[92:95]
	v_mfma_f32_16x16x32_bf16 v[76:79], v[168:171], v[234:237], v[76:79]
	v_mfma_f32_16x16x32_bf16 v[76:79], v[172:175], v[238:241], v[76:79]
	v_mfma_f32_16x16x32_bf16 v[120:123], v[176:179], v[188:191], v[120:123]
	v_mfma_f32_16x16x32_bf16 v[120:123], v[184:187], v[192:195], v[120:123]
	v_mfma_f32_16x16x32_bf16 v[104:107], v[176:179], v[196:199], v[104:107]
	v_mfma_f32_16x16x32_bf16 v[104:107], v[184:187], v[200:203], v[104:107]
	v_mfma_f32_16x16x32_bf16 v[88:91], v[176:179], v[204:207], v[88:91]
	v_mfma_f32_16x16x32_bf16 v[88:91], v[184:187], v[230:233], v[88:91]
	v_mfma_f32_16x16x32_bf16 v[72:75], v[176:179], v[234:237], v[72:75]
	v_mfma_f32_16x16x32_bf16 v[72:75], v[184:187], v[238:241], v[72:75]
	s_setprio 0
	s_barrier
; #define PG8_STAGE(bufoff, gbase, voff) do { _Pragma("unroll") for (int _i = 0; _i < 2; ++_i) \
;         __builtin_amdgcn_global_load_lds((const unsigned*)((const char*)(gbase) + (voff)[_i]), (PG8_LAS unsigned*)(lds + (bufoff) + ldsw + _i * 8192), 16, 0, 0); } while (0)
; #define PG8_LDA(dst, b, h) do { _Pragma("unroll") for (int m = 0; m < 4; ++m) _Pragma("unroll") for (int k = 0; k < 2; ++k) dst[m][k] = *(const PG8_LAS bf16x8*)(lds + PG8_SA(b, h) + aoff + m * 2048 + k * 1024); } while (0)
; #define PG8_MMA(ai, bj, At, Bt) do { __builtin_amdgcn_s_setprio(1); _Pragma("unroll") for (int m = 0; m < 4; ++m) _Pragma("unroll") for (int n = 0; n < 2; ++n) _Pragma("unroll") for (int k = 0; k < 2; ++k) \
;         acc[ai][bj][m][n] = __builtin_amdgcn_mfma_f32_16x16x32_bf16(Bt[n][k], At[m][k], acc[ai][bj][m][n], 0, 0, 0); __builtin_amdgcn_s_setprio(0); } while (0)
; #define PG8_WAIT_V(n) asm volatile("s_waitcnt vmcnt(" #n ")" ::: "memory")
; #define PG8_WAIT_L(n) asm volatile("s_waitcnt lgkmcnt(" #n ")" ::: "memory")
; #define PG8_BAR __builtin_amdgcn_s_barrier()
; #define PG8_SCHED __builtin_amdgcn_sched_barrier(0)
; template <class Epi, class Sched, bool ALIGN_EPI = false, bool SP2 = false>
; __device__ __forceinline__ void gemm_phase(PG8_LAS unsigned char* lds, const Gemm g, const Sched& S, const Epi& E) {
;     ...
;             PG8_LDA(At, 1, 1); PG8_STAGE(PG8_SB(1, 0), b3, voffB); PG8_STAGE(PG8_SB(1, 1), b3 + hstep, voffB); PG8_STAGE(PG8_SA(1, 0), a3, voffA);
;             PG8_WAIT_V(8); PG8_WAIT_L(0); PG8_BAR; PG8_MMA(1, 0, At, B0); PG8_MMA(1, 1, At, B1); PG8_BAR; PG8_SCHED;
	s_add_i32 s38, s91, s20
	v_lshl_add_u64 v[2:3], v[2:3], 0, s[24:25]
	s_mov_b32 m0, s38
	ds_read_b128 v[188:191], v151 offset:49152
	ds_read_b128 v[192:195], v151 offset:50176
	ds_read_b128 v[196:199], v151 offset:51200
	ds_read_b128 v[200:203], v151 offset:52224
	ds_read_b128 v[204:207], v151 offset:53248
	ds_read_b128 v[230:233], v151 offset:54272
	ds_read_b128 v[234:237], v151 offset:55296
	ds_read_b128 v[238:241], v151 offset:56320
	global_load_lds_dwordx4 v[2:3], off
	v_lshl_add_u64 v[2:3], v[180:181], 0, s[24:25]
	s_add_i32 m0, s38, 0x2000
	s_add_i32 s38, s79, s20
	global_load_lds_dwordx4 v[2:3], off
	v_lshl_add_u64 v[2:3], v[208:209], 0, s[24:25]
	s_mov_b32 m0, s38
	s_nop 0
	global_load_lds_dwordx4 v[2:3], off
	v_lshl_add_u64 v[2:3], v[216:217], 0, s[24:25]
	s_add_i32 m0, s38, 0x2000
	s_nop 0
	global_load_lds_dwordx4 v[2:3], off
	v_lshl_add_u64 v[2:3], v[224:225], 0, s[24:25]
	s_mov_b32 m0, s52
	s_nop 0
	global_load_lds_dwordx4 v[2:3], off
	v_lshl_add_u64 v[2:3], v[226:227], 0, s[24:25]
	s_mov_b32 m0, s53
	s_nop 0
	global_load_lds_dwordx4 v[2:3], off
	s_waitcnt vmcnt(8)
	s_waitcnt lgkmcnt(0)
	s_barrier
	s_setprio 1
	s_waitcnt lgkmcnt(0)
	v_mfma_f32_16x16x32_bf16 v[68:71], v[152:155], v[188:191], v[68:71]
	v_mfma_f32_16x16x32_bf16 v[68:71], v[156:159], v[192:195], v[68:71]
	v_mfma_f32_16x16x32_bf16 v[52:55], v[152:155], v[196:199], v[52:55]
	v_mfma_f32_16x16x32_bf16 v[52:55], v[156:159], v[200:203], v[52:55]
	v_mfma_f32_16x16x32_bf16 v[36:39], v[152:155], v[204:207], v[36:39]
	v_mfma_f32_16x16x32_bf16 v[36:39], v[156:159], v[230:233], v[36:39]
	v_mfma_f32_16x16x32_bf16 v[20:23], v[152:155], v[234:237], v[20:23]
	v_mfma_f32_16x16x32_bf16 v[20:23], v[156:159], v[238:241], v[20:23]
	v_mfma_f32_16x16x32_bf16 v[64:67], v[160:163], v[188:191], v[64:67]
	v_mfma_f32_16x16x32_bf16 v[64:67], v[164:167], v[192:195], v[64:67]
	v_mfma_f32_16x16x32_bf16 v[48:51], v[160:163], v[196:199], v[48:51]
	v_mfma_f32_16x16x32_bf16 v[48:51], v[164:167], v[200:203], v[48:51]
	v_mfma_f32_16x16x32_bf16 v[32:35], v[160:163], v[204:207], v[32:35]
	v_mfma_f32_16x16x32_bf16 v[32:35], v[164:167], v[230:233], v[32:35]
	v_mfma_f32_16x16x32_bf16 v[16:19], v[160:163], v[234:237], v[16:19]
	v_mfma_f32_16x16x32_bf16 v[16:19], v[164:167], v[238:241], v[16:19]
	s_setprio 0
	s_setprio 1
	v_mfma_f32_16x16x32_bf16 v[60:63], v[168:171], v[188:191], v[60:63]
	v_mfma_f32_16x16x32_bf16 v[60:63], v[172:175], v[192:195], v[60:63]
	v_mfma_f32_16x16x32_bf16 v[44:47], v[168:171], v[196:199], v[44:47]
	v_mfma_f32_16x16x32_bf16 v[44:47], v[172:175], v[200:203], v[44:47]
	v_mfma_f32_16x16x32_bf16 v[28:31], v[168:171], v[204:207], v[28:31]
	v_mfma_f32_16x16x32_bf16 v[28:31], v[172:175], v[230:233], v[28:31]
	v_mfma_f32_16x16x32_bf16 v[12:15], v[168:171], v[234:237], v[12:15]
	v_mfma_f32_16x16x32_bf16 v[12:15], v[172:175], v[238:241], v[12:15]
	v_mfma_f32_16x16x32_bf16 v[56:59], v[176:179], v[188:191], v[56:59]
	v_mfma_f32_16x16x32_bf16 v[56:59], v[184:187], v[192:195], v[56:59]
	v_mfma_f32_16x16x32_bf16 v[40:43], v[176:179], v[196:199], v[40:43]
	v_mfma_f32_16x16x32_bf16 v[40:43], v[184:187], v[200:203], v[40:43]
	v_mfma_f32_16x16x32_bf16 v[24:27], v[176:179], v[204:207], v[24:27]
	v_mfma_f32_16x16x32_bf16 v[24:27], v[184:187], v[230:233], v[24:27]
	v_mfma_f32_16x16x32_bf16 v[8:11], v[176:179], v[234:237], v[8:11]
	v_mfma_f32_16x16x32_bf16 v[8:11], v[184:187], v[238:241], v[8:11]
	s_setprio 0
	s_barrier
	s_add_u32 s22, s22, 0x100
	s_addc_u32 s23, s23, 0
	s_add_u32 s76, s76, 0x100
	s_addc_u32 s77, s77, 0
	s_cmp_ge_u32 s78, s9
	s_mov_b32 s38, s78
	s_cbranch_scc0 .LBB0_202

; #define PG8_STAGE(bufoff, gbase, voff) do { _Pragma("unroll") for (int _i = 0; _i < 2; ++_i) \
;         __builtin_amdgcn_global_load_lds((const unsigned*)((const char*)(gbase) + (voff)[_i]), (PG8_LAS unsigned*)(lds + (bufoff) + ldsw + _i * 8192), 16, 0, 0); } while (0)
; #define PG8_LDA(dst, b, h) do { _Pragma("unroll") for (int m = 0; m < 4; ++m) _Pragma("unroll") for (int k = 0; k < 2; ++k) dst[m][k] = *(const PG8_LAS bf16x8*)(lds + PG8_SA(b, h) + aoff + m * 2048 + k * 1024); } while (0)
; #define PG8_LDB(dst, b, h) do { _Pragma("unroll") for (int n = 0; n < 2; ++n) _Pragma("unroll") for (int k = 0; k < 2; ++k) dst[n][k] = *(const PG8_LAS bf16x8*)(lds + PG8_SB(b, h) + boff + n * 2048 + k * 1024); } while (0)
; #define PG8_MMA(ai, bj, At, Bt) do { __builtin_amdgcn_s_setprio(1); _Pragma("unroll") for (int m = 0; m < 4; ++m) _Pragma("unroll") for (int n = 0; n < 2; ++n) _Pragma("unroll") for (int k = 0; k < 2; ++k) \
;         acc[ai][bj][m][n] = __builtin_amdgcn_mfma_f32_16x16x32_bf16(Bt[n][k], At[m][k], acc[ai][bj][m][n], 0, 0, 0); __builtin_amdgcn_s_setprio(0); } while (0)
; #define PG8_WAIT_V(n) asm volatile("s_waitcnt vmcnt(" #n ")" ::: "memory")
; template <class Epi, class Sched, bool ALIGN_EPI = false, bool SP2 = false>
; __device__ __forceinline__ void gemm_phase(PG8_LAS unsigned char* lds, const Gemm g, const Sched& S, const Epi& E) {
;     ...
;             if constexpr (Epi::KHOOK) { if ((t & 7) == 0 && t != 0) E.khook(acc, t >> 3, wr, fr, lds); }
;             const bool last = (t == nt - 2);
;             const char* a1 = cA + (size_t)(t + 1) * kstep;
;             const char* a2 = last ? nA : cA + (size_t)(t + 2) * kstep; const char* b2 = last ? nB : cB + (size_t)(t + 2) * kstep;
;             const char* a3 = a2 + kstep; const char* b3 = b2 + kstep;
;             if (last && has_next) S.a_ready(nxt);
;             if constexpr (SP2) {
;             PG8_LDB(B0, 0, 0); PG8_LDB(B1, 0, 1); PG8_SCHED; PG8_LDA(At, 0, 0); PG8_STAGE(PG8_SA(1, 1), a1 + hstep, voffA);
;             PG8_WAIT_V(8); PG8_WAIT_L(0); PG8_BAR; PG8_MMA(0, 0, At, B0); PG8_MMA(0, 1, At, B1); PG8_BAR; PG8_SCHED;
;             PG8_LDA(At, 0, 1); PG8_STAGE(PG8_SB(0, 0), b2, voffB); PG8_STAGE(PG8_SB(0, 1), b2 + hstep, voffB); PG8_STAGE(PG8_SA(0, 0), a2, voffA);
;             PG8_WAIT_V(8); PG8_WAIT_L(0); PG8_BAR; PG8_MMA(1, 0, At, B0); PG8_MMA(1, 1, At, B1); PG8_BAR; PG8_SCHED;
.LBB0_245:
	v_readlane_b32 s22, v252, 59
	v_readlane_b32 s23, v252, 60
	s_andn2_b64 vcc, exec, s[22:23]
	s_cbranch_vccnz .LBB0_252
	s_add_u32 s40, s6, s48
	s_addc_u32 s41, s7, s49
	s_add_u32 s37, s6, 0x100
	s_addc_u32 s80, s7, 0
	s_and_b64 s[22:23], s[12:13], exec
	s_cselect_b32 s23, s5, s80
	s_cselect_b32 s22, s4, s37
	s_add_u32 s37, s10, 0x100
	s_addc_u32 s82, s11, 0
	s_and_b64 s[80:81], s[12:13], exec
	s_cselect_b32 s85, s17, s82
	s_cselect_b32 s84, s16, s37
	s_add_i32 s83, 0, 0x14000
	v_add_u32_e32 v150, s19, v147
	v_add_u32_e32 v151, s83, v147
	ds_read_b128 v[152:155], v150
	ds_read_b128 v[156:159], v150 offset:1024
	ds_read_b128 v[160:163], v150 offset:2048
	ds_read_b128 v[164:167], v150 offset:3072
	ds_read_b128 v[168:171], v151
	ds_read_b128 v[172:175], v151 offset:1024
	ds_read_b128 v[176:179], v151 offset:2048
	ds_read_b128 v[184:187], v151 offset:3072
	v_lshl_add_u64 v[180:181], s[40:41], 0, v[2:3]
	s_add_i32 s37, s47, 0xc000
	v_lshl_add_u64 v[180:181], v[180:181], 0, s[24:25]
	s_mov_b32 m0, s37
	ds_read_b128 v[188:191], v149
	ds_read_b128 v[192:195], v149 offset:1024
	ds_read_b128 v[196:199], v149 offset:2048
	ds_read_b128 v[200:203], v149 offset:3072
	ds_read_b128 v[204:207], v149 offset:4096
	ds_read_b128 v[230:233], v149 offset:5120
	ds_read_b128 v[234:237], v149 offset:6144
	ds_read_b128 v[238:241], v149 offset:7168
	global_load_lds_dwordx4 v[180:181], off
	v_lshl_add_u64 v[180:181], s[40:41], 0, v[136:137]
	s_add_i32 s80, s47, 0xe000
	v_lshl_add_u64 v[180:181], v[180:181], 0, s[24:25]
	s_mov_b32 m0, s80
	s_nop 0
	global_load_lds_dwordx4 v[180:181], off
	s_waitcnt vmcnt(8)
	s_waitcnt lgkmcnt(0)
	s_barrier
	s_setprio 1
	s_waitcnt lgkmcnt(0)
	v_mfma_f32_16x16x32_bf16 v[132:135], v[152:155], v[188:191], v[132:135]
	v_mfma_f32_16x16x32_bf16 v[132:135], v[156:159], v[192:195], v[132:135]
	v_mfma_f32_16x16x32_bf16 v[116:119], v[152:155], v[196:199], v[116:119]
	v_mfma_f32_16x16x32_bf16 v[116:119], v[156:159], v[200:203], v[116:119]
	v_mfma_f32_16x16x32_bf16 v[100:103], v[152:155], v[204:207], v[100:103]
	v_mfma_f32_16x16x32_bf16 v[100:103], v[156:159], v[230:233], v[100:103]
	v_mfma_f32_16x16x32_bf16 v[84:87], v[152:155], v[234:237], v[84:87]
	v_mfma_f32_16x16x32_bf16 v[84:87], v[156:159], v[238:241], v[84:87]
	v_mfma_f32_16x16x32_bf16 v[128:131], v[160:163], v[188:191], v[128:131]
	v_mfma_f32_16x16x32_bf16 v[128:131], v[164:167], v[192:195], v[128:131]
	v_mfma_f32_16x16x32_bf16 v[112:115], v[160:163], v[196:199], v[112:115]
	v_mfma_f32_16x16x32_bf16 v[112:115], v[164:167], v[200:203], v[112:115]
	v_mfma_f32_16x16x32_bf16 v[96:99], v[160:163], v[204:207], v[96:99]
	v_mfma_f32_16x16x32_bf16 v[96:99], v[164:167], v[230:233], v[96:99]
	v_mfma_f32_16x16x32_bf16 v[80:83], v[160:163], v[234:237], v[80:83]
	v_mfma_f32_16x16x32_bf16 v[80:83], v[164:167], v[238:241], v[80:83]
	s_setprio 0
	s_setprio 1
	v_mfma_f32_16x16x32_bf16 v[124:127], v[168:171], v[188:191], v[124:127]
	v_mfma_f32_16x16x32_bf16 v[124:127], v[172:175], v[192:195], v[124:127]
	v_mfma_f32_16x16x32_bf16 v[108:111], v[168:171], v[196:199], v[108:111]
	v_mfma_f32_16x16x32_bf16 v[108:111], v[172:175], v[200:203], v[108:111]
	v_mfma_f32_16x16x32_bf16 v[92:95], v[168:171], v[204:207], v[92:95]
	v_mfma_f32_16x16x32_bf16 v[92:95], v[172:175], v[230:233], v[92:95]
	v_mfma_f32_16x16x32_bf16 v[76:79], v[168:171], v[234:237], v[76:79]
	v_mfma_f32_16x16x32_bf16 v[76:79], v[172:175], v[238:241], v[76:79]
	v_mfma_f32_16x16x32_bf16 v[120:123], v[176:179], v[188:191], v[120:123]
	v_mfma_f32_16x16x32_bf16 v[120:123], v[184:187], v[192:195], v[120:123]
	v_mfma_f32_16x16x32_bf16 v[104:107], v[176:179], v[196:199], v[104:107]
	v_mfma_f32_16x16x32_bf16 v[104:107], v[184:187], v[200:203], v[104:107]
	v_mfma_f32_16x16x32_bf16 v[88:91], v[176:179], v[204:207], v[88:91]
	v_mfma_f32_16x16x32_bf16 v[88:91], v[184:187], v[230:233], v[88:91]
	v_mfma_f32_16x16x32_bf16 v[72:75], v[176:179], v[234:237], v[72:75]
	v_mfma_f32_16x16x32_bf16 v[72:75], v[184:187], v[238:241], v[72:75]
	s_setprio 0
	s_barrier
	s_add_i32 s81, s19, s46
	s_add_i32 s82, s81, 0x2000
	v_lshl_add_u64 v[208:209], s[84:85], 0, v[0:1]
	s_mov_b32 m0, s81
	s_add_u32 s40, s84, s48
	ds_read_b128 v[188:191], v149 offset:16384
	ds_read_b128 v[192:195], v149 offset:17408
	ds_read_b128 v[196:199], v149 offset:18432
	ds_read_b128 v[200:203], v149 offset:19456
	ds_read_b128 v[204:207], v149 offset:20480
	ds_read_b128 v[230:233], v149 offset:21504
	ds_read_b128 v[234:237], v149 offset:22528
	ds_read_b128 v[238:241], v149 offset:23552
	global_load_lds_dwordx4 v[208:209], off
	v_lshl_add_u64 v[216:217], s[84:85], 0, v[138:139]
	s_mov_b32 m0, s82
	s_addc_u32 s41, s85, s49
	s_add_i32 s83, s83, s46
	global_load_lds_dwordx4 v[216:217], off
	v_lshl_add_u64 v[224:225], s[40:41], 0, v[0:1]
	s_mov_b32 m0, s83
	s_add_i32 s84, s83, 0x2000
	global_load_lds_dwordx4 v[224:225], off
	v_lshl_add_u64 v[226:227], s[40:41], 0, v[138:139]
	s_mov_b32 m0, s84
	v_lshl_add_u64 v[228:229], s[22:23], 0, v[2:3]
	global_load_lds_dwordx4 v[226:227], off
	s_mov_b32 m0, s47
	v_lshl_add_u64 v[242:243], s[22:23], 0, v[136:137]
	global_load_lds_dwordx4 v[228:229], off
	s_mov_b32 m0, s52
	s_nop 0
	global_load_lds_dwordx4 v[242:243], off
	s_waitcnt vmcnt(8)
	s_waitcnt lgkmcnt(0)
	s_barrier
; #define PG8_STAGE(bufoff, gbase, voff) do { _Pragma("unroll") for (int _i = 0; _i < 2; ++_i) \
;         __builtin_amdgcn_global_load_lds((const unsigned*)((const char*)(gbase) + (voff)[_i]), (PG8_LAS unsigned*)(lds + (bufoff) + ldsw + _i * 8192), 16, 0, 0); } while (0)
; #define PG8_LDA(dst, b, h) do { _Pragma("unroll") for (int m = 0; m < 4; ++m) _Pragma("unroll") for (int k = 0; k < 2; ++k) dst[m][k] = *(const PG8_LAS bf16x8*)(lds + PG8_SA(b, h) + aoff + m * 2048 + k * 1024); } while (0)
; #define PG8_LDB(dst, b, h) do { _Pragma("unroll") for (int n = 0; n < 2; ++n) _Pragma("unroll") for (int k = 0; k < 2; ++k) dst[n][k] = *(const PG8_LAS bf16x8*)(lds + PG8_SB(b, h) + boff + n * 2048 + k * 1024); } while (0)
; #define PG8_MMA(ai, bj, At, Bt) do { __builtin_amdgcn_s_setprio(1); _Pragma("unroll") for (int m = 0; m < 4; ++m) _Pragma("unroll") for (int n = 0; n < 2; ++n) _Pragma("unroll") for (int k = 0; k < 2; ++k) \
;         acc[ai][bj][m][n] = __builtin_amdgcn_mfma_f32_16x16x32_bf16(Bt[n][k], At[m][k], acc[ai][bj][m][n], 0, 0, 0); __builtin_amdgcn_s_setprio(0); } while (0)
; #define PG8_WAIT_V(n) asm volatile("s_waitcnt vmcnt(" #n ")" ::: "memory")
; #define PG8_WAIT_L(n) asm volatile("s_waitcnt lgkmcnt(" #n ")" ::: "memory")
; #define PG8_BAR __builtin_amdgcn_s_barrier()
; #define PG8_SCHED __builtin_amdgcn_sched_barrier(0)
; template <class Epi, class Sched, bool ALIGN_EPI = false, bool SP2 = false>
; __device__ __forceinline__ void gemm_phase(PG8_LAS unsigned char* lds, const Gemm g, const Sched& S, const Epi& E) {
;     ...
;             PG8_WAIT_V(8); PG8_WAIT_L(0); PG8_BAR; PG8_MMA(1, 0, At, B0); PG8_MMA(1, 1, At, B1); PG8_BAR; PG8_SCHED;
;             PG8_LDB(B0, 1, 0); PG8_LDB(B1, 1, 1); PG8_SCHED; PG8_LDA(At, 1, 0); PG8_STAGE(PG8_SA(0, 1), a2 + hstep, voffA);
;             PG8_WAIT_V(8); PG8_WAIT_L(0); PG8_BAR; PG8_MMA(0, 0, At, B0); PG8_MMA(0, 1, At, B1); PG8_BAR; PG8_SCHED;
	s_setprio 1
	s_waitcnt lgkmcnt(0)
	v_mfma_f32_16x16x32_bf16 v[68:71], v[152:155], v[188:191], v[68:71]
	v_mfma_f32_16x16x32_bf16 v[68:71], v[156:159], v[192:195], v[68:71]
	v_mfma_f32_16x16x32_bf16 v[52:55], v[152:155], v[196:199], v[52:55]
	v_mfma_f32_16x16x32_bf16 v[52:55], v[156:159], v[200:203], v[52:55]
	v_mfma_f32_16x16x32_bf16 v[36:39], v[152:155], v[204:207], v[36:39]
	v_mfma_f32_16x16x32_bf16 v[36:39], v[156:159], v[230:233], v[36:39]
	v_mfma_f32_16x16x32_bf16 v[20:23], v[152:155], v[234:237], v[20:23]
	v_mfma_f32_16x16x32_bf16 v[20:23], v[156:159], v[238:241], v[20:23]
	v_mfma_f32_16x16x32_bf16 v[64:67], v[160:163], v[188:191], v[64:67]
	v_mfma_f32_16x16x32_bf16 v[64:67], v[164:167], v[192:195], v[64:67]
	v_mfma_f32_16x16x32_bf16 v[48:51], v[160:163], v[196:199], v[48:51]
	v_mfma_f32_16x16x32_bf16 v[48:51], v[164:167], v[200:203], v[48:51]
	v_mfma_f32_16x16x32_bf16 v[32:35], v[160:163], v[204:207], v[32:35]
	v_mfma_f32_16x16x32_bf16 v[32:35], v[164:167], v[230:233], v[32:35]
	v_mfma_f32_16x16x32_bf16 v[16:19], v[160:163], v[234:237], v[16:19]
	v_mfma_f32_16x16x32_bf16 v[16:19], v[164:167], v[238:241], v[16:19]
	s_setprio 0
	s_setprio 1
	v_mfma_f32_16x16x32_bf16 v[60:63], v[168:171], v[188:191], v[60:63]
	v_mfma_f32_16x16x32_bf16 v[60:63], v[172:175], v[192:195], v[60:63]
	v_mfma_f32_16x16x32_bf16 v[44:47], v[168:171], v[196:199], v[44:47]
	v_mfma_f32_16x16x32_bf16 v[44:47], v[172:175], v[200:203], v[44:47]
	v_mfma_f32_16x16x32_bf16 v[28:31], v[168:171], v[204:207], v[28:31]
	v_mfma_f32_16x16x32_bf16 v[28:31], v[172:175], v[230:233], v[28:31]
	v_mfma_f32_16x16x32_bf16 v[12:15], v[168:171], v[234:237], v[12:15]
	v_mfma_f32_16x16x32_bf16 v[12:15], v[172:175], v[238:241], v[12:15]
	v_mfma_f32_16x16x32_bf16 v[56:59], v[176:179], v[188:191], v[56:59]
	v_mfma_f32_16x16x32_bf16 v[56:59], v[184:187], v[192:195], v[56:59]
	v_mfma_f32_16x16x32_bf16 v[40:43], v[176:179], v[196:199], v[40:43]
	v_mfma_f32_16x16x32_bf16 v[40:43], v[184:187], v[200:203], v[40:43]
	v_mfma_f32_16x16x32_bf16 v[24:27], v[176:179], v[204:207], v[24:27]
	v_mfma_f32_16x16x32_bf16 v[24:27], v[184:187], v[230:233], v[24:27]
	v_mfma_f32_16x16x32_bf16 v[8:11], v[176:179], v[234:237], v[8:11]
	v_mfma_f32_16x16x32_bf16 v[8:11], v[184:187], v[238:241], v[8:11]
	s_setprio 0
	s_barrier
	s_add_i32 s87, 0, 0x1c000
	v_add_u32_e32 v152, s91, v147
	v_add_u32_e32 v153, s87, v147
	ds_read_b128 v[154:157], v152
	ds_read_b128 v[158:161], v152 offset:1024
	ds_read_b128 v[162:165], v152 offset:2048
	ds_read_b128 v[166:169], v152 offset:3072
	ds_read_b128 v[170:173], v153
	ds_read_b128 v[174:177], v153 offset:1024
	ds_read_b128 v[178:181], v153 offset:2048
	ds_read_b128 v[184:187], v153 offset:3072
	s_add_u32 s22, s22, s48
	s_addc_u32 s23, s23, s49
	s_mov_b32 m0, s53
	v_lshl_add_u64 v[244:245], s[22:23], 0, v[2:3]
	ds_read_b128 v[188:191], v149 offset:32768
	ds_read_b128 v[192:195], v149 offset:33792
	ds_read_b128 v[196:199], v149 offset:34816
	ds_read_b128 v[200:203], v149 offset:35840
	ds_read_b128 v[204:207], v149 offset:36864
	ds_read_b128 v[230:233], v149 offset:37888
	ds_read_b128 v[234:237], v149 offset:38912
	ds_read_b128 v[238:241], v149 offset:39936
	global_load_lds_dwordx4 v[244:245], off
	v_lshl_add_u64 v[244:245], s[22:23], 0, v[136:137]
	s_mov_b32 m0, s72
	s_nop 0
	global_load_lds_dwordx4 v[244:245], off
	s_waitcnt vmcnt(8)
	s_waitcnt lgkmcnt(0)
	s_barrier
	s_setprio 1
	s_waitcnt lgkmcnt(0)
	v_mfma_f32_16x16x32_bf16 v[132:135], v[154:157], v[188:191], v[132:135]
	v_mfma_f32_16x16x32_bf16 v[132:135], v[158:161], v[192:195], v[132:135]
	v_mfma_f32_16x16x32_bf16 v[116:119], v[154:157], v[196:199], v[116:119]
	v_mfma_f32_16x16x32_bf16 v[116:119], v[158:161], v[200:203], v[116:119]
	v_mfma_f32_16x16x32_bf16 v[100:103], v[154:157], v[204:207], v[100:103]
	v_mfma_f32_16x16x32_bf16 v[100:103], v[158:161], v[230:233], v[100:103]
	v_mfma_f32_16x16x32_bf16 v[84:87], v[154:157], v[234:237], v[84:87]
	v_mfma_f32_16x16x32_bf16 v[84:87], v[158:161], v[238:241], v[84:87]
	v_mfma_f32_16x16x32_bf16 v[128:131], v[162:165], v[188:191], v[128:131]
	v_mfma_f32_16x16x32_bf16 v[128:131], v[166:169], v[192:195], v[128:131]
	v_mfma_f32_16x16x32_bf16 v[112:115], v[162:165], v[196:199], v[112:115]
	v_mfma_f32_16x16x32_bf16 v[112:115], v[166:169], v[200:203], v[112:115]
	v_mfma_f32_16x16x32_bf16 v[96:99], v[162:165], v[204:207], v[96:99]
	v_mfma_f32_16x16x32_bf16 v[96:99], v[166:169], v[230:233], v[96:99]
	v_mfma_f32_16x16x32_bf16 v[80:83], v[162:165], v[234:237], v[80:83]
	v_mfma_f32_16x16x32_bf16 v[80:83], v[166:169], v[238:241], v[80:83]
	s_setprio 0
	s_setprio 1
	v_mfma_f32_16x16x32_bf16 v[124:127], v[170:173], v[188:191], v[124:127]
	v_mfma_f32_16x16x32_bf16 v[124:127], v[174:177], v[192:195], v[124:127]
	v_mfma_f32_16x16x32_bf16 v[108:111], v[170:173], v[196:199], v[108:111]
	v_mfma_f32_16x16x32_bf16 v[108:111], v[174:177], v[200:203], v[108:111]
	v_mfma_f32_16x16x32_bf16 v[92:95], v[170:173], v[204:207], v[92:95]
	v_mfma_f32_16x16x32_bf16 v[92:95], v[174:177], v[230:233], v[92:95]
	v_mfma_f32_16x16x32_bf16 v[76:79], v[170:173], v[234:237], v[76:79]
	v_mfma_f32_16x16x32_bf16 v[76:79], v[174:177], v[238:241], v[76:79]
	v_mfma_f32_16x16x32_bf16 v[120:123], v[178:181], v[188:191], v[120:123]
	v_mfma_f32_16x16x32_bf16 v[120:123], v[184:187], v[192:195], v[120:123]
	v_mfma_f32_16x16x32_bf16 v[104:107], v[178:181], v[196:199], v[104:107]
	v_mfma_f32_16x16x32_bf16 v[104:107], v[184:187], v[200:203], v[104:107]
	v_mfma_f32_16x16x32_bf16 v[88:91], v[178:181], v[204:207], v[88:91]
	v_mfma_f32_16x16x32_bf16 v[88:91], v[184:187], v[230:233], v[88:91]
	v_mfma_f32_16x16x32_bf16 v[72:75], v[178:181], v[234:237], v[72:75]
	v_mfma_f32_16x16x32_bf16 v[72:75], v[184:187], v[238:241], v[72:75]
	s_setprio 0
	s_barrier
; #define PG8_STAGE(bufoff, gbase, voff) do { _Pragma("unroll") for (int _i = 0; _i < 2; ++_i) \
;         __builtin_amdgcn_global_load_lds((const unsigned*)((const char*)(gbase) + (voff)[_i]), (PG8_LAS unsigned*)(lds + (bufoff) + ldsw + _i * 8192), 16, 0, 0); } while (0)
; #define PG8_LDA(dst, b, h) do { _Pragma("unroll") for (int m = 0; m < 4; ++m) _Pragma("unroll") for (int k = 0; k < 2; ++k) dst[m][k] = *(const PG8_LAS bf16x8*)(lds + PG8_SA(b, h) + aoff + m * 2048 + k * 1024); } while (0)
; #define PG8_MMA(ai, bj, At, Bt) do { __builtin_amdgcn_s_setprio(1); _Pragma("unroll") for (int m = 0; m < 4; ++m) _Pragma("unroll") for (int n = 0; n < 2; ++n) _Pragma("unroll") for (int k = 0; k < 2; ++k) \
;         acc[ai][bj][m][n] = __builtin_amdgcn_mfma_f32_16x16x32_bf16(Bt[n][k], At[m][k], acc[ai][bj][m][n], 0, 0, 0); __builtin_amdgcn_s_setprio(0); } while (0)
; #define PG8_WAIT_V(n) asm volatile("s_waitcnt vmcnt(" #n ")" ::: "memory")
; #define PG8_WAIT_L(n) asm volatile("s_waitcnt lgkmcnt(" #n ")" ::: "memory")
; #define PG8_BAR __builtin_amdgcn_s_barrier()
; #define PG8_SCHED __builtin_amdgcn_sched_barrier(0)
; template <class Epi, class Sched, bool ALIGN_EPI = false, bool SP2 = false>
; __device__ __forceinline__ void gemm_phase(PG8_LAS unsigned char* lds, const Gemm g, const Sched& S, const Epi& E) {
;     ...
;             if constexpr (Epi::KHOOK) { if ((t & 7) == 0 && t != 0) E.khook(acc, t >> 3, wr, fr, lds); }
;     ...
;             PG8_LDA(At, 1, 1); PG8_STAGE(PG8_SB(1, 0), b3, voffB); PG8_STAGE(PG8_SB(1, 1), b3 + hstep, voffB); PG8_STAGE(PG8_SA(1, 0), a3, voffA);
;             PG8_WAIT_V(8); PG8_WAIT_L(0); PG8_BAR; PG8_MMA(1, 0, At, B0); PG8_MMA(1, 1, At, B1); PG8_BAR; PG8_SCHED;
	s_add_i32 s85, s91, s46
	v_lshl_add_u64 v[208:209], v[208:209], 0, s[24:25]
	s_mov_b32 m0, s85
	s_add_i32 s86, s85, 0x2000
	ds_read_b128 v[188:191], v149 offset:49152
	ds_read_b128 v[192:195], v149 offset:50176
	ds_read_b128 v[196:199], v149 offset:51200
	ds_read_b128 v[200:203], v149 offset:52224
	ds_read_b128 v[204:207], v149 offset:53248
	ds_read_b128 v[230:233], v149 offset:54272
	ds_read_b128 v[234:237], v149 offset:55296
	ds_read_b128 v[238:241], v149 offset:56320
	global_load_lds_dwordx4 v[208:209], off
	v_lshl_add_u64 v[208:209], v[216:217], 0, s[24:25]
	s_mov_b32 m0, s86
	s_add_i32 s87, s87, s46
	global_load_lds_dwordx4 v[208:209], off
	v_lshl_add_u64 v[208:209], v[224:225], 0, s[24:25]
	s_mov_b32 m0, s87
	s_add_i32 s88, s87, 0x2000
	global_load_lds_dwordx4 v[208:209], off
	v_lshl_add_u64 v[208:209], v[226:227], 0, s[24:25]
	s_mov_b32 m0, s88
	s_nop 0
	global_load_lds_dwordx4 v[208:209], off
	v_lshl_add_u64 v[208:209], v[228:229], 0, s[24:25]
	s_mov_b32 m0, s75
	s_nop 0
	global_load_lds_dwordx4 v[208:209], off
	v_lshl_add_u64 v[208:209], v[242:243], 0, s[24:25]
	s_mov_b32 m0, s76
	s_nop 0
	global_load_lds_dwordx4 v[208:209], off
	s_waitcnt vmcnt(8)
	s_waitcnt lgkmcnt(0)
	s_barrier
	s_setprio 1
	s_waitcnt lgkmcnt(0)
	v_mfma_f32_16x16x32_bf16 v[68:71], v[154:157], v[188:191], v[68:71]
	v_mfma_f32_16x16x32_bf16 v[68:71], v[158:161], v[192:195], v[68:71]
	v_mfma_f32_16x16x32_bf16 v[52:55], v[154:157], v[196:199], v[52:55]
	v_mfma_f32_16x16x32_bf16 v[52:55], v[158:161], v[200:203], v[52:55]
	v_mfma_f32_16x16x32_bf16 v[36:39], v[154:157], v[204:207], v[36:39]
	v_mfma_f32_16x16x32_bf16 v[36:39], v[158:161], v[230:233], v[36:39]
	v_mfma_f32_16x16x32_bf16 v[20:23], v[154:157], v[234:237], v[20:23]
	v_mfma_f32_16x16x32_bf16 v[20:23], v[158:161], v[238:241], v[20:23]
	v_mfma_f32_16x16x32_bf16 v[64:67], v[162:165], v[188:191], v[64:67]
	v_mfma_f32_16x16x32_bf16 v[64:67], v[166:169], v[192:195], v[64:67]
	v_mfma_f32_16x16x32_bf16 v[48:51], v[162:165], v[196:199], v[48:51]
	v_mfma_f32_16x16x32_bf16 v[48:51], v[166:169], v[200:203], v[48:51]
	v_mfma_f32_16x16x32_bf16 v[32:35], v[162:165], v[204:207], v[32:35]
	v_mfma_f32_16x16x32_bf16 v[32:35], v[166:169], v[230:233], v[32:35]
	v_mfma_f32_16x16x32_bf16 v[16:19], v[162:165], v[234:237], v[16:19]
	v_mfma_f32_16x16x32_bf16 v[16:19], v[166:169], v[238:241], v[16:19]
	s_setprio 0
	s_setprio 1
	v_mfma_f32_16x16x32_bf16 v[60:63], v[170:173], v[188:191], v[60:63]
	v_mfma_f32_16x16x32_bf16 v[60:63], v[174:177], v[192:195], v[60:63]
	v_mfma_f32_16x16x32_bf16 v[44:47], v[170:173], v[196:199], v[44:47]
	v_mfma_f32_16x16x32_bf16 v[44:47], v[174:177], v[200:203], v[44:47]
	v_mfma_f32_16x16x32_bf16 v[28:31], v[170:173], v[204:207], v[28:31]
	v_mfma_f32_16x16x32_bf16 v[28:31], v[174:177], v[230:233], v[28:31]
	v_mfma_f32_16x16x32_bf16 v[12:15], v[170:173], v[234:237], v[12:15]
	v_mfma_f32_16x16x32_bf16 v[12:15], v[174:177], v[238:241], v[12:15]
	v_mfma_f32_16x16x32_bf16 v[56:59], v[178:181], v[188:191], v[56:59]
	v_mfma_f32_16x16x32_bf16 v[56:59], v[184:187], v[192:195], v[56:59]
	v_mfma_f32_16x16x32_bf16 v[40:43], v[178:181], v[196:199], v[40:43]
	v_mfma_f32_16x16x32_bf16 v[40:43], v[184:187], v[200:203], v[40:43]
	v_mfma_f32_16x16x32_bf16 v[24:27], v[178:181], v[204:207], v[24:27]
	v_mfma_f32_16x16x32_bf16 v[24:27], v[184:187], v[230:233], v[24:27]
	v_mfma_f32_16x16x32_bf16 v[8:11], v[178:181], v[234:237], v[8:11]
	v_mfma_f32_16x16x32_bf16 v[8:11], v[184:187], v[238:241], v[8:11]
	s_setprio 0
	s_barrier
	v_readlane_b32 s22, v252, 42
	v_readlane_b32 s23, v252, 43
	s_andn2_b64 vcc, exec, s[22:23]
	s_cbranch_vccnz .LBB0_251
	s_add_u32 s22, s6, 0x180
	s_addc_u32 s23, s7, 0
	s_add_u32 s89, s10, 0x200
	s_addc_u32 s92, s11, 0
	s_mov_b32 s93, 4
	v_mov_b32_e32 v154, v148
	s_add_i32 s40, s93, -2
	s_and_b32 s40, s40, 6
	s_cmp_lg_u32 s40, 0
	s_cbranch_scc1 .LBB0_250
	s_branch .LBB0_249

; #define PG8_STAGE(bufoff, gbase, voff) do { _Pragma("unroll") for (int _i = 0; _i < 2; ++_i) \
;         __builtin_amdgcn_global_load_lds((const unsigned*)((const char*)(gbase) + (voff)[_i]), (PG8_LAS unsigned*)(lds + (bufoff) + ldsw + _i * 8192), 16, 0, 0); } while (0)
; #define PG8_LDA(dst, b, h) do { _Pragma("unroll") for (int m = 0; m < 4; ++m) _Pragma("unroll") for (int k = 0; k < 2; ++k) dst[m][k] = *(const PG8_LAS bf16x8*)(lds + PG8_SA(b, h) + aoff + m * 2048 + k * 1024); } while (0)
; #define PG8_LDB(dst, b, h) do { _Pragma("unroll") for (int n = 0; n < 2; ++n) _Pragma("unroll") for (int k = 0; k < 2; ++k) dst[n][k] = *(const PG8_LAS bf16x8*)(lds + PG8_SB(b, h) + boff + n * 2048 + k * 1024); } while (0)
; #define PG8_MMA(ai, bj, At, Bt) do { __builtin_amdgcn_s_setprio(1); _Pragma("unroll") for (int m = 0; m < 4; ++m) _Pragma("unroll") for (int n = 0; n < 2; ++n) _Pragma("unroll") for (int k = 0; k < 2; ++k) \
;         acc[ai][bj][m][n] = __builtin_amdgcn_mfma_f32_16x16x32_bf16(Bt[n][k], At[m][k], acc[ai][bj][m][n], 0, 0, 0); __builtin_amdgcn_s_setprio(0); } while (0)
; #define PG8_WAIT_V(n) asm volatile("s_waitcnt vmcnt(" #n ")" ::: "memory")
; #define PG8_WAIT_L(n) asm volatile("s_waitcnt lgkmcnt(" #n ")" ::: "memory")
; template <class Epi, class Sched, bool ALIGN_EPI = false, bool SP2 = false>
; __device__ __forceinline__ void gemm_phase(PG8_LAS unsigned char* lds, const Gemm g, const Sched& S, const Epi& E) {
;     ...
;             const bool last = (t == nt - 2);
;             const char* a1 = cA + (size_t)(t + 1) * kstep;
;             const char* a2 = last ? nA : cA + (size_t)(t + 2) * kstep; const char* b2 = last ? nB : cB + (size_t)(t + 2) * kstep;
;             const char* a3 = a2 + kstep; const char* b3 = b2 + kstep;
;             if (last && has_next) S.a_ready(nxt);
;             if constexpr (SP2) {
;             PG8_LDB(B0, 0, 0); PG8_LDB(B1, 0, 1); PG8_SCHED; PG8_LDA(At, 0, 0); PG8_STAGE(PG8_SA(1, 1), a1 + hstep, voffA);
;             PG8_WAIT_V(8); PG8_WAIT_L(0); PG8_BAR; PG8_MMA(0, 0, At, B0); PG8_MMA(0, 1, At, B1); PG8_BAR; PG8_SCHED;
;             PG8_LDA(At, 0, 1); PG8_STAGE(PG8_SB(0, 0), b2, voffB); PG8_STAGE(PG8_SB(0, 1), b2 + hstep, voffB); PG8_STAGE(PG8_SA(0, 0), a2, voffA);
;             PG8_WAIT_V(8); PG8_WAIT_L(0); PG8_BAR; PG8_MMA(1, 0, At, B0); PG8_MMA(1, 1, At, B1); PG8_BAR; PG8_SCHED;
.LBB0_250:
	ds_read_b128 v[156:159], v150
	ds_read_b128 v[160:163], v150 offset:1024
	ds_read_b128 v[164:167], v150 offset:2048
	ds_read_b128 v[168:171], v150 offset:3072
	ds_read_b128 v[172:175], v151
	ds_read_b128 v[176:179], v151 offset:1024
	ds_read_b128 v[184:187], v151 offset:2048
	ds_read_b128 v[188:191], v151 offset:3072
	s_add_u32 s40, s22, 0x80
	s_addc_u32 s41, s23, 0
	s_cmp_eq_u32 s9, s93
	s_cselect_b32 s40, s4, s40
	s_cselect_b32 s41, s5, s41
	s_cselect_b32 s95, s17, s92
	s_cselect_b32 s94, s16, s89
	s_mov_b32 m0, s37
	v_lshl_add_u64 v[180:181], s[22:23], 0, v[140:141]
	ds_read_b128 v[192:195], v149
	ds_read_b128 v[196:199], v149 offset:1024
	ds_read_b128 v[200:203], v149 offset:2048
	ds_read_b128 v[204:207], v149 offset:3072
	ds_read_b128 v[230:233], v149 offset:4096
	ds_read_b128 v[234:237], v149 offset:5120
	ds_read_b128 v[238:241], v149 offset:6144
	ds_read_b128 v[242:245], v149 offset:7168
	global_load_lds_dwordx4 v[180:181], off
	v_lshl_add_u64 v[180:181], s[22:23], 0, v[142:143]
	s_mov_b32 m0, s80
	s_nop 0
	global_load_lds_dwordx4 v[180:181], off
	s_waitcnt vmcnt(8)
	s_waitcnt lgkmcnt(0)
	s_barrier
	s_setprio 1
	s_waitcnt lgkmcnt(0)
	v_mfma_f32_16x16x32_bf16 v[132:135], v[156:159], v[192:195], v[132:135]
	v_mfma_f32_16x16x32_bf16 v[132:135], v[160:163], v[196:199], v[132:135]
	v_mfma_f32_16x16x32_bf16 v[116:119], v[156:159], v[200:203], v[116:119]
	v_mfma_f32_16x16x32_bf16 v[116:119], v[160:163], v[204:207], v[116:119]
	v_mfma_f32_16x16x32_bf16 v[100:103], v[156:159], v[230:233], v[100:103]
	v_mfma_f32_16x16x32_bf16 v[100:103], v[160:163], v[234:237], v[100:103]
	v_mfma_f32_16x16x32_bf16 v[84:87], v[156:159], v[238:241], v[84:87]
	v_mfma_f32_16x16x32_bf16 v[84:87], v[160:163], v[242:245], v[84:87]
	v_mfma_f32_16x16x32_bf16 v[128:131], v[164:167], v[192:195], v[128:131]
	v_mfma_f32_16x16x32_bf16 v[128:131], v[168:171], v[196:199], v[128:131]
	v_mfma_f32_16x16x32_bf16 v[112:115], v[164:167], v[200:203], v[112:115]
	v_mfma_f32_16x16x32_bf16 v[112:115], v[168:171], v[204:207], v[112:115]
	v_mfma_f32_16x16x32_bf16 v[96:99], v[164:167], v[230:233], v[96:99]
	v_mfma_f32_16x16x32_bf16 v[96:99], v[168:171], v[234:237], v[96:99]
	v_mfma_f32_16x16x32_bf16 v[80:83], v[164:167], v[238:241], v[80:83]
	v_mfma_f32_16x16x32_bf16 v[80:83], v[168:171], v[242:245], v[80:83]
	s_setprio 0
	s_setprio 1
	v_mfma_f32_16x16x32_bf16 v[124:127], v[172:175], v[192:195], v[124:127]
	v_mfma_f32_16x16x32_bf16 v[124:127], v[176:179], v[196:199], v[124:127]
	v_mfma_f32_16x16x32_bf16 v[108:111], v[172:175], v[200:203], v[108:111]
	v_mfma_f32_16x16x32_bf16 v[108:111], v[176:179], v[204:207], v[108:111]
	v_mfma_f32_16x16x32_bf16 v[92:95], v[172:175], v[230:233], v[92:95]
	v_mfma_f32_16x16x32_bf16 v[92:95], v[176:179], v[234:237], v[92:95]
	v_mfma_f32_16x16x32_bf16 v[76:79], v[172:175], v[238:241], v[76:79]
	v_mfma_f32_16x16x32_bf16 v[76:79], v[176:179], v[242:245], v[76:79]
	v_mfma_f32_16x16x32_bf16 v[120:123], v[184:187], v[192:195], v[120:123]
	v_mfma_f32_16x16x32_bf16 v[120:123], v[188:191], v[196:199], v[120:123]
	v_mfma_f32_16x16x32_bf16 v[104:107], v[184:187], v[200:203], v[104:107]
	v_mfma_f32_16x16x32_bf16 v[104:107], v[188:191], v[204:207], v[104:107]
	v_mfma_f32_16x16x32_bf16 v[88:91], v[184:187], v[230:233], v[88:91]
	v_mfma_f32_16x16x32_bf16 v[88:91], v[188:191], v[234:237], v[88:91]
	v_mfma_f32_16x16x32_bf16 v[72:75], v[184:187], v[238:241], v[72:75]
	v_mfma_f32_16x16x32_bf16 v[72:75], v[188:191], v[242:245], v[72:75]
	s_setprio 0
	s_barrier
	s_mov_b32 m0, s81
	v_lshl_add_u64 v[180:181], s[94:95], 0, v[0:1]
	v_lshl_add_u64 v[208:209], s[94:95], 0, v[138:139]
	s_add_u32 s94, s94, s48
	ds_read_b128 v[192:195], v149 offset:16384
	ds_read_b128 v[196:199], v149 offset:17408
	ds_read_b128 v[200:203], v149 offset:18432
	ds_read_b128 v[204:207], v149 offset:19456
	ds_read_b128 v[230:233], v149 offset:20480
	ds_read_b128 v[234:237], v149 offset:21504
	ds_read_b128 v[238:241], v149 offset:22528
	ds_read_b128 v[242:245], v149 offset:23552
	global_load_lds_dwordx4 v[180:181], off
	s_mov_b32 m0, s82
	s_addc_u32 s95, s95, s49
	global_load_lds_dwordx4 v[208:209], off
	v_lshl_add_u64 v[216:217], s[94:95], 0, v[0:1]
	s_mov_b32 m0, s83
	v_lshl_add_u64 v[224:225], s[94:95], 0, v[138:139]
	global_load_lds_dwordx4 v[216:217], off
	s_mov_b32 m0, s84
	v_lshl_add_u64 v[226:227], s[40:41], 0, v[2:3]
	global_load_lds_dwordx4 v[224:225], off
	s_mov_b32 m0, s47
	v_lshl_add_u64 v[228:229], s[40:41], 0, v[136:137]
	global_load_lds_dwordx4 v[226:227], off
	s_mov_b32 m0, s52
	s_nop 0
	global_load_lds_dwordx4 v[228:229], off
	s_waitcnt vmcnt(8)
	s_waitcnt lgkmcnt(0)
	s_barrier
; #define PG8_STAGE(bufoff, gbase, voff) do { _Pragma("unroll") for (int _i = 0; _i < 2; ++_i) \
;         __builtin_amdgcn_global_load_lds((const unsigned*)((const char*)(gbase) + (voff)[_i]), (PG8_LAS unsigned*)(lds + (bufoff) + ldsw + _i * 8192), 16, 0, 0); } while (0)
; #define PG8_LDA(dst, b, h) do { _Pragma("unroll") for (int m = 0; m < 4; ++m) _Pragma("unroll") for (int k = 0; k < 2; ++k) dst[m][k] = *(const PG8_LAS bf16x8*)(lds + PG8_SA(b, h) + aoff + m * 2048 + k * 1024); } while (0)
; #define PG8_LDB(dst, b, h) do { _Pragma("unroll") for (int n = 0; n < 2; ++n) _Pragma("unroll") for (int k = 0; k < 2; ++k) dst[n][k] = *(const PG8_LAS bf16x8*)(lds + PG8_SB(b, h) + boff + n * 2048 + k * 1024); } while (0)
; #define PG8_MMA(ai, bj, At, Bt) do { __builtin_amdgcn_s_setprio(1); _Pragma("unroll") for (int m = 0; m < 4; ++m) _Pragma("unroll") for (int n = 0; n < 2; ++n) _Pragma("unroll") for (int k = 0; k < 2; ++k) \
;         acc[ai][bj][m][n] = __builtin_amdgcn_mfma_f32_16x16x32_bf16(Bt[n][k], At[m][k], acc[ai][bj][m][n], 0, 0, 0); __builtin_amdgcn_s_setprio(0); } while (0)
; #define PG8_WAIT_V(n) asm volatile("s_waitcnt vmcnt(" #n ")" ::: "memory")
; #define PG8_WAIT_L(n) asm volatile("s_waitcnt lgkmcnt(" #n ")" ::: "memory")
; #define PG8_BAR __builtin_amdgcn_s_barrier()
; #define PG8_SCHED __builtin_amdgcn_sched_barrier(0)
; template <class Epi, class Sched, bool ALIGN_EPI = false, bool SP2 = false>
; __device__ __forceinline__ void gemm_phase(PG8_LAS unsigned char* lds, const Gemm g, const Sched& S, const Epi& E) {
;     ...
;             PG8_WAIT_V(8); PG8_WAIT_L(0); PG8_BAR; PG8_MMA(1, 0, At, B0); PG8_MMA(1, 1, At, B1); PG8_BAR; PG8_SCHED;
;             PG8_LDB(B0, 1, 0); PG8_LDB(B1, 1, 1); PG8_SCHED; PG8_LDA(At, 1, 0); PG8_STAGE(PG8_SA(0, 1), a2 + hstep, voffA);
;             PG8_WAIT_V(8); PG8_WAIT_L(0); PG8_BAR; PG8_MMA(0, 0, At, B0); PG8_MMA(0, 1, At, B1); PG8_BAR; PG8_SCHED;
	s_setprio 1
	s_waitcnt lgkmcnt(0)
	v_mfma_f32_16x16x32_bf16 v[68:71], v[156:159], v[192:195], v[68:71]
	v_mfma_f32_16x16x32_bf16 v[68:71], v[160:163], v[196:199], v[68:71]
	v_mfma_f32_16x16x32_bf16 v[52:55], v[156:159], v[200:203], v[52:55]
	v_mfma_f32_16x16x32_bf16 v[52:55], v[160:163], v[204:207], v[52:55]
	v_mfma_f32_16x16x32_bf16 v[36:39], v[156:159], v[230:233], v[36:39]
	v_mfma_f32_16x16x32_bf16 v[36:39], v[160:163], v[234:237], v[36:39]
	v_mfma_f32_16x16x32_bf16 v[20:23], v[156:159], v[238:241], v[20:23]
	v_mfma_f32_16x16x32_bf16 v[20:23], v[160:163], v[242:245], v[20:23]
	v_mfma_f32_16x16x32_bf16 v[64:67], v[164:167], v[192:195], v[64:67]
	v_mfma_f32_16x16x32_bf16 v[64:67], v[168:171], v[196:199], v[64:67]
	v_mfma_f32_16x16x32_bf16 v[48:51], v[164:167], v[200:203], v[48:51]
	v_mfma_f32_16x16x32_bf16 v[48:51], v[168:171], v[204:207], v[48:51]
	v_mfma_f32_16x16x32_bf16 v[32:35], v[164:167], v[230:233], v[32:35]
	v_mfma_f32_16x16x32_bf16 v[32:35], v[168:171], v[234:237], v[32:35]
	v_mfma_f32_16x16x32_bf16 v[16:19], v[164:167], v[238:241], v[16:19]
	v_mfma_f32_16x16x32_bf16 v[16:19], v[168:171], v[242:245], v[16:19]
	s_setprio 0
	s_setprio 1
	v_mfma_f32_16x16x32_bf16 v[60:63], v[172:175], v[192:195], v[60:63]
	v_mfma_f32_16x16x32_bf16 v[60:63], v[176:179], v[196:199], v[60:63]
	v_mfma_f32_16x16x32_bf16 v[44:47], v[172:175], v[200:203], v[44:47]
	v_mfma_f32_16x16x32_bf16 v[44:47], v[176:179], v[204:207], v[44:47]
	v_mfma_f32_16x16x32_bf16 v[28:31], v[172:175], v[230:233], v[28:31]
	v_mfma_f32_16x16x32_bf16 v[28:31], v[176:179], v[234:237], v[28:31]
	v_mfma_f32_16x16x32_bf16 v[12:15], v[172:175], v[238:241], v[12:15]
	v_mfma_f32_16x16x32_bf16 v[12:15], v[176:179], v[242:245], v[12:15]
	v_mfma_f32_16x16x32_bf16 v[56:59], v[184:187], v[192:195], v[56:59]
	v_mfma_f32_16x16x32_bf16 v[56:59], v[188:191], v[196:199], v[56:59]
	v_mfma_f32_16x16x32_bf16 v[40:43], v[184:187], v[200:203], v[40:43]
	v_mfma_f32_16x16x32_bf16 v[40:43], v[188:191], v[204:207], v[40:43]
	v_mfma_f32_16x16x32_bf16 v[24:27], v[184:187], v[230:233], v[24:27]
	v_mfma_f32_16x16x32_bf16 v[24:27], v[188:191], v[234:237], v[24:27]
	v_mfma_f32_16x16x32_bf16 v[8:11], v[184:187], v[238:241], v[8:11]
	v_mfma_f32_16x16x32_bf16 v[8:11], v[188:191], v[242:245], v[8:11]
	s_setprio 0
	s_barrier
	ds_read_b128 v[156:159], v152
	ds_read_b128 v[160:163], v152 offset:1024
	ds_read_b128 v[164:167], v152 offset:2048
	ds_read_b128 v[168:171], v152 offset:3072
	ds_read_b128 v[172:175], v153
	ds_read_b128 v[176:179], v153 offset:1024
	ds_read_b128 v[184:187], v153 offset:2048
	ds_read_b128 v[188:191], v153 offset:3072
	s_add_u32 s40, s40, s48
	s_addc_u32 s41, s41, s49
	s_mov_b32 m0, s53
	v_lshl_add_u64 v[246:247], s[40:41], 0, v[2:3]
	ds_read_b128 v[192:195], v149 offset:32768
	ds_read_b128 v[196:199], v149 offset:33792
	ds_read_b128 v[200:203], v149 offset:34816
	ds_read_b128 v[204:207], v149 offset:35840
	ds_read_b128 v[230:233], v149 offset:36864
	ds_read_b128 v[234:237], v149 offset:37888
	ds_read_b128 v[238:241], v149 offset:38912
	ds_read_b128 v[242:245], v149 offset:39936
	global_load_lds_dwordx4 v[246:247], off
	v_lshl_add_u64 v[246:247], s[40:41], 0, v[136:137]
	s_mov_b32 m0, s72
	s_nop 0
	global_load_lds_dwordx4 v[246:247], off
	s_waitcnt vmcnt(8)
	s_waitcnt lgkmcnt(0)
	s_barrier
	s_setprio 1
	s_waitcnt lgkmcnt(0)
	v_mfma_f32_16x16x32_bf16 v[132:135], v[156:159], v[192:195], v[132:135]
	v_mfma_f32_16x16x32_bf16 v[132:135], v[160:163], v[196:199], v[132:135]
	v_mfma_f32_16x16x32_bf16 v[116:119], v[156:159], v[200:203], v[116:119]
	v_mfma_f32_16x16x32_bf16 v[116:119], v[160:163], v[204:207], v[116:119]
	v_mfma_f32_16x16x32_bf16 v[100:103], v[156:159], v[230:233], v[100:103]
	v_mfma_f32_16x16x32_bf16 v[100:103], v[160:163], v[234:237], v[100:103]
	v_mfma_f32_16x16x32_bf16 v[84:87], v[156:159], v[238:241], v[84:87]
	v_mfma_f32_16x16x32_bf16 v[84:87], v[160:163], v[242:245], v[84:87]
	v_mfma_f32_16x16x32_bf16 v[128:131], v[164:167], v[192:195], v[128:131]
	v_mfma_f32_16x16x32_bf16 v[128:131], v[168:171], v[196:199], v[128:131]
	v_mfma_f32_16x16x32_bf16 v[112:115], v[164:167], v[200:203], v[112:115]
	v_mfma_f32_16x16x32_bf16 v[112:115], v[168:171], v[204:207], v[112:115]
	v_mfma_f32_16x16x32_bf16 v[96:99], v[164:167], v[230:233], v[96:99]
	v_mfma_f32_16x16x32_bf16 v[96:99], v[168:171], v[234:237], v[96:99]
	v_mfma_f32_16x16x32_bf16 v[80:83], v[164:167], v[238:241], v[80:83]
	v_mfma_f32_16x16x32_bf16 v[80:83], v[168:171], v[242:245], v[80:83]
	s_setprio 0
	s_setprio 1
	v_mfma_f32_16x16x32_bf16 v[124:127], v[172:175], v[192:195], v[124:127]
	v_mfma_f32_16x16x32_bf16 v[124:127], v[176:179], v[196:199], v[124:127]
	v_mfma_f32_16x16x32_bf16 v[108:111], v[172:175], v[200:203], v[108:111]
	v_mfma_f32_16x16x32_bf16 v[108:111], v[176:179], v[204:207], v[108:111]
	v_mfma_f32_16x16x32_bf16 v[92:95], v[172:175], v[230:233], v[92:95]
	v_mfma_f32_16x16x32_bf16 v[92:95], v[176:179], v[234:237], v[92:95]
	v_mfma_f32_16x16x32_bf16 v[76:79], v[172:175], v[238:241], v[76:79]
	v_mfma_f32_16x16x32_bf16 v[76:79], v[176:179], v[242:245], v[76:79]
	v_mfma_f32_16x16x32_bf16 v[120:123], v[184:187], v[192:195], v[120:123]
	v_mfma_f32_16x16x32_bf16 v[120:123], v[188:191], v[196:199], v[120:123]
	v_mfma_f32_16x16x32_bf16 v[104:107], v[184:187], v[200:203], v[104:107]
	v_mfma_f32_16x16x32_bf16 v[104:107], v[188:191], v[204:207], v[104:107]
	v_mfma_f32_16x16x32_bf16 v[88:91], v[184:187], v[230:233], v[88:91]
	v_mfma_f32_16x16x32_bf16 v[88:91], v[188:191], v[234:237], v[88:91]
	v_mfma_f32_16x16x32_bf16 v[72:75], v[184:187], v[238:241], v[72:75]
	v_mfma_f32_16x16x32_bf16 v[72:75], v[188:191], v[242:245], v[72:75]
	s_setprio 0
	s_barrier
; #define PG8_STAGE(bufoff, gbase, voff) do { _Pragma("unroll") for (int _i = 0; _i < 2; ++_i) \
;         __builtin_amdgcn_global_load_lds((const unsigned*)((const char*)(gbase) + (voff)[_i]), (PG8_LAS unsigned*)(lds + (bufoff) + ldsw + _i * 8192), 16, 0, 0); } while (0)
; #define PG8_LDA(dst, b, h) do { _Pragma("unroll") for (int m = 0; m < 4; ++m) _Pragma("unroll") for (int k = 0; k < 2; ++k) dst[m][k] = *(const PG8_LAS bf16x8*)(lds + PG8_SA(b, h) + aoff + m * 2048 + k * 1024); } while (0)
; #define PG8_MMA(ai, bj, At, Bt) do { __builtin_amdgcn_s_setprio(1); _Pragma("unroll") for (int m = 0; m < 4; ++m) _Pragma("unroll") for (int n = 0; n < 2; ++n) _Pragma("unroll") for (int k = 0; k < 2; ++k) \
;         acc[ai][bj][m][n] = __builtin_amdgcn_mfma_f32_16x16x32_bf16(Bt[n][k], At[m][k], acc[ai][bj][m][n], 0, 0, 0); __builtin_amdgcn_s_setprio(0); } while (0)
; #define PG8_WAIT_V(n) asm volatile("s_waitcnt vmcnt(" #n ")" ::: "memory")
; #define PG8_WAIT_L(n) asm volatile("s_waitcnt lgkmcnt(" #n ")" ::: "memory")
; #define PG8_BAR __builtin_amdgcn_s_barrier()
; #define PG8_SCHED __builtin_amdgcn_sched_barrier(0)
; template <class Epi, class Sched, bool ALIGN_EPI = false, bool SP2 = false>
; __device__ __forceinline__ void gemm_phase(PG8_LAS unsigned char* lds, const Gemm g, const Sched& S, const Epi& E) {
;     ...
;         for (int t = 0; t < nt; t += 2) {
;     ...
;             PG8_LDA(At, 1, 1); PG8_STAGE(PG8_SB(1, 0), b3, voffB); PG8_STAGE(PG8_SB(1, 1), b3 + hstep, voffB); PG8_STAGE(PG8_SA(1, 0), a3, voffA);
;             PG8_WAIT_V(8); PG8_WAIT_L(0); PG8_BAR; PG8_MMA(1, 0, At, B0); PG8_MMA(1, 1, At, B1); PG8_BAR; PG8_SCHED;
	s_mov_b32 m0, s85
	v_lshl_add_u64 v[180:181], v[180:181], 0, s[24:25]
	ds_read_b128 v[192:195], v149 offset:49152
	ds_read_b128 v[196:199], v149 offset:50176
	ds_read_b128 v[200:203], v149 offset:51200
	ds_read_b128 v[204:207], v149 offset:52224
	ds_read_b128 v[230:233], v149 offset:53248
	ds_read_b128 v[234:237], v149 offset:54272
	ds_read_b128 v[238:241], v149 offset:55296
	ds_read_b128 v[242:245], v149 offset:56320
	global_load_lds_dwordx4 v[180:181], off
	v_lshl_add_u64 v[180:181], v[208:209], 0, s[24:25]
	s_mov_b32 m0, s86
	s_nop 0
	global_load_lds_dwordx4 v[180:181], off
	v_lshl_add_u64 v[180:181], v[216:217], 0, s[24:25]
	s_mov_b32 m0, s87
	s_nop 0
	global_load_lds_dwordx4 v[180:181], off
	v_lshl_add_u64 v[180:181], v[224:225], 0, s[24:25]
	s_mov_b32 m0, s88
	s_nop 0
	global_load_lds_dwordx4 v[180:181], off
	v_lshl_add_u64 v[180:181], v[226:227], 0, s[24:25]
	s_mov_b32 m0, s75
	s_nop 0
	global_load_lds_dwordx4 v[180:181], off
	v_lshl_add_u64 v[180:181], v[228:229], 0, s[24:25]
	s_mov_b32 m0, s76
	s_nop 0
	global_load_lds_dwordx4 v[180:181], off
	s_waitcnt vmcnt(8)
	s_waitcnt lgkmcnt(0)
	s_barrier
	s_setprio 1
	s_waitcnt lgkmcnt(0)
	v_mfma_f32_16x16x32_bf16 v[68:71], v[156:159], v[192:195], v[68:71]
	v_mfma_f32_16x16x32_bf16 v[68:71], v[160:163], v[196:199], v[68:71]
	v_mfma_f32_16x16x32_bf16 v[52:55], v[156:159], v[200:203], v[52:55]
	v_mfma_f32_16x16x32_bf16 v[52:55], v[160:163], v[204:207], v[52:55]
	v_mfma_f32_16x16x32_bf16 v[36:39], v[156:159], v[230:233], v[36:39]
	v_mfma_f32_16x16x32_bf16 v[36:39], v[160:163], v[234:237], v[36:39]
	v_mfma_f32_16x16x32_bf16 v[20:23], v[156:159], v[238:241], v[20:23]
	v_mfma_f32_16x16x32_bf16 v[20:23], v[160:163], v[242:245], v[20:23]
	v_mfma_f32_16x16x32_bf16 v[64:67], v[164:167], v[192:195], v[64:67]
	v_mfma_f32_16x16x32_bf16 v[64:67], v[168:171], v[196:199], v[64:67]
	v_mfma_f32_16x16x32_bf16 v[48:51], v[164:167], v[200:203], v[48:51]
	v_mfma_f32_16x16x32_bf16 v[48:51], v[168:171], v[204:207], v[48:51]
	v_mfma_f32_16x16x32_bf16 v[32:35], v[164:167], v[230:233], v[32:35]
	v_mfma_f32_16x16x32_bf16 v[32:35], v[168:171], v[234:237], v[32:35]
	v_mfma_f32_16x16x32_bf16 v[16:19], v[164:167], v[238:241], v[16:19]
	v_mfma_f32_16x16x32_bf16 v[16:19], v[168:171], v[242:245], v[16:19]
	s_setprio 0
	s_setprio 1
	v_mfma_f32_16x16x32_bf16 v[60:63], v[172:175], v[192:195], v[60:63]
	v_mfma_f32_16x16x32_bf16 v[60:63], v[176:179], v[196:199], v[60:63]
	v_mfma_f32_16x16x32_bf16 v[44:47], v[172:175], v[200:203], v[44:47]
	v_mfma_f32_16x16x32_bf16 v[44:47], v[176:179], v[204:207], v[44:47]
	v_mfma_f32_16x16x32_bf16 v[28:31], v[172:175], v[230:233], v[28:31]
	v_mfma_f32_16x16x32_bf16 v[28:31], v[176:179], v[234:237], v[28:31]
	v_mfma_f32_16x16x32_bf16 v[12:15], v[172:175], v[238:241], v[12:15]
	v_mfma_f32_16x16x32_bf16 v[12:15], v[176:179], v[242:245], v[12:15]
	v_mfma_f32_16x16x32_bf16 v[56:59], v[184:187], v[192:195], v[56:59]
	v_mfma_f32_16x16x32_bf16 v[56:59], v[188:191], v[196:199], v[56:59]
	v_mfma_f32_16x16x32_bf16 v[40:43], v[184:187], v[200:203], v[40:43]
	v_mfma_f32_16x16x32_bf16 v[40:43], v[188:191], v[204:207], v[40:43]
	v_mfma_f32_16x16x32_bf16 v[24:27], v[184:187], v[230:233], v[24:27]
	v_mfma_f32_16x16x32_bf16 v[24:27], v[188:191], v[234:237], v[24:27]
	v_mfma_f32_16x16x32_bf16 v[8:11], v[184:187], v[238:241], v[8:11]
	v_mfma_f32_16x16x32_bf16 v[8:11], v[188:191], v[242:245], v[8:11]
	s_setprio 0
	s_barrier
	s_add_i32 s40, s93, 2
	s_add_u32 s22, s22, 0x100
	s_addc_u32 s23, s23, 0
	s_add_u32 s89, s89, 0x100
	s_addc_u32 s92, s92, 0
	s_cmp_ge_u32 s93, s9
	v_add_u32_e32 v154, 0x100, v154
	s_cbranch_scc0 .LBB0_248

; #define PG8_STAGE(bufoff, gbase, voff) do { _Pragma("unroll") for (int _i = 0; _i < 2; ++_i) \
;         __builtin_amdgcn_global_load_lds((const unsigned*)((const char*)(gbase) + (voff)[_i]), (PG8_LAS unsigned*)(lds + (bufoff) + ldsw + _i * 8192), 16, 0, 0); } while (0)
; #define PG8_LDA(dst, b, h) do { _Pragma("unroll") for (int m = 0; m < 4; ++m) _Pragma("unroll") for (int k = 0; k < 2; ++k) dst[m][k] = *(const PG8_LAS bf16x8*)(lds + PG8_SA(b, h) + aoff + m * 2048 + k * 1024); } while (0)
; #define PG8_LDB(dst, b, h) do { _Pragma("unroll") for (int n = 0; n < 2; ++n) _Pragma("unroll") for (int k = 0; k < 2; ++k) dst[n][k] = *(const PG8_LAS bf16x8*)(lds + PG8_SB(b, h) + boff + n * 2048 + k * 1024); } while (0)
; #define PG8_MMA(ai, bj, At, Bt) do { __builtin_amdgcn_s_setprio(1); _Pragma("unroll") for (int m = 0; m < 4; ++m) _Pragma("unroll") for (int n = 0; n < 2; ++n) _Pragma("unroll") for (int k = 0; k < 2; ++k) \
;         acc[ai][bj][m][n] = __builtin_amdgcn_mfma_f32_16x16x32_bf16(Bt[n][k], At[m][k], acc[ai][bj][m][n], 0, 0, 0); __builtin_amdgcn_s_setprio(0); } while (0)
; #define PG8_WAIT_V(n) asm volatile("s_waitcnt vmcnt(" #n ")" ::: "memory")
; #define PG8_WAIT_L(n) asm volatile("s_waitcnt lgkmcnt(" #n ")" ::: "memory")
; template <class Epi, class Sched, bool ALIGN_EPI = false, bool SP2 = false>
; __device__ __forceinline__ void gemm_phase(PG8_LAS unsigned char* lds, const Gemm g, const Sched& S, const Epi& E) {
;     ...
;             const bool last = (t == nt - 2);
;             const char* a1 = cA + (size_t)(t + 1) * kstep;
;             const char* a2 = last ? nA : cA + (size_t)(t + 2) * kstep; const char* b2 = last ? nB : cB + (size_t)(t + 2) * kstep;
;             const char* a3 = a2 + kstep; const char* b3 = b2 + kstep;
;             if (last && has_next) S.a_ready(nxt);
;             if constexpr (SP2) {
;             PG8_LDB(B0, 0, 0); PG8_LDB(B1, 0, 1); PG8_SCHED; PG8_LDA(At, 0, 0); PG8_STAGE(PG8_SA(1, 1), a1 + hstep, voffA);
;             PG8_WAIT_V(8); PG8_WAIT_L(0); PG8_BAR; PG8_MMA(0, 0, At, B0); PG8_MMA(0, 1, At, B1); PG8_BAR; PG8_SCHED;
;             PG8_LDA(At, 0, 1); PG8_STAGE(PG8_SB(0, 0), b2, voffB); PG8_STAGE(PG8_SB(0, 1), b2 + hstep, voffB); PG8_STAGE(PG8_SA(0, 0), a2, voffA);
;             PG8_WAIT_V(8); PG8_WAIT_L(0); PG8_BAR; PG8_MMA(1, 0, At, B0); PG8_MMA(1, 1, At, B1); PG8_BAR; PG8_SCHED;
.LBB0_294:
	s_add_i32 s81, s40, 2
	s_add_u32 s82, s38, 0x80
	s_addc_u32 s41, s39, 0
	s_cmp_eq_u32 s33, s40
	s_cselect_b32 s41, s7, s41
	s_cselect_b32 s40, s6, s82
	v_add_u32_e32 v0, s19, v151
	s_cselect_b32 s83, s23, s80
	s_cselect_b32 s82, s22, s79
	s_add_i32 s84, 0, 0x14000
	ds_read_b128 v[154:157], v0
	ds_read_b128 v[158:161], v0 offset:1024
	ds_read_b128 v[162:165], v0 offset:2048
	ds_read_b128 v[166:169], v0 offset:3072
	v_add_u32_e32 v0, s84, v151
	ds_read_b128 v[170:173], v0
	ds_read_b128 v[174:177], v0 offset:1024
	ds_read_b128 v[178:181], v0 offset:2048
	ds_read_b128 v[184:187], v0 offset:3072
	v_lshl_add_u64 v[2:3], s[38:39], 0, v[144:145]
	s_add_i32 m0, s46, 0xc000
	ds_read_b128 v[188:191], v152
	ds_read_b128 v[192:195], v152 offset:1024
	ds_read_b128 v[196:199], v152 offset:2048
	ds_read_b128 v[200:203], v152 offset:3072
	ds_read_b128 v[204:207], v152 offset:4096
	ds_read_b128 v[230:233], v152 offset:5120
	ds_read_b128 v[234:237], v152 offset:6144
	ds_read_b128 v[238:241], v152 offset:7168
	global_load_lds_dwordx4 v[2:3], off
	v_lshl_add_u64 v[2:3], s[38:39], 0, v[146:147]
	s_add_i32 m0, s46, 0xe000
	s_nop 0
	global_load_lds_dwordx4 v[2:3], off
	s_waitcnt vmcnt(8)
	s_waitcnt lgkmcnt(0)
	s_barrier
	s_setprio 1
	s_waitcnt lgkmcnt(0)
	v_mfma_f32_16x16x32_bf16 v[8:11], v[154:157], v[188:191], v[8:11]
	v_mfma_f32_16x16x32_bf16 v[8:11], v[158:161], v[192:195], v[8:11]
	v_mfma_f32_16x16x32_bf16 v[48:51], v[154:157], v[196:199], v[48:51]
	v_mfma_f32_16x16x32_bf16 v[48:51], v[158:161], v[200:203], v[48:51]
	v_mfma_f32_16x16x32_bf16 v[96:99], v[154:157], v[204:207], v[96:99]
	v_mfma_f32_16x16x32_bf16 v[96:99], v[158:161], v[230:233], v[96:99]
	v_mfma_f32_16x16x32_bf16 v[120:123], v[154:157], v[234:237], v[120:123]
	v_mfma_f32_16x16x32_bf16 v[120:123], v[158:161], v[238:241], v[120:123]
	v_mfma_f32_16x16x32_bf16 v[12:15], v[162:165], v[188:191], v[12:15]
	v_mfma_f32_16x16x32_bf16 v[12:15], v[166:169], v[192:195], v[12:15]
	v_mfma_f32_16x16x32_bf16 v[52:55], v[162:165], v[196:199], v[52:55]
	v_mfma_f32_16x16x32_bf16 v[52:55], v[166:169], v[200:203], v[52:55]
	v_mfma_f32_16x16x32_bf16 v[100:103], v[162:165], v[204:207], v[100:103]
	v_mfma_f32_16x16x32_bf16 v[100:103], v[166:169], v[230:233], v[100:103]
	v_mfma_f32_16x16x32_bf16 v[124:127], v[162:165], v[234:237], v[124:127]
	v_mfma_f32_16x16x32_bf16 v[124:127], v[166:169], v[238:241], v[124:127]
	s_setprio 0
	s_setprio 1
	v_mfma_f32_16x16x32_bf16 v[24:27], v[170:173], v[188:191], v[24:27]
	v_mfma_f32_16x16x32_bf16 v[24:27], v[174:177], v[192:195], v[24:27]
	v_mfma_f32_16x16x32_bf16 v[72:75], v[170:173], v[196:199], v[72:75]
	v_mfma_f32_16x16x32_bf16 v[72:75], v[174:177], v[200:203], v[72:75]
	v_mfma_f32_16x16x32_bf16 v[112:115], v[170:173], v[204:207], v[112:115]
	v_mfma_f32_16x16x32_bf16 v[112:115], v[174:177], v[230:233], v[112:115]
	v_mfma_f32_16x16x32_bf16 v[128:131], v[170:173], v[234:237], v[128:131]
	v_mfma_f32_16x16x32_bf16 v[128:131], v[174:177], v[238:241], v[128:131]
	v_mfma_f32_16x16x32_bf16 v[28:31], v[178:181], v[188:191], v[28:31]
	v_mfma_f32_16x16x32_bf16 v[28:31], v[184:187], v[192:195], v[28:31]
	v_mfma_f32_16x16x32_bf16 v[76:79], v[178:181], v[196:199], v[76:79]
	v_mfma_f32_16x16x32_bf16 v[76:79], v[184:187], v[200:203], v[76:79]
	v_mfma_f32_16x16x32_bf16 v[116:119], v[178:181], v[204:207], v[116:119]
	v_mfma_f32_16x16x32_bf16 v[116:119], v[184:187], v[230:233], v[116:119]
	v_mfma_f32_16x16x32_bf16 v[132:135], v[178:181], v[234:237], v[132:135]
	v_mfma_f32_16x16x32_bf16 v[132:135], v[184:187], v[238:241], v[132:135]
	s_setprio 0
	s_barrier
	s_add_i32 s85, s19, s37
	v_lshl_add_u64 v[2:3], s[82:83], 0, v[140:141]
	s_mov_b32 m0, s85
	ds_read_b128 v[188:191], v152 offset:16384
	ds_read_b128 v[192:195], v152 offset:17408
	ds_read_b128 v[196:199], v152 offset:18432
	ds_read_b128 v[200:203], v152 offset:19456
	ds_read_b128 v[204:207], v152 offset:20480
	ds_read_b128 v[230:233], v152 offset:21504
	ds_read_b128 v[234:237], v152 offset:22528
	ds_read_b128 v[238:241], v152 offset:23552
	global_load_lds_dwordx4 v[2:3], off
	s_add_i32 m0, s85, 0x2000
	v_lshl_add_u64 v[208:209], s[82:83], 0, v[136:137]
	s_add_u32 s82, s82, s48
	s_addc_u32 s83, s83, s49
	s_add_i32 s84, s84, s37
	global_load_lds_dwordx4 v[208:209], off
	v_lshl_add_u64 v[216:217], s[82:83], 0, v[140:141]
	s_mov_b32 m0, s84
	v_lshl_add_u64 v[224:225], s[82:83], 0, v[136:137]
	global_load_lds_dwordx4 v[216:217], off
	s_add_i32 m0, s84, 0x2000
	v_lshl_add_u64 v[226:227], s[40:41], 0, v[142:143]
	global_load_lds_dwordx4 v[224:225], off
	s_mov_b32 m0, s46
	v_lshl_add_u64 v[228:229], s[40:41], 0, v[138:139]
	global_load_lds_dwordx4 v[226:227], off
	s_mov_b32 m0, s47
	s_nop 0
	global_load_lds_dwordx4 v[228:229], off
	s_waitcnt vmcnt(8)
	s_waitcnt lgkmcnt(0)
	s_barrier
; #define PG8_STAGE(bufoff, gbase, voff) do { _Pragma("unroll") for (int _i = 0; _i < 2; ++_i) \
;         __builtin_amdgcn_global_load_lds((const unsigned*)((const char*)(gbase) + (voff)[_i]), (PG8_LAS unsigned*)(lds + (bufoff) + ldsw + _i * 8192), 16, 0, 0); } while (0)
; #define PG8_LDA(dst, b, h) do { _Pragma("unroll") for (int m = 0; m < 4; ++m) _Pragma("unroll") for (int k = 0; k < 2; ++k) dst[m][k] = *(const PG8_LAS bf16x8*)(lds + PG8_SA(b, h) + aoff + m * 2048 + k * 1024); } while (0)
; #define PG8_LDB(dst, b, h) do { _Pragma("unroll") for (int n = 0; n < 2; ++n) _Pragma("unroll") for (int k = 0; k < 2; ++k) dst[n][k] = *(const PG8_LAS bf16x8*)(lds + PG8_SB(b, h) + boff + n * 2048 + k * 1024); } while (0)
; #define PG8_MMA(ai, bj, At, Bt) do { __builtin_amdgcn_s_setprio(1); _Pragma("unroll") for (int m = 0; m < 4; ++m) _Pragma("unroll") for (int n = 0; n < 2; ++n) _Pragma("unroll") for (int k = 0; k < 2; ++k) \
;         acc[ai][bj][m][n] = __builtin_amdgcn_mfma_f32_16x16x32_bf16(Bt[n][k], At[m][k], acc[ai][bj][m][n], 0, 0, 0); __builtin_amdgcn_s_setprio(0); } while (0)
; #define PG8_WAIT_V(n) asm volatile("s_waitcnt vmcnt(" #n ")" ::: "memory")
; #define PG8_WAIT_L(n) asm volatile("s_waitcnt lgkmcnt(" #n ")" ::: "memory")
; #define PG8_BAR __builtin_amdgcn_s_barrier()
; #define PG8_SCHED __builtin_amdgcn_sched_barrier(0)
; template <class Epi, class Sched, bool ALIGN_EPI = false, bool SP2 = false>
; __device__ __forceinline__ void gemm_phase(PG8_LAS unsigned char* lds, const Gemm g, const Sched& S, const Epi& E) {
;     ...
;             PG8_WAIT_V(8); PG8_WAIT_L(0); PG8_BAR; PG8_MMA(1, 0, At, B0); PG8_MMA(1, 1, At, B1); PG8_BAR; PG8_SCHED;
;             PG8_LDB(B0, 1, 0); PG8_LDB(B1, 1, 1); PG8_SCHED; PG8_LDA(At, 1, 0); PG8_STAGE(PG8_SA(0, 1), a2 + hstep, voffA);
;             PG8_WAIT_V(8); PG8_WAIT_L(0); PG8_BAR; PG8_MMA(0, 0, At, B0); PG8_MMA(0, 1, At, B1); PG8_BAR; PG8_SCHED;
	s_setprio 1
	s_waitcnt lgkmcnt(0)
	v_mfma_f32_16x16x32_bf16 v[16:19], v[154:157], v[188:191], v[16:19]
	v_mfma_f32_16x16x32_bf16 v[16:19], v[158:161], v[192:195], v[16:19]
	v_mfma_f32_16x16x32_bf16 v[56:59], v[154:157], v[196:199], v[56:59]
	v_mfma_f32_16x16x32_bf16 v[56:59], v[158:161], v[200:203], v[56:59]
	v_mfma_f32_16x16x32_bf16 v[104:107], v[154:157], v[204:207], v[104:107]
	v_mfma_f32_16x16x32_bf16 v[104:107], v[158:161], v[230:233], v[104:107]
	v_mfma_f32_16x16x32_bf16 v[68:71], v[154:157], v[234:237], v[68:71]
	v_mfma_f32_16x16x32_bf16 v[68:71], v[158:161], v[238:241], v[68:71]
	v_mfma_f32_16x16x32_bf16 v[20:23], v[162:165], v[188:191], v[20:23]
	v_mfma_f32_16x16x32_bf16 v[20:23], v[166:169], v[192:195], v[20:23]
	v_mfma_f32_16x16x32_bf16 v[60:63], v[162:165], v[196:199], v[60:63]
	v_mfma_f32_16x16x32_bf16 v[60:63], v[166:169], v[200:203], v[60:63]
	v_mfma_f32_16x16x32_bf16 v[108:111], v[162:165], v[204:207], v[108:111]
	v_mfma_f32_16x16x32_bf16 v[108:111], v[166:169], v[230:233], v[108:111]
	v_mfma_f32_16x16x32_bf16 v[64:67], v[162:165], v[234:237], v[64:67]
	v_mfma_f32_16x16x32_bf16 v[64:67], v[166:169], v[238:241], v[64:67]
	s_setprio 0
	s_setprio 1
	v_mfma_f32_16x16x32_bf16 v[40:43], v[170:173], v[188:191], v[40:43]
	v_mfma_f32_16x16x32_bf16 v[40:43], v[174:177], v[192:195], v[40:43]
	v_mfma_f32_16x16x32_bf16 v[88:91], v[170:173], v[196:199], v[88:91]
	v_mfma_f32_16x16x32_bf16 v[88:91], v[174:177], v[200:203], v[88:91]
	v_mfma_f32_16x16x32_bf16 v[84:87], v[170:173], v[204:207], v[84:87]
	v_mfma_f32_16x16x32_bf16 v[84:87], v[174:177], v[230:233], v[84:87]
	v_mfma_f32_16x16x32_bf16 v[36:39], v[170:173], v[234:237], v[36:39]
	v_mfma_f32_16x16x32_bf16 v[36:39], v[174:177], v[238:241], v[36:39]
	v_mfma_f32_16x16x32_bf16 v[44:47], v[178:181], v[188:191], v[44:47]
	v_mfma_f32_16x16x32_bf16 v[44:47], v[184:187], v[192:195], v[44:47]
	v_mfma_f32_16x16x32_bf16 v[92:95], v[178:181], v[196:199], v[92:95]
	v_mfma_f32_16x16x32_bf16 v[92:95], v[184:187], v[200:203], v[92:95]
	v_mfma_f32_16x16x32_bf16 v[80:83], v[178:181], v[204:207], v[80:83]
	v_mfma_f32_16x16x32_bf16 v[80:83], v[184:187], v[230:233], v[80:83]
	v_mfma_f32_16x16x32_bf16 v[32:35], v[178:181], v[234:237], v[32:35]
	v_mfma_f32_16x16x32_bf16 v[32:35], v[184:187], v[238:241], v[32:35]
	s_setprio 0
	s_barrier
	v_add_u32_e32 v0, s91, v151
	s_add_i32 s82, 0, 0x1c000
	ds_read_b128 v[154:157], v0
	ds_read_b128 v[158:161], v0 offset:1024
	ds_read_b128 v[162:165], v0 offset:2048
	ds_read_b128 v[166:169], v0 offset:3072
	v_add_u32_e32 v0, s82, v151
	ds_read_b128 v[170:173], v0
	ds_read_b128 v[174:177], v0 offset:1024
	ds_read_b128 v[178:181], v0 offset:2048
	ds_read_b128 v[184:187], v0 offset:3072
	s_add_u32 s40, s40, s48
	s_addc_u32 s41, s41, s49
	s_mov_b32 m0, s52
	v_lshl_add_u64 v[242:243], s[40:41], 0, v[142:143]
	ds_read_b128 v[188:191], v152 offset:32768
	ds_read_b128 v[192:195], v152 offset:33792
	ds_read_b128 v[196:199], v152 offset:34816
	ds_read_b128 v[200:203], v152 offset:35840
	ds_read_b128 v[204:207], v152 offset:36864
	ds_read_b128 v[230:233], v152 offset:37888
	ds_read_b128 v[234:237], v152 offset:38912
	ds_read_b128 v[238:241], v152 offset:39936
	global_load_lds_dwordx4 v[242:243], off
	v_lshl_add_u64 v[242:243], s[40:41], 0, v[138:139]
	s_mov_b32 m0, s53
	s_nop 0
	global_load_lds_dwordx4 v[242:243], off
	s_waitcnt vmcnt(8)
	s_waitcnt lgkmcnt(0)
	s_barrier
	s_setprio 1
	s_waitcnt lgkmcnt(0)
	v_mfma_f32_16x16x32_bf16 v[8:11], v[154:157], v[188:191], v[8:11]
	v_mfma_f32_16x16x32_bf16 v[8:11], v[158:161], v[192:195], v[8:11]
	v_mfma_f32_16x16x32_bf16 v[48:51], v[154:157], v[196:199], v[48:51]
	v_mfma_f32_16x16x32_bf16 v[48:51], v[158:161], v[200:203], v[48:51]
	v_mfma_f32_16x16x32_bf16 v[96:99], v[154:157], v[204:207], v[96:99]
	v_mfma_f32_16x16x32_bf16 v[96:99], v[158:161], v[230:233], v[96:99]
	v_mfma_f32_16x16x32_bf16 v[120:123], v[154:157], v[234:237], v[120:123]
	v_mfma_f32_16x16x32_bf16 v[120:123], v[158:161], v[238:241], v[120:123]
	v_mfma_f32_16x16x32_bf16 v[12:15], v[162:165], v[188:191], v[12:15]
	v_mfma_f32_16x16x32_bf16 v[12:15], v[166:169], v[192:195], v[12:15]
	v_mfma_f32_16x16x32_bf16 v[52:55], v[162:165], v[196:199], v[52:55]
	v_mfma_f32_16x16x32_bf16 v[52:55], v[166:169], v[200:203], v[52:55]
	v_mfma_f32_16x16x32_bf16 v[100:103], v[162:165], v[204:207], v[100:103]
	v_mfma_f32_16x16x32_bf16 v[100:103], v[166:169], v[230:233], v[100:103]
	v_mfma_f32_16x16x32_bf16 v[124:127], v[162:165], v[234:237], v[124:127]
	v_mfma_f32_16x16x32_bf16 v[124:127], v[166:169], v[238:241], v[124:127]
	s_setprio 0
	s_setprio 1
	v_mfma_f32_16x16x32_bf16 v[24:27], v[170:173], v[188:191], v[24:27]
	v_mfma_f32_16x16x32_bf16 v[24:27], v[174:177], v[192:195], v[24:27]
	v_mfma_f32_16x16x32_bf16 v[72:75], v[170:173], v[196:199], v[72:75]
	v_mfma_f32_16x16x32_bf16 v[72:75], v[174:177], v[200:203], v[72:75]
	v_mfma_f32_16x16x32_bf16 v[112:115], v[170:173], v[204:207], v[112:115]
	v_mfma_f32_16x16x32_bf16 v[112:115], v[174:177], v[230:233], v[112:115]
	v_mfma_f32_16x16x32_bf16 v[128:131], v[170:173], v[234:237], v[128:131]
	v_mfma_f32_16x16x32_bf16 v[128:131], v[174:177], v[238:241], v[128:131]
	v_mfma_f32_16x16x32_bf16 v[28:31], v[178:181], v[188:191], v[28:31]
	v_mfma_f32_16x16x32_bf16 v[28:31], v[184:187], v[192:195], v[28:31]
	v_mfma_f32_16x16x32_bf16 v[76:79], v[178:181], v[196:199], v[76:79]
	v_mfma_f32_16x16x32_bf16 v[76:79], v[184:187], v[200:203], v[76:79]
	v_mfma_f32_16x16x32_bf16 v[116:119], v[178:181], v[204:207], v[116:119]
	v_mfma_f32_16x16x32_bf16 v[116:119], v[184:187], v[230:233], v[116:119]
	v_mfma_f32_16x16x32_bf16 v[132:135], v[178:181], v[234:237], v[132:135]
	v_mfma_f32_16x16x32_bf16 v[132:135], v[184:187], v[238:241], v[132:135]
	s_setprio 0
	s_barrier
; #define PG8_STAGE(bufoff, gbase, voff) do { _Pragma("unroll") for (int _i = 0; _i < 2; ++_i) \
;         __builtin_amdgcn_global_load_lds((const unsigned*)((const char*)(gbase) + (voff)[_i]), (PG8_LAS unsigned*)(lds + (bufoff) + ldsw + _i * 8192), 16, 0, 0); } while (0)
; #define PG8_LDA(dst, b, h) do { _Pragma("unroll") for (int m = 0; m < 4; ++m) _Pragma("unroll") for (int k = 0; k < 2; ++k) dst[m][k] = *(const PG8_LAS bf16x8*)(lds + PG8_SA(b, h) + aoff + m * 2048 + k * 1024); } while (0)
; #define PG8_MMA(ai, bj, At, Bt) do { __builtin_amdgcn_s_setprio(1); _Pragma("unroll") for (int m = 0; m < 4; ++m) _Pragma("unroll") for (int n = 0; n < 2; ++n) _Pragma("unroll") for (int k = 0; k < 2; ++k) \
;         acc[ai][bj][m][n] = __builtin_amdgcn_mfma_f32_16x16x32_bf16(Bt[n][k], At[m][k], acc[ai][bj][m][n], 0, 0, 0); __builtin_amdgcn_s_setprio(0); } while (0)
; #define PG8_WAIT_V(n) asm volatile("s_waitcnt vmcnt(" #n ")" ::: "memory")
; #define PG8_WAIT_L(n) asm volatile("s_waitcnt lgkmcnt(" #n ")" ::: "memory")
; #define PG8_BAR __builtin_amdgcn_s_barrier()
; #define PG8_SCHED __builtin_amdgcn_sched_barrier(0)
; template <class Epi, class Sched, bool ALIGN_EPI = false, bool SP2 = false>
; __device__ __forceinline__ void gemm_phase(PG8_LAS unsigned char* lds, const Gemm g, const Sched& S, const Epi& E) {
;     ...
;         for (int t = 0; t < nt; t += 2) {
;     ...
;             PG8_LDA(At, 1, 1); PG8_STAGE(PG8_SB(1, 0), b3, voffB); PG8_STAGE(PG8_SB(1, 1), b3 + hstep, voffB); PG8_STAGE(PG8_SA(1, 0), a3, voffA);
;             PG8_WAIT_V(8); PG8_WAIT_L(0); PG8_BAR; PG8_MMA(1, 0, At, B0); PG8_MMA(1, 1, At, B1); PG8_BAR; PG8_SCHED;
	s_add_i32 s40, s91, s37
	v_lshl_add_u64 v[2:3], v[2:3], 0, s[24:25]
	s_mov_b32 m0, s40
	ds_read_b128 v[188:191], v152 offset:49152
	ds_read_b128 v[192:195], v152 offset:50176
	ds_read_b128 v[196:199], v152 offset:51200
	ds_read_b128 v[200:203], v152 offset:52224
	ds_read_b128 v[204:207], v152 offset:53248
	ds_read_b128 v[230:233], v152 offset:54272
	ds_read_b128 v[234:237], v152 offset:55296
	ds_read_b128 v[238:241], v152 offset:56320
	global_load_lds_dwordx4 v[2:3], off
	v_lshl_add_u64 v[2:3], v[208:209], 0, s[24:25]
	s_add_i32 m0, s40, 0x2000
	s_add_i32 s40, s82, s37
	global_load_lds_dwordx4 v[2:3], off
	v_lshl_add_u64 v[2:3], v[216:217], 0, s[24:25]
	s_mov_b32 m0, s40
	s_nop 0
	global_load_lds_dwordx4 v[2:3], off
	v_lshl_add_u64 v[2:3], v[224:225], 0, s[24:25]
	s_add_i32 m0, s40, 0x2000
	s_nop 0
	global_load_lds_dwordx4 v[2:3], off
	v_lshl_add_u64 v[2:3], v[226:227], 0, s[24:25]
	s_mov_b32 m0, s73
	s_nop 0
	global_load_lds_dwordx4 v[2:3], off
	v_lshl_add_u64 v[2:3], v[228:229], 0, s[24:25]
	s_mov_b32 m0, s74
	s_nop 0
	global_load_lds_dwordx4 v[2:3], off
	s_waitcnt vmcnt(8)
	s_waitcnt lgkmcnt(0)
	s_barrier
	s_setprio 1
	s_waitcnt lgkmcnt(0)
	v_mfma_f32_16x16x32_bf16 v[16:19], v[154:157], v[188:191], v[16:19]
	v_mfma_f32_16x16x32_bf16 v[16:19], v[158:161], v[192:195], v[16:19]
	v_mfma_f32_16x16x32_bf16 v[56:59], v[154:157], v[196:199], v[56:59]
	v_mfma_f32_16x16x32_bf16 v[56:59], v[158:161], v[200:203], v[56:59]
	v_mfma_f32_16x16x32_bf16 v[104:107], v[154:157], v[204:207], v[104:107]
	v_mfma_f32_16x16x32_bf16 v[104:107], v[158:161], v[230:233], v[104:107]
	v_mfma_f32_16x16x32_bf16 v[68:71], v[154:157], v[234:237], v[68:71]
	v_mfma_f32_16x16x32_bf16 v[68:71], v[158:161], v[238:241], v[68:71]
	v_mfma_f32_16x16x32_bf16 v[20:23], v[162:165], v[188:191], v[20:23]
	v_mfma_f32_16x16x32_bf16 v[20:23], v[166:169], v[192:195], v[20:23]
	v_mfma_f32_16x16x32_bf16 v[60:63], v[162:165], v[196:199], v[60:63]
	v_mfma_f32_16x16x32_bf16 v[60:63], v[166:169], v[200:203], v[60:63]
	v_mfma_f32_16x16x32_bf16 v[108:111], v[162:165], v[204:207], v[108:111]
	v_mfma_f32_16x16x32_bf16 v[108:111], v[166:169], v[230:233], v[108:111]
	v_mfma_f32_16x16x32_bf16 v[64:67], v[162:165], v[234:237], v[64:67]
	v_mfma_f32_16x16x32_bf16 v[64:67], v[166:169], v[238:241], v[64:67]
	s_setprio 0
	s_setprio 1
	v_mfma_f32_16x16x32_bf16 v[40:43], v[170:173], v[188:191], v[40:43]
	v_mfma_f32_16x16x32_bf16 v[40:43], v[174:177], v[192:195], v[40:43]
	v_mfma_f32_16x16x32_bf16 v[88:91], v[170:173], v[196:199], v[88:91]
	v_mfma_f32_16x16x32_bf16 v[88:91], v[174:177], v[200:203], v[88:91]
	v_mfma_f32_16x16x32_bf16 v[84:87], v[170:173], v[204:207], v[84:87]
	v_mfma_f32_16x16x32_bf16 v[84:87], v[174:177], v[230:233], v[84:87]
	v_mfma_f32_16x16x32_bf16 v[36:39], v[170:173], v[234:237], v[36:39]
	v_mfma_f32_16x16x32_bf16 v[36:39], v[174:177], v[238:241], v[36:39]
	v_mfma_f32_16x16x32_bf16 v[44:47], v[178:181], v[188:191], v[44:47]
	v_mfma_f32_16x16x32_bf16 v[44:47], v[184:187], v[192:195], v[44:47]
	v_mfma_f32_16x16x32_bf16 v[92:95], v[178:181], v[196:199], v[92:95]
	v_mfma_f32_16x16x32_bf16 v[92:95], v[184:187], v[200:203], v[92:95]
	v_mfma_f32_16x16x32_bf16 v[80:83], v[178:181], v[204:207], v[80:83]
	v_mfma_f32_16x16x32_bf16 v[80:83], v[184:187], v[230:233], v[80:83]
	v_mfma_f32_16x16x32_bf16 v[32:35], v[178:181], v[234:237], v[32:35]
	v_mfma_f32_16x16x32_bf16 v[32:35], v[184:187], v[238:241], v[32:35]
	s_setprio 0
	s_barrier
	s_add_u32 s38, s38, 0x100
	s_addc_u32 s39, s39, 0
	s_add_u32 s79, s79, 0x100
	s_addc_u32 s80, s80, 0
	s_cmp_ge_u32 s81, s9
	s_mov_b32 s40, s81
	s_cbranch_scc0 .LBB0_294

; #define PG8_STAGE(bufoff, gbase, voff) do { _Pragma("unroll") for (int _i = 0; _i < 2; ++_i) \
;         __builtin_amdgcn_global_load_lds((const unsigned*)((const char*)(gbase) + (voff)[_i]), (PG8_LAS unsigned*)(lds + (bufoff) + ldsw + _i * 8192), 16, 0, 0); } while (0)
; #define PG8_LDA(dst, b, h) do { _Pragma("unroll") for (int m = 0; m < 4; ++m) _Pragma("unroll") for (int k = 0; k < 2; ++k) dst[m][k] = *(const PG8_LAS bf16x8*)(lds + PG8_SA(b, h) + aoff + m * 2048 + k * 1024); } while (0)
; #define PG8_LDB(dst, b, h) do { _Pragma("unroll") for (int n = 0; n < 2; ++n) _Pragma("unroll") for (int k = 0; k < 2; ++k) dst[n][k] = *(const PG8_LAS bf16x8*)(lds + PG8_SB(b, h) + boff + n * 2048 + k * 1024); } while (0)
; #define PG8_MMA(ai, bj, At, Bt) do { __builtin_amdgcn_s_setprio(1); _Pragma("unroll") for (int m = 0; m < 4; ++m) _Pragma("unroll") for (int n = 0; n < 2; ++n) _Pragma("unroll") for (int k = 0; k < 2; ++k) \
;         acc[ai][bj][m][n] = __builtin_amdgcn_mfma_f32_16x16x32_bf16(Bt[n][k], At[m][k], acc[ai][bj][m][n], 0, 0, 0); __builtin_amdgcn_s_setprio(0); } while (0)
; #define PG8_WAIT_V(n) asm volatile("s_waitcnt vmcnt(" #n ")" ::: "memory")
; #define PG8_WAIT_L(n) asm volatile("s_waitcnt lgkmcnt(" #n ")" ::: "memory")
; template <class Epi, class Sched, bool ALIGN_EPI = false, bool SP2 = false>
; __device__ __forceinline__ void gemm_phase(PG8_LAS unsigned char* lds, const Gemm g, const Sched& S, const Epi& E) {
;     ...
;             const bool last = (t == nt - 2);
;             const char* a1 = cA + (size_t)(t + 1) * kstep;
;             const char* a2 = last ? nA : cA + (size_t)(t + 2) * kstep; const char* b2 = last ? nB : cB + (size_t)(t + 2) * kstep;
;             const char* a3 = a2 + kstep; const char* b3 = b2 + kstep;
;             if (last && has_next) S.a_ready(nxt);
;             if constexpr (SP2) {
;             PG8_LDB(B0, 0, 0); PG8_LDB(B1, 0, 1); PG8_SCHED; PG8_LDA(At, 0, 0); PG8_STAGE(PG8_SA(1, 1), a1 + hstep, voffA);
;             PG8_WAIT_V(8); PG8_WAIT_L(0); PG8_BAR; PG8_MMA(0, 0, At, B0); PG8_MMA(0, 1, At, B1); PG8_BAR; PG8_SCHED;
;             PG8_LDA(At, 0, 1); PG8_STAGE(PG8_SB(0, 0), b2, voffB); PG8_STAGE(PG8_SB(0, 1), b2 + hstep, voffB); PG8_STAGE(PG8_SA(0, 0), a2, voffA);
;             PG8_WAIT_V(8); PG8_WAIT_L(0); PG8_BAR; PG8_MMA(1, 0, At, B0); PG8_MMA(1, 1, At, B1); PG8_BAR; PG8_SCHED;
.LBB0_365:
	s_add_i32 s88, s86, 2
	s_add_u32 s89, s0, 0x80
	s_addc_u32 s87, s1, 0
	s_cmp_eq_u32 s33, s86
	s_cselect_b32 s87, s3, s87
	s_cselect_b32 s86, s2, s89
	v_add_u32_e32 v0, s19, v230
	s_cselect_b32 vcc_hi, s85, s73
	s_cselect_b32 vcc_lo, s84, s72
	s_add_i32 s89, 0, 0x14000
	ds_read_b128 v[120:123], v0
	ds_read_b128 v[124:127], v0 offset:1024
	ds_read_b128 v[128:131], v0 offset:2048
	ds_read_b128 v[132:135], v0 offset:3072
	v_add_u32_e32 v0, s89, v230
	ds_read_b128 v[136:139], v0
	ds_read_b128 v[140:143], v0 offset:1024
	ds_read_b128 v[162:165], v0 offset:2048
	ds_read_b128 v[166:169], v0 offset:3072
	v_lshl_add_u64 v[144:145], s[0:1], 0, v[184:185]
	s_add_i32 m0, s93, 0xc000
	ds_read_b128 v[170:173], v238
	ds_read_b128 v[188:191], v238 offset:1024
	ds_read_b128 v[192:195], v238 offset:2048
	ds_read_b128 v[196:199], v238 offset:3072
	ds_read_b128 v[200:203], v238 offset:4096
	ds_read_b128 v[204:207], v238 offset:5120
	ds_read_b128 v[242:245], v238 offset:6144
	ds_read_b128 v[246:249], v238 offset:7168
	global_load_lds_dwordx4 v[144:145], off
	v_lshl_add_u64 v[144:145], s[0:1], 0, v[186:187]
	s_add_i32 m0, s93, 0xe000
	s_nop 0
	global_load_lds_dwordx4 v[144:145], off
	s_waitcnt vmcnt(8)
	s_waitcnt lgkmcnt(0)
	s_barrier
	s_setprio 1
	s_waitcnt lgkmcnt(0)
	v_mfma_f32_16x16x32_bf16 v[158:161], v[120:123], v[170:173], v[158:161]
	v_mfma_f32_16x16x32_bf16 v[158:161], v[124:127], v[188:191], v[158:161]
	v_mfma_f32_16x16x32_bf16 v[150:153], v[120:123], v[192:195], v[150:153]
	v_mfma_f32_16x16x32_bf16 v[150:153], v[124:127], v[196:199], v[150:153]
	v_mfma_f32_16x16x32_bf16 v[100:103], v[120:123], v[200:203], v[100:103]
	v_mfma_f32_16x16x32_bf16 v[100:103], v[124:127], v[204:207], v[100:103]
	v_mfma_f32_16x16x32_bf16 v[116:119], v[120:123], v[242:245], v[116:119]
	v_mfma_f32_16x16x32_bf16 v[116:119], v[124:127], v[246:249], v[116:119]
	v_mfma_f32_16x16x32_bf16 v[68:71], v[128:131], v[242:245], v[68:71]
	v_mfma_f32_16x16x32_bf16 v[68:71], v[132:135], v[246:249], v[68:71]
	v_mfma_f32_16x16x32_bf16 v[36:39], v[128:131], v[200:203], v[36:39]
	v_mfma_f32_16x16x32_bf16 v[36:39], v[132:135], v[204:207], v[36:39]
	v_mfma_f32_16x16x32_bf16 v[52:55], v[128:131], v[192:195], v[52:55]
	v_mfma_f32_16x16x32_bf16 v[52:55], v[132:135], v[196:199], v[52:55]
	v_mfma_f32_16x16x32_bf16 v[60:63], v[128:131], v[170:173], v[60:63]
	v_mfma_f32_16x16x32_bf16 v[60:63], v[132:135], v[188:191], v[60:63]
	s_setprio 0
	s_setprio 1
	v_mfma_f32_16x16x32_bf16 v[154:157], v[136:139], v[170:173], v[154:157]
	v_mfma_f32_16x16x32_bf16 v[154:157], v[140:143], v[188:191], v[154:157]
	v_mfma_f32_16x16x32_bf16 v[144:147], v[136:139], v[192:195], v[146:149]
	v_mfma_f32_16x16x32_bf16 v[144:147], v[140:143], v[196:199], v[144:147]
	v_mfma_f32_16x16x32_bf16 v[96:99], v[136:139], v[200:203], v[96:99]
	v_mfma_f32_16x16x32_bf16 v[96:99], v[140:143], v[204:207], v[96:99]
	v_mfma_f32_16x16x32_bf16 v[112:115], v[136:139], v[242:245], v[112:115]
	v_mfma_f32_16x16x32_bf16 v[112:115], v[140:143], v[246:249], v[112:115]
	v_mfma_f32_16x16x32_bf16 v[64:67], v[162:165], v[242:245], v[64:67]
	v_mfma_f32_16x16x32_bf16 v[64:67], v[166:169], v[246:249], v[64:67]
	v_mfma_f32_16x16x32_bf16 v[32:35], v[162:165], v[200:203], v[32:35]
	v_mfma_f32_16x16x32_bf16 v[32:35], v[166:169], v[204:207], v[32:35]
	v_mfma_f32_16x16x32_bf16 v[48:51], v[162:165], v[192:195], v[48:51]
	v_mfma_f32_16x16x32_bf16 v[48:51], v[166:169], v[196:199], v[48:51]
	v_mfma_f32_16x16x32_bf16 v[56:59], v[162:165], v[170:173], v[56:59]
	v_mfma_f32_16x16x32_bf16 v[56:59], v[166:169], v[188:191], v[56:59]
	s_setprio 0
	s_barrier
	s_add_i32 s38, s19, s92
	v_lshl_add_u64 v[174:175], vcc, 0, v[176:177]
	s_mov_b32 m0, s38
	ds_read_b128 v[170:173], v238 offset:16384
	ds_read_b128 v[188:191], v238 offset:17408
	ds_read_b128 v[192:195], v238 offset:18432
	ds_read_b128 v[196:199], v238 offset:19456
	ds_read_b128 v[200:203], v238 offset:20480
	ds_read_b128 v[204:207], v238 offset:21504
	ds_read_b128 v[242:245], v238 offset:22528
	ds_read_b128 v[246:249], v238 offset:23552
	global_load_lds_dwordx4 v[174:175], off
	s_add_i32 m0, s38, 0x2000
	v_lshl_add_u64 v[208:209], vcc, 0, v[180:181]
	s_add_u32 vcc_lo, vcc_lo, s48
	s_addc_u32 vcc_hi, vcc_hi, s49
	s_add_i32 s38, s89, s92
	global_load_lds_dwordx4 v[208:209], off
	v_lshl_add_u64 v[216:217], vcc, 0, v[176:177]
	s_mov_b32 m0, s38
	v_lshl_add_u64 v[224:225], vcc, 0, v[180:181]
	global_load_lds_dwordx4 v[216:217], off
	s_add_i32 m0, s38, 0x2000
	v_lshl_add_u64 v[226:227], s[86:87], 0, v[2:3]
	global_load_lds_dwordx4 v[224:225], off
	s_mov_b32 m0, s93
	v_lshl_add_u64 v[228:229], s[86:87], 0, v[178:179]
	global_load_lds_dwordx4 v[226:227], off
	s_mov_b32 m0, s94
	s_nop 0
	global_load_lds_dwordx4 v[228:229], off
	s_waitcnt vmcnt(8)
	s_waitcnt lgkmcnt(0)
	s_barrier
; #define PG8_STAGE(bufoff, gbase, voff) do { _Pragma("unroll") for (int _i = 0; _i < 2; ++_i) \
;         __builtin_amdgcn_global_load_lds((const unsigned*)((const char*)(gbase) + (voff)[_i]), (PG8_LAS unsigned*)(lds + (bufoff) + ldsw + _i * 8192), 16, 0, 0); } while (0)
; #define PG8_LDA(dst, b, h) do { _Pragma("unroll") for (int m = 0; m < 4; ++m) _Pragma("unroll") for (int k = 0; k < 2; ++k) dst[m][k] = *(const PG8_LAS bf16x8*)(lds + PG8_SA(b, h) + aoff + m * 2048 + k * 1024); } while (0)
; #define PG8_LDB(dst, b, h) do { _Pragma("unroll") for (int n = 0; n < 2; ++n) _Pragma("unroll") for (int k = 0; k < 2; ++k) dst[n][k] = *(const PG8_LAS bf16x8*)(lds + PG8_SB(b, h) + boff + n * 2048 + k * 1024); } while (0)
; #define PG8_MMA(ai, bj, At, Bt) do { __builtin_amdgcn_s_setprio(1); _Pragma("unroll") for (int m = 0; m < 4; ++m) _Pragma("unroll") for (int n = 0; n < 2; ++n) _Pragma("unroll") for (int k = 0; k < 2; ++k) \
;         acc[ai][bj][m][n] = __builtin_amdgcn_mfma_f32_16x16x32_bf16(Bt[n][k], At[m][k], acc[ai][bj][m][n], 0, 0, 0); __builtin_amdgcn_s_setprio(0); } while (0)
; #define PG8_WAIT_V(n) asm volatile("s_waitcnt vmcnt(" #n ")" ::: "memory")
; #define PG8_WAIT_L(n) asm volatile("s_waitcnt lgkmcnt(" #n ")" ::: "memory")
; #define PG8_BAR __builtin_amdgcn_s_barrier()
; #define PG8_SCHED __builtin_amdgcn_sched_barrier(0)
; template <class Epi, class Sched, bool ALIGN_EPI = false, bool SP2 = false>
; __device__ __forceinline__ void gemm_phase(PG8_LAS unsigned char* lds, const Gemm g, const Sched& S, const Epi& E) {
;     ...
;             PG8_WAIT_V(8); PG8_WAIT_L(0); PG8_BAR; PG8_MMA(1, 0, At, B0); PG8_MMA(1, 1, At, B1); PG8_BAR; PG8_SCHED;
;             PG8_LDB(B0, 1, 0); PG8_LDB(B1, 1, 1); PG8_SCHED; PG8_LDA(At, 1, 0); PG8_STAGE(PG8_SA(0, 1), a2 + hstep, voffA);
;             PG8_WAIT_V(8); PG8_WAIT_L(0); PG8_BAR; PG8_MMA(0, 0, At, B0); PG8_MMA(0, 1, At, B1); PG8_BAR; PG8_SCHED;
	s_setprio 1
	s_waitcnt lgkmcnt(0)
	v_mfma_f32_16x16x32_bf16 v[92:95], v[120:123], v[170:173], v[92:95]
	v_mfma_f32_16x16x32_bf16 v[92:95], v[124:127], v[188:191], v[92:95]
	v_mfma_f32_16x16x32_bf16 v[84:87], v[120:123], v[192:195], v[84:87]
	v_mfma_f32_16x16x32_bf16 v[84:87], v[124:127], v[196:199], v[84:87]
	v_mfma_f32_16x16x32_bf16 v[76:79], v[120:123], v[200:203], v[76:79]
	v_mfma_f32_16x16x32_bf16 v[76:79], v[124:127], v[204:207], v[76:79]
	v_mfma_f32_16x16x32_bf16 v[108:111], v[120:123], v[242:245], v[108:111]
	v_mfma_f32_16x16x32_bf16 v[108:111], v[124:127], v[246:249], v[108:111]
	v_mfma_f32_16x16x32_bf16 v[28:31], v[128:131], v[170:173], v[28:31]
	v_mfma_f32_16x16x32_bf16 v[28:31], v[132:135], v[188:191], v[28:31]
	v_mfma_f32_16x16x32_bf16 v[20:23], v[128:131], v[192:195], v[20:23]
	v_mfma_f32_16x16x32_bf16 v[20:23], v[132:135], v[196:199], v[20:23]
	v_mfma_f32_16x16x32_bf16 v[12:15], v[128:131], v[200:203], v[12:15]
	v_mfma_f32_16x16x32_bf16 v[12:15], v[132:135], v[204:207], v[12:15]
	v_mfma_f32_16x16x32_bf16 v[44:47], v[128:131], v[242:245], v[44:47]
	v_mfma_f32_16x16x32_bf16 v[44:47], v[132:135], v[246:249], v[44:47]
	s_setprio 0
	s_setprio 1
	v_mfma_f32_16x16x32_bf16 v[88:91], v[136:139], v[170:173], v[88:91]
	v_mfma_f32_16x16x32_bf16 v[88:91], v[140:143], v[188:191], v[88:91]
	v_mfma_f32_16x16x32_bf16 v[80:83], v[136:139], v[192:195], v[80:83]
	v_mfma_f32_16x16x32_bf16 v[80:83], v[140:143], v[196:199], v[80:83]
	v_mfma_f32_16x16x32_bf16 v[72:75], v[136:139], v[200:203], v[72:75]
	v_mfma_f32_16x16x32_bf16 v[72:75], v[140:143], v[204:207], v[72:75]
	v_mfma_f32_16x16x32_bf16 v[104:107], v[136:139], v[242:245], v[104:107]
	v_mfma_f32_16x16x32_bf16 v[104:107], v[140:143], v[246:249], v[104:107]
	v_mfma_f32_16x16x32_bf16 v[24:27], v[162:165], v[170:173], v[24:27]
	v_mfma_f32_16x16x32_bf16 v[24:27], v[166:169], v[188:191], v[24:27]
	v_mfma_f32_16x16x32_bf16 v[16:19], v[162:165], v[192:195], v[16:19]
	v_mfma_f32_16x16x32_bf16 v[16:19], v[166:169], v[196:199], v[16:19]
	v_mfma_f32_16x16x32_bf16 v[8:11], v[162:165], v[200:203], v[8:11]
	v_mfma_f32_16x16x32_bf16 v[8:11], v[166:169], v[204:207], v[8:11]
	v_mfma_f32_16x16x32_bf16 v[40:43], v[162:165], v[242:245], v[40:43]
	v_mfma_f32_16x16x32_bf16 v[40:43], v[166:169], v[246:249], v[40:43]
	s_setprio 0
	s_barrier
	v_add_u32_e32 v0, s91, v230
	s_add_i32 s38, 0, 0x1c000
	ds_read_b128 v[120:123], v0
	ds_read_b128 v[124:127], v0 offset:1024
	ds_read_b128 v[128:131], v0 offset:2048
	ds_read_b128 v[132:135], v0 offset:3072
	v_add_u32_e32 v0, s38, v230
	ds_read_b128 v[136:139], v0
	ds_read_b128 v[140:143], v0 offset:1024
	ds_read_b128 v[162:165], v0 offset:2048
	ds_read_b128 v[166:169], v0 offset:3072
	s_add_u32 s86, s86, s48
	s_addc_u32 s87, s87, s49
	s_mov_b32 m0, s95
	v_lshl_add_u64 v[148:149], s[86:87], 0, v[2:3]
	ds_read_b128 v[170:173], v238 offset:32768
	ds_read_b128 v[188:191], v238 offset:33792
	ds_read_b128 v[192:195], v238 offset:34816
	ds_read_b128 v[196:199], v238 offset:35840
	ds_read_b128 v[200:203], v238 offset:36864
	ds_read_b128 v[204:207], v238 offset:37888
	ds_read_b128 v[242:245], v238 offset:38912
	ds_read_b128 v[246:249], v238 offset:39936
	global_load_lds_dwordx4 v[148:149], off
	v_lshl_add_u64 v[148:149], s[86:87], 0, v[178:179]
	s_mov_b32 m0, s96
	s_nop 0
	global_load_lds_dwordx4 v[148:149], off
	s_waitcnt vmcnt(8)
	s_waitcnt lgkmcnt(0)
	s_barrier
	s_setprio 1
	s_waitcnt lgkmcnt(0)
	v_mfma_f32_16x16x32_bf16 v[158:161], v[120:123], v[170:173], v[158:161]
	v_mfma_f32_16x16x32_bf16 v[158:161], v[124:127], v[188:191], v[158:161]
	v_mfma_f32_16x16x32_bf16 v[148:151], v[120:123], v[192:195], v[150:153]
	v_mfma_f32_16x16x32_bf16 v[150:153], v[124:127], v[196:199], v[148:151]
	v_mfma_f32_16x16x32_bf16 v[100:103], v[120:123], v[200:203], v[100:103]
	v_mfma_f32_16x16x32_bf16 v[100:103], v[124:127], v[204:207], v[100:103]
	v_mfma_f32_16x16x32_bf16 v[116:119], v[120:123], v[242:245], v[116:119]
	v_mfma_f32_16x16x32_bf16 v[116:119], v[124:127], v[246:249], v[116:119]
	v_mfma_f32_16x16x32_bf16 v[68:71], v[128:131], v[242:245], v[68:71]
	v_mfma_f32_16x16x32_bf16 v[68:71], v[132:135], v[246:249], v[68:71]
	v_mfma_f32_16x16x32_bf16 v[36:39], v[128:131], v[200:203], v[36:39]
	v_mfma_f32_16x16x32_bf16 v[36:39], v[132:135], v[204:207], v[36:39]
	v_mfma_f32_16x16x32_bf16 v[52:55], v[128:131], v[192:195], v[52:55]
	v_mfma_f32_16x16x32_bf16 v[52:55], v[132:135], v[196:199], v[52:55]
	v_mfma_f32_16x16x32_bf16 v[60:63], v[128:131], v[170:173], v[60:63]
	v_mfma_f32_16x16x32_bf16 v[60:63], v[132:135], v[188:191], v[60:63]
	s_setprio 0
	s_setprio 1
	v_mfma_f32_16x16x32_bf16 v[154:157], v[136:139], v[170:173], v[154:157]
	v_mfma_f32_16x16x32_bf16 v[154:157], v[140:143], v[188:191], v[154:157]
	v_mfma_f32_16x16x32_bf16 v[144:147], v[136:139], v[192:195], v[144:147]
	v_mfma_f32_16x16x32_bf16 v[146:149], v[140:143], v[196:199], v[144:147]
	v_mfma_f32_16x16x32_bf16 v[96:99], v[136:139], v[200:203], v[96:99]
	v_mfma_f32_16x16x32_bf16 v[96:99], v[140:143], v[204:207], v[96:99]
	v_mfma_f32_16x16x32_bf16 v[112:115], v[136:139], v[242:245], v[112:115]
	v_mfma_f32_16x16x32_bf16 v[112:115], v[140:143], v[246:249], v[112:115]
	v_mfma_f32_16x16x32_bf16 v[64:67], v[162:165], v[242:245], v[64:67]
	v_mfma_f32_16x16x32_bf16 v[64:67], v[166:169], v[246:249], v[64:67]
	v_mfma_f32_16x16x32_bf16 v[32:35], v[162:165], v[200:203], v[32:35]
	v_mfma_f32_16x16x32_bf16 v[32:35], v[166:169], v[204:207], v[32:35]
	v_mfma_f32_16x16x32_bf16 v[48:51], v[162:165], v[192:195], v[48:51]
	v_mfma_f32_16x16x32_bf16 v[48:51], v[166:169], v[196:199], v[48:51]
	v_mfma_f32_16x16x32_bf16 v[56:59], v[162:165], v[170:173], v[56:59]
	v_mfma_f32_16x16x32_bf16 v[56:59], v[166:169], v[188:191], v[56:59]
	s_setprio 0
	s_barrier
; #define PG8_STAGE(bufoff, gbase, voff) do { _Pragma("unroll") for (int _i = 0; _i < 2; ++_i) \
;         __builtin_amdgcn_global_load_lds((const unsigned*)((const char*)(gbase) + (voff)[_i]), (PG8_LAS unsigned*)(lds + (bufoff) + ldsw + _i * 8192), 16, 0, 0); } while (0)
; #define PG8_LDA(dst, b, h) do { _Pragma("unroll") for (int m = 0; m < 4; ++m) _Pragma("unroll") for (int k = 0; k < 2; ++k) dst[m][k] = *(const PG8_LAS bf16x8*)(lds + PG8_SA(b, h) + aoff + m * 2048 + k * 1024); } while (0)
; #define PG8_MMA(ai, bj, At, Bt) do { __builtin_amdgcn_s_setprio(1); _Pragma("unroll") for (int m = 0; m < 4; ++m) _Pragma("unroll") for (int n = 0; n < 2; ++n) _Pragma("unroll") for (int k = 0; k < 2; ++k) \
;         acc[ai][bj][m][n] = __builtin_amdgcn_mfma_f32_16x16x32_bf16(Bt[n][k], At[m][k], acc[ai][bj][m][n], 0, 0, 0); __builtin_amdgcn_s_setprio(0); } while (0)
; #define PG8_WAIT_V(n) asm volatile("s_waitcnt vmcnt(" #n ")" ::: "memory")
; #define PG8_WAIT_L(n) asm volatile("s_waitcnt lgkmcnt(" #n ")" ::: "memory")
; #define PG8_BAR __builtin_amdgcn_s_barrier()
; #define PG8_SCHED __builtin_amdgcn_sched_barrier(0)
; template <class Epi, class Sched, bool ALIGN_EPI = false, bool SP2 = false>
; __device__ __forceinline__ void gemm_phase(PG8_LAS unsigned char* lds, const Gemm g, const Sched& S, const Epi& E) {
;     ...
;         for (int t = 0; t < nt; t += 2) {
;     ...
;             PG8_LDA(At, 1, 1); PG8_STAGE(PG8_SB(1, 0), b3, voffB); PG8_STAGE(PG8_SB(1, 1), b3 + hstep, voffB); PG8_STAGE(PG8_SA(1, 0), a3, voffA);
;             PG8_WAIT_V(8); PG8_WAIT_L(0); PG8_BAR; PG8_MMA(1, 0, At, B0); PG8_MMA(1, 1, At, B1); PG8_BAR; PG8_SCHED;
	s_add_i32 s39, s91, s92
	v_lshl_add_u64 v[144:145], v[174:175], 0, s[24:25]
	s_mov_b32 m0, s39
	ds_read_b128 v[170:173], v238 offset:49152
	ds_read_b128 v[188:191], v238 offset:50176
	ds_read_b128 v[192:195], v238 offset:51200
	ds_read_b128 v[196:199], v238 offset:52224
	ds_read_b128 v[200:203], v238 offset:53248
	ds_read_b128 v[204:207], v238 offset:54272
	ds_read_b128 v[242:245], v238 offset:55296
	ds_read_b128 v[246:249], v238 offset:56320
	global_load_lds_dwordx4 v[144:145], off
	v_lshl_add_u64 v[144:145], v[208:209], 0, s[24:25]
	s_add_i32 m0, s39, 0x2000
	s_add_i32 s38, s38, s92
	global_load_lds_dwordx4 v[144:145], off
	v_lshl_add_u64 v[144:145], v[216:217], 0, s[24:25]
	s_mov_b32 m0, s38
	s_nop 0
	global_load_lds_dwordx4 v[144:145], off
	v_lshl_add_u64 v[144:145], v[224:225], 0, s[24:25]
	s_add_i32 m0, s38, 0x2000
	s_nop 0
	global_load_lds_dwordx4 v[144:145], off
	v_lshl_add_u64 v[144:145], v[226:227], 0, s[24:25]
	s_mov_b32 m0, s10
	s_nop 0
	global_load_lds_dwordx4 v[144:145], off
	v_lshl_add_u64 v[144:145], v[228:229], 0, s[24:25]
	s_mov_b32 m0, s11
	s_nop 0
	global_load_lds_dwordx4 v[144:145], off
	s_waitcnt vmcnt(8)
	s_waitcnt lgkmcnt(0)
	s_barrier
	s_setprio 1
	s_waitcnt lgkmcnt(0)
	v_mfma_f32_16x16x32_bf16 v[92:95], v[120:123], v[170:173], v[92:95]
	v_mfma_f32_16x16x32_bf16 v[92:95], v[124:127], v[188:191], v[92:95]
	v_mfma_f32_16x16x32_bf16 v[84:87], v[120:123], v[192:195], v[84:87]
	v_mfma_f32_16x16x32_bf16 v[84:87], v[124:127], v[196:199], v[84:87]
	v_mfma_f32_16x16x32_bf16 v[76:79], v[120:123], v[200:203], v[76:79]
	v_mfma_f32_16x16x32_bf16 v[76:79], v[124:127], v[204:207], v[76:79]
	v_mfma_f32_16x16x32_bf16 v[108:111], v[120:123], v[242:245], v[108:111]
	v_mfma_f32_16x16x32_bf16 v[108:111], v[124:127], v[246:249], v[108:111]
	v_mfma_f32_16x16x32_bf16 v[28:31], v[128:131], v[170:173], v[28:31]
	v_mfma_f32_16x16x32_bf16 v[28:31], v[132:135], v[188:191], v[28:31]
	v_mfma_f32_16x16x32_bf16 v[20:23], v[128:131], v[192:195], v[20:23]
	v_mfma_f32_16x16x32_bf16 v[20:23], v[132:135], v[196:199], v[20:23]
	v_mfma_f32_16x16x32_bf16 v[12:15], v[128:131], v[200:203], v[12:15]
	v_mfma_f32_16x16x32_bf16 v[12:15], v[132:135], v[204:207], v[12:15]
	v_mfma_f32_16x16x32_bf16 v[44:47], v[128:131], v[242:245], v[44:47]
	v_mfma_f32_16x16x32_bf16 v[44:47], v[132:135], v[246:249], v[44:47]
	s_setprio 0
	s_setprio 1
	v_mfma_f32_16x16x32_bf16 v[88:91], v[136:139], v[170:173], v[88:91]
	v_mfma_f32_16x16x32_bf16 v[88:91], v[140:143], v[188:191], v[88:91]
	v_mfma_f32_16x16x32_bf16 v[80:83], v[136:139], v[192:195], v[80:83]
	v_mfma_f32_16x16x32_bf16 v[80:83], v[140:143], v[196:199], v[80:83]
	v_mfma_f32_16x16x32_bf16 v[72:75], v[136:139], v[200:203], v[72:75]
	v_mfma_f32_16x16x32_bf16 v[72:75], v[140:143], v[204:207], v[72:75]
	v_mfma_f32_16x16x32_bf16 v[104:107], v[136:139], v[242:245], v[104:107]
	v_mfma_f32_16x16x32_bf16 v[104:107], v[140:143], v[246:249], v[104:107]
	v_mfma_f32_16x16x32_bf16 v[24:27], v[162:165], v[170:173], v[24:27]
	v_mfma_f32_16x16x32_bf16 v[24:27], v[166:169], v[188:191], v[24:27]
	v_mfma_f32_16x16x32_bf16 v[16:19], v[162:165], v[192:195], v[16:19]
	v_mfma_f32_16x16x32_bf16 v[16:19], v[166:169], v[196:199], v[16:19]
	v_mfma_f32_16x16x32_bf16 v[8:11], v[162:165], v[200:203], v[8:11]
	v_mfma_f32_16x16x32_bf16 v[8:11], v[166:169], v[204:207], v[8:11]
	v_mfma_f32_16x16x32_bf16 v[40:43], v[162:165], v[242:245], v[40:43]
	v_mfma_f32_16x16x32_bf16 v[40:43], v[166:169], v[246:249], v[40:43]
	s_setprio 0
	s_barrier
	s_add_u32 s0, s0, 0x100
	s_addc_u32 s1, s1, 0
	s_add_u32 s72, s72, 0x100
	s_addc_u32 s73, s73, 0
	s_cmp_ge_u32 s88, s9
	s_mov_b32 s86, s88
	s_cbranch_scc0 .LBB0_365

; #define PG8_STAGE(bufoff, gbase, voff) do { _Pragma("unroll") for (int _i = 0; _i < 2; ++_i) \
;         __builtin_amdgcn_global_load_lds((const unsigned*)((const char*)(gbase) + (voff)[_i]), (PG8_LAS unsigned*)(lds + (bufoff) + ldsw + _i * 8192), 16, 0, 0); } while (0)
; #define PG8_LDA(dst, b, h) do { _Pragma("unroll") for (int m = 0; m < 4; ++m) _Pragma("unroll") for (int k = 0; k < 2; ++k) dst[m][k] = *(const PG8_LAS bf16x8*)(lds + PG8_SA(b, h) + aoff + m * 2048 + k * 1024); } while (0)
; #define PG8_LDB(dst, b, h) do { _Pragma("unroll") for (int n = 0; n < 2; ++n) _Pragma("unroll") for (int k = 0; k < 2; ++k) dst[n][k] = *(const PG8_LAS bf16x8*)(lds + PG8_SB(b, h) + boff + n * 2048 + k * 1024); } while (0)
; #define PG8_MMA(ai, bj, At, Bt) do { __builtin_amdgcn_s_setprio(1); _Pragma("unroll") for (int m = 0; m < 4; ++m) _Pragma("unroll") for (int n = 0; n < 2; ++n) _Pragma("unroll") for (int k = 0; k < 2; ++k) \
;         acc[ai][bj][m][n] = __builtin_amdgcn_mfma_f32_16x16x32_bf16(Bt[n][k], At[m][k], acc[ai][bj][m][n], 0, 0, 0); __builtin_amdgcn_s_setprio(0); } while (0)
; #define PG8_WAIT_V(n) asm volatile("s_waitcnt vmcnt(" #n ")" ::: "memory")
; #define PG8_WAIT_L(n) asm volatile("s_waitcnt lgkmcnt(" #n ")" ::: "memory")
; template <class Epi, class Sched, bool ALIGN_EPI = false, bool SP2 = false>
; __device__ __forceinline__ void gemm_phase(PG8_LAS unsigned char* lds, const Gemm g, const Sched& S, const Epi& E) {
;     ...
;             const bool last = (t == nt - 2);
;             const char* a1 = cA + (size_t)(t + 1) * kstep;
;             const char* a2 = last ? nA : cA + (size_t)(t + 2) * kstep; const char* b2 = last ? nB : cB + (size_t)(t + 2) * kstep;
;             const char* a3 = a2 + kstep; const char* b3 = b2 + kstep;
;             if (last && has_next) S.a_ready(nxt);
;             if constexpr (SP2) {
;             PG8_LDB(B0, 0, 0); PG8_LDB(B1, 0, 1); PG8_SCHED; PG8_LDA(At, 0, 0); PG8_STAGE(PG8_SA(1, 1), a1 + hstep, voffA);
;             PG8_WAIT_V(8); PG8_WAIT_L(0); PG8_BAR; PG8_MMA(0, 0, At, B0); PG8_MMA(0, 1, At, B1); PG8_BAR; PG8_SCHED;
;             PG8_LDA(At, 0, 1); PG8_STAGE(PG8_SB(0, 0), b2, voffB); PG8_STAGE(PG8_SB(0, 1), b2 + hstep, voffB); PG8_STAGE(PG8_SA(0, 0), a2, voffA);
;             PG8_WAIT_V(8); PG8_WAIT_L(0); PG8_BAR; PG8_MMA(1, 0, At, B0); PG8_MMA(1, 1, At, B1); PG8_BAR; PG8_SCHED;
.LBB0_468:
	s_add_i32 s78, s38, 2
	s_add_u32 s79, s0, 0x80
	s_addc_u32 s39, s1, 0
	s_cmp_eq_u32 s33, s38
	s_cselect_b32 s39, s7, s39
	s_cselect_b32 s38, s6, s79
	s_cselect_b32 s81, s23, s41
	s_cselect_b32 s80, s22, s40
	s_add_i32 s79, 0, 0x14000
	v_add_u32_e32 v148, s19, v162
	v_add_u32_e32 v171, s79, v162
	ds_read_b128 v[136:139], v148
	ds_read_b128 v[140:143], v148 offset:1024
	ds_read_b128 v[144:147], v148 offset:2048
	ds_read_b128 v[148:151], v148 offset:3072
	ds_read_b128 v[172:175], v171
	ds_read_b128 v[176:179], v171 offset:1024
	ds_read_b128 v[184:187], v171 offset:2048
	ds_read_b128 v[188:191], v171 offset:3072
	v_lshl_add_u64 v[180:181], s[0:1], 0, v[158:159]
	s_add_i32 m0, s46, 0xc000
	ds_read_b128 v[192:195], v167
	ds_read_b128 v[196:199], v167 offset:1024
	ds_read_b128 v[200:203], v167 offset:2048
	ds_read_b128 v[204:207], v167 offset:3072
	ds_read_b128 v[230:233], v167 offset:4096
	ds_read_b128 v[234:237], v167 offset:5120
	ds_read_b128 v[238:241], v167 offset:6144
	ds_read_b128 v[242:245], v167 offset:7168
	global_load_lds_dwordx4 v[180:181], off
	v_lshl_add_u64 v[180:181], s[0:1], 0, v[160:161]
	s_add_i32 m0, s46, 0xe000
	s_nop 0
	global_load_lds_dwordx4 v[180:181], off
	s_waitcnt vmcnt(8)
	s_waitcnt lgkmcnt(0)
	s_barrier
	s_setprio 1
	s_waitcnt lgkmcnt(0)
	v_mfma_f32_16x16x32_bf16 v[132:135], v[136:139], v[192:195], v[132:135]
	v_mfma_f32_16x16x32_bf16 v[132:135], v[140:143], v[196:199], v[132:135]
	v_mfma_f32_16x16x32_bf16 v[116:119], v[136:139], v[200:203], v[116:119]
	v_mfma_f32_16x16x32_bf16 v[116:119], v[140:143], v[204:207], v[116:119]
	v_mfma_f32_16x16x32_bf16 v[100:103], v[136:139], v[230:233], v[100:103]
	v_mfma_f32_16x16x32_bf16 v[100:103], v[140:143], v[234:237], v[100:103]
	v_mfma_f32_16x16x32_bf16 v[84:87], v[136:139], v[238:241], v[84:87]
	v_mfma_f32_16x16x32_bf16 v[84:87], v[140:143], v[242:245], v[84:87]
	v_mfma_f32_16x16x32_bf16 v[128:131], v[144:147], v[192:195], v[128:131]
	v_mfma_f32_16x16x32_bf16 v[128:131], v[148:151], v[196:199], v[128:131]
	v_mfma_f32_16x16x32_bf16 v[112:115], v[144:147], v[200:203], v[112:115]
	v_mfma_f32_16x16x32_bf16 v[112:115], v[148:151], v[204:207], v[112:115]
	v_mfma_f32_16x16x32_bf16 v[96:99], v[144:147], v[230:233], v[96:99]
	v_mfma_f32_16x16x32_bf16 v[96:99], v[148:151], v[234:237], v[96:99]
	v_mfma_f32_16x16x32_bf16 v[80:83], v[144:147], v[238:241], v[80:83]
	v_mfma_f32_16x16x32_bf16 v[80:83], v[148:151], v[242:245], v[80:83]
	s_setprio 0
	s_setprio 1
	v_mfma_f32_16x16x32_bf16 v[124:127], v[172:175], v[192:195], v[124:127]
	v_mfma_f32_16x16x32_bf16 v[124:127], v[176:179], v[196:199], v[124:127]
	v_mfma_f32_16x16x32_bf16 v[108:111], v[172:175], v[200:203], v[108:111]
	v_mfma_f32_16x16x32_bf16 v[108:111], v[176:179], v[204:207], v[108:111]
	v_mfma_f32_16x16x32_bf16 v[92:95], v[172:175], v[230:233], v[92:95]
	v_mfma_f32_16x16x32_bf16 v[92:95], v[176:179], v[234:237], v[92:95]
	v_mfma_f32_16x16x32_bf16 v[76:79], v[172:175], v[238:241], v[76:79]
	v_mfma_f32_16x16x32_bf16 v[76:79], v[176:179], v[242:245], v[76:79]
	v_mfma_f32_16x16x32_bf16 v[120:123], v[184:187], v[192:195], v[120:123]
	v_mfma_f32_16x16x32_bf16 v[120:123], v[188:191], v[196:199], v[120:123]
	v_mfma_f32_16x16x32_bf16 v[104:107], v[184:187], v[200:203], v[104:107]
	v_mfma_f32_16x16x32_bf16 v[104:107], v[188:191], v[204:207], v[104:107]
	v_mfma_f32_16x16x32_bf16 v[88:91], v[184:187], v[230:233], v[88:91]
	v_mfma_f32_16x16x32_bf16 v[88:91], v[188:191], v[234:237], v[88:91]
	v_mfma_f32_16x16x32_bf16 v[72:75], v[184:187], v[238:241], v[72:75]
	v_mfma_f32_16x16x32_bf16 v[72:75], v[188:191], v[242:245], v[72:75]
	s_setprio 0
	s_barrier
	s_add_i32 s82, s19, s42
	v_lshl_add_u64 v[180:181], s[80:81], 0, v[154:155]
	s_mov_b32 m0, s82
	ds_read_b128 v[192:195], v167 offset:16384
	ds_read_b128 v[196:199], v167 offset:17408
	ds_read_b128 v[200:203], v167 offset:18432
	ds_read_b128 v[204:207], v167 offset:19456
	ds_read_b128 v[230:233], v167 offset:20480
	ds_read_b128 v[234:237], v167 offset:21504
	ds_read_b128 v[238:241], v167 offset:22528
	ds_read_b128 v[242:245], v167 offset:23552
	global_load_lds_dwordx4 v[180:181], off
	s_add_i32 m0, s82, 0x2000
	v_lshl_add_u64 v[208:209], s[80:81], 0, v[2:3]
	s_add_u32 s80, s80, s48
	s_addc_u32 s81, s81, s49
	s_add_i32 s79, s79, s42
	global_load_lds_dwordx4 v[208:209], off
	v_lshl_add_u64 v[216:217], s[80:81], 0, v[154:155]
	s_mov_b32 m0, s79
	v_lshl_add_u64 v[224:225], s[80:81], 0, v[2:3]
	global_load_lds_dwordx4 v[216:217], off
	s_add_i32 m0, s79, 0x2000
	v_lshl_add_u64 v[226:227], s[38:39], 0, v[156:157]
	global_load_lds_dwordx4 v[224:225], off
	s_mov_b32 m0, s46
	v_lshl_add_u64 v[246:247], s[38:39], 0, v[152:153]
	global_load_lds_dwordx4 v[226:227], off
	s_mov_b32 m0, s47
	s_nop 0
	global_load_lds_dwordx4 v[246:247], off
	s_waitcnt vmcnt(8)
	s_waitcnt lgkmcnt(0)
	s_barrier
; #define PG8_STAGE(bufoff, gbase, voff) do { _Pragma("unroll") for (int _i = 0; _i < 2; ++_i) \
;         __builtin_amdgcn_global_load_lds((const unsigned*)((const char*)(gbase) + (voff)[_i]), (PG8_LAS unsigned*)(lds + (bufoff) + ldsw + _i * 8192), 16, 0, 0); } while (0)
; #define PG8_LDA(dst, b, h) do { _Pragma("unroll") for (int m = 0; m < 4; ++m) _Pragma("unroll") for (int k = 0; k < 2; ++k) dst[m][k] = *(const PG8_LAS bf16x8*)(lds + PG8_SA(b, h) + aoff + m * 2048 + k * 1024); } while (0)
; #define PG8_LDB(dst, b, h) do { _Pragma("unroll") for (int n = 0; n < 2; ++n) _Pragma("unroll") for (int k = 0; k < 2; ++k) dst[n][k] = *(const PG8_LAS bf16x8*)(lds + PG8_SB(b, h) + boff + n * 2048 + k * 1024); } while (0)
; #define PG8_MMA(ai, bj, At, Bt) do { __builtin_amdgcn_s_setprio(1); _Pragma("unroll") for (int m = 0; m < 4; ++m) _Pragma("unroll") for (int n = 0; n < 2; ++n) _Pragma("unroll") for (int k = 0; k < 2; ++k) \
;         acc[ai][bj][m][n] = __builtin_amdgcn_mfma_f32_16x16x32_bf16(Bt[n][k], At[m][k], acc[ai][bj][m][n], 0, 0, 0); __builtin_amdgcn_s_setprio(0); } while (0)
; #define PG8_WAIT_V(n) asm volatile("s_waitcnt vmcnt(" #n ")" ::: "memory")
; #define PG8_WAIT_L(n) asm volatile("s_waitcnt lgkmcnt(" #n ")" ::: "memory")
; #define PG8_BAR __builtin_amdgcn_s_barrier()
; #define PG8_SCHED __builtin_amdgcn_sched_barrier(0)
; template <class Epi, class Sched, bool ALIGN_EPI = false, bool SP2 = false>
; __device__ __forceinline__ void gemm_phase(PG8_LAS unsigned char* lds, const Gemm g, const Sched& S, const Epi& E) {
;     ...
;             PG8_WAIT_V(8); PG8_WAIT_L(0); PG8_BAR; PG8_MMA(1, 0, At, B0); PG8_MMA(1, 1, At, B1); PG8_BAR; PG8_SCHED;
;             PG8_LDB(B0, 1, 0); PG8_LDB(B1, 1, 1); PG8_SCHED; PG8_LDA(At, 1, 0); PG8_STAGE(PG8_SA(0, 1), a2 + hstep, voffA);
;             PG8_WAIT_V(8); PG8_WAIT_L(0); PG8_BAR; PG8_MMA(0, 0, At, B0); PG8_MMA(0, 1, At, B1); PG8_BAR; PG8_SCHED;
	s_setprio 1
	s_waitcnt lgkmcnt(0)
	v_mfma_f32_16x16x32_bf16 v[68:71], v[136:139], v[192:195], v[68:71]
	v_mfma_f32_16x16x32_bf16 v[68:71], v[140:143], v[196:199], v[68:71]
	v_mfma_f32_16x16x32_bf16 v[52:55], v[136:139], v[200:203], v[52:55]
	v_mfma_f32_16x16x32_bf16 v[52:55], v[140:143], v[204:207], v[52:55]
	v_mfma_f32_16x16x32_bf16 v[36:39], v[136:139], v[230:233], v[36:39]
	v_mfma_f32_16x16x32_bf16 v[36:39], v[140:143], v[234:237], v[36:39]
	v_mfma_f32_16x16x32_bf16 v[20:23], v[136:139], v[238:241], v[20:23]
	v_mfma_f32_16x16x32_bf16 v[20:23], v[140:143], v[242:245], v[20:23]
	v_mfma_f32_16x16x32_bf16 v[64:67], v[144:147], v[192:195], v[64:67]
	v_mfma_f32_16x16x32_bf16 v[64:67], v[148:151], v[196:199], v[64:67]
	v_mfma_f32_16x16x32_bf16 v[48:51], v[144:147], v[200:203], v[48:51]
	v_mfma_f32_16x16x32_bf16 v[48:51], v[148:151], v[204:207], v[48:51]
	v_mfma_f32_16x16x32_bf16 v[32:35], v[144:147], v[230:233], v[32:35]
	v_mfma_f32_16x16x32_bf16 v[32:35], v[148:151], v[234:237], v[32:35]
	v_mfma_f32_16x16x32_bf16 v[16:19], v[144:147], v[238:241], v[16:19]
	v_mfma_f32_16x16x32_bf16 v[16:19], v[148:151], v[242:245], v[16:19]
	s_setprio 0
	s_setprio 1
	v_mfma_f32_16x16x32_bf16 v[60:63], v[172:175], v[192:195], v[60:63]
	v_mfma_f32_16x16x32_bf16 v[60:63], v[176:179], v[196:199], v[60:63]
	v_mfma_f32_16x16x32_bf16 v[44:47], v[172:175], v[200:203], v[44:47]
	v_mfma_f32_16x16x32_bf16 v[44:47], v[176:179], v[204:207], v[44:47]
	v_mfma_f32_16x16x32_bf16 v[28:31], v[172:175], v[230:233], v[28:31]
	v_mfma_f32_16x16x32_bf16 v[28:31], v[176:179], v[234:237], v[28:31]
	v_mfma_f32_16x16x32_bf16 v[12:15], v[172:175], v[238:241], v[12:15]
	v_mfma_f32_16x16x32_bf16 v[12:15], v[176:179], v[242:245], v[12:15]
	v_mfma_f32_16x16x32_bf16 v[56:59], v[184:187], v[192:195], v[56:59]
	v_mfma_f32_16x16x32_bf16 v[56:59], v[188:191], v[196:199], v[56:59]
	v_mfma_f32_16x16x32_bf16 v[40:43], v[184:187], v[200:203], v[40:43]
	v_mfma_f32_16x16x32_bf16 v[40:43], v[188:191], v[204:207], v[40:43]
	v_mfma_f32_16x16x32_bf16 v[24:27], v[184:187], v[230:233], v[24:27]
	v_mfma_f32_16x16x32_bf16 v[24:27], v[188:191], v[234:237], v[24:27]
	v_mfma_f32_16x16x32_bf16 v[8:11], v[184:187], v[238:241], v[8:11]
	v_mfma_f32_16x16x32_bf16 v[8:11], v[188:191], v[242:245], v[8:11]
	s_setprio 0
	s_barrier
	s_add_i32 s79, 0, 0x1c000
	v_add_u32_e32 v148, s91, v162
	v_add_u32_e32 v171, s79, v162
	ds_read_b128 v[136:139], v148
	ds_read_b128 v[140:143], v148 offset:1024
	ds_read_b128 v[144:147], v148 offset:2048
	ds_read_b128 v[148:151], v148 offset:3072
	ds_read_b128 v[172:175], v171
	ds_read_b128 v[176:179], v171 offset:1024
	ds_read_b128 v[184:187], v171 offset:2048
	ds_read_b128 v[188:191], v171 offset:3072
	s_add_u32 s38, s38, s48
	s_addc_u32 s39, s39, s49
	s_mov_b32 m0, s52
	v_lshl_add_u64 v[248:249], s[38:39], 0, v[156:157]
	ds_read_b128 v[192:195], v167 offset:32768
	ds_read_b128 v[196:199], v167 offset:33792
	ds_read_b128 v[200:203], v167 offset:34816
	ds_read_b128 v[204:207], v167 offset:35840
	ds_read_b128 v[230:233], v167 offset:36864
	ds_read_b128 v[234:237], v167 offset:37888
	ds_read_b128 v[238:241], v167 offset:38912
	ds_read_b128 v[242:245], v167 offset:39936
	global_load_lds_dwordx4 v[248:249], off
	v_lshl_add_u64 v[248:249], s[38:39], 0, v[152:153]
	s_mov_b32 m0, s53
	s_nop 0
	global_load_lds_dwordx4 v[248:249], off
	s_waitcnt vmcnt(8)
	s_waitcnt lgkmcnt(0)
	s_barrier
	s_setprio 1
	s_waitcnt lgkmcnt(0)
	v_mfma_f32_16x16x32_bf16 v[132:135], v[136:139], v[192:195], v[132:135]
	v_mfma_f32_16x16x32_bf16 v[132:135], v[140:143], v[196:199], v[132:135]
	v_mfma_f32_16x16x32_bf16 v[116:119], v[136:139], v[200:203], v[116:119]
	v_mfma_f32_16x16x32_bf16 v[116:119], v[140:143], v[204:207], v[116:119]
	v_mfma_f32_16x16x32_bf16 v[100:103], v[136:139], v[230:233], v[100:103]
	v_mfma_f32_16x16x32_bf16 v[100:103], v[140:143], v[234:237], v[100:103]
	v_mfma_f32_16x16x32_bf16 v[84:87], v[136:139], v[238:241], v[84:87]
	v_mfma_f32_16x16x32_bf16 v[84:87], v[140:143], v[242:245], v[84:87]
	v_mfma_f32_16x16x32_bf16 v[128:131], v[144:147], v[192:195], v[128:131]
	v_mfma_f32_16x16x32_bf16 v[128:131], v[148:151], v[196:199], v[128:131]
	v_mfma_f32_16x16x32_bf16 v[112:115], v[144:147], v[200:203], v[112:115]
	v_mfma_f32_16x16x32_bf16 v[112:115], v[148:151], v[204:207], v[112:115]
	v_mfma_f32_16x16x32_bf16 v[96:99], v[144:147], v[230:233], v[96:99]
	v_mfma_f32_16x16x32_bf16 v[96:99], v[148:151], v[234:237], v[96:99]
	v_mfma_f32_16x16x32_bf16 v[80:83], v[144:147], v[238:241], v[80:83]
	v_mfma_f32_16x16x32_bf16 v[80:83], v[148:151], v[242:245], v[80:83]
	s_setprio 0
	s_setprio 1
	v_mfma_f32_16x16x32_bf16 v[124:127], v[172:175], v[192:195], v[124:127]
	v_mfma_f32_16x16x32_bf16 v[124:127], v[176:179], v[196:199], v[124:127]
	v_mfma_f32_16x16x32_bf16 v[108:111], v[172:175], v[200:203], v[108:111]
	v_mfma_f32_16x16x32_bf16 v[108:111], v[176:179], v[204:207], v[108:111]
	v_mfma_f32_16x16x32_bf16 v[92:95], v[172:175], v[230:233], v[92:95]
	v_mfma_f32_16x16x32_bf16 v[92:95], v[176:179], v[234:237], v[92:95]
	v_mfma_f32_16x16x32_bf16 v[76:79], v[172:175], v[238:241], v[76:79]
	v_mfma_f32_16x16x32_bf16 v[76:79], v[176:179], v[242:245], v[76:79]
	v_mfma_f32_16x16x32_bf16 v[120:123], v[184:187], v[192:195], v[120:123]
	v_mfma_f32_16x16x32_bf16 v[120:123], v[188:191], v[196:199], v[120:123]
	v_mfma_f32_16x16x32_bf16 v[104:107], v[184:187], v[200:203], v[104:107]
	v_mfma_f32_16x16x32_bf16 v[104:107], v[188:191], v[204:207], v[104:107]
	v_mfma_f32_16x16x32_bf16 v[88:91], v[184:187], v[230:233], v[88:91]
	v_mfma_f32_16x16x32_bf16 v[88:91], v[188:191], v[234:237], v[88:91]
	v_mfma_f32_16x16x32_bf16 v[72:75], v[184:187], v[238:241], v[72:75]
	v_mfma_f32_16x16x32_bf16 v[72:75], v[188:191], v[242:245], v[72:75]
	s_setprio 0
	s_barrier
; #define PG8_STAGE(bufoff, gbase, voff) do { _Pragma("unroll") for (int _i = 0; _i < 2; ++_i) \
;         __builtin_amdgcn_global_load_lds((const unsigned*)((const char*)(gbase) + (voff)[_i]), (PG8_LAS unsigned*)(lds + (bufoff) + ldsw + _i * 8192), 16, 0, 0); } while (0)
; #define PG8_LDA(dst, b, h) do { _Pragma("unroll") for (int m = 0; m < 4; ++m) _Pragma("unroll") for (int k = 0; k < 2; ++k) dst[m][k] = *(const PG8_LAS bf16x8*)(lds + PG8_SA(b, h) + aoff + m * 2048 + k * 1024); } while (0)
; #define PG8_MMA(ai, bj, At, Bt) do { __builtin_amdgcn_s_setprio(1); _Pragma("unroll") for (int m = 0; m < 4; ++m) _Pragma("unroll") for (int n = 0; n < 2; ++n) _Pragma("unroll") for (int k = 0; k < 2; ++k) \
;         acc[ai][bj][m][n] = __builtin_amdgcn_mfma_f32_16x16x32_bf16(Bt[n][k], At[m][k], acc[ai][bj][m][n], 0, 0, 0); __builtin_amdgcn_s_setprio(0); } while (0)
; #define PG8_WAIT_V(n) asm volatile("s_waitcnt vmcnt(" #n ")" ::: "memory")
; #define PG8_WAIT_L(n) asm volatile("s_waitcnt lgkmcnt(" #n ")" ::: "memory")
; #define PG8_BAR __builtin_amdgcn_s_barrier()
; #define PG8_SCHED __builtin_amdgcn_sched_barrier(0)
; template <class Epi, class Sched, bool ALIGN_EPI = false, bool SP2 = false>
; __device__ __forceinline__ void gemm_phase(PG8_LAS unsigned char* lds, const Gemm g, const Sched& S, const Epi& E) {
;     ...
;         for (int t = 0; t < nt; t += 2) {
;     ...
;             PG8_LDA(At, 1, 1); PG8_STAGE(PG8_SB(1, 0), b3, voffB); PG8_STAGE(PG8_SB(1, 1), b3 + hstep, voffB); PG8_STAGE(PG8_SA(1, 0), a3, voffA);
;             PG8_WAIT_V(8); PG8_WAIT_L(0); PG8_BAR; PG8_MMA(1, 0, At, B0); PG8_MMA(1, 1, At, B1); PG8_BAR; PG8_SCHED;
	s_add_i32 s38, s91, s42
	v_lshl_add_u64 v[180:181], v[180:181], 0, s[24:25]
	s_mov_b32 m0, s38
	ds_read_b128 v[192:195], v167 offset:49152
	ds_read_b128 v[196:199], v167 offset:50176
	ds_read_b128 v[200:203], v167 offset:51200
	ds_read_b128 v[204:207], v167 offset:52224
	ds_read_b128 v[230:233], v167 offset:53248
	ds_read_b128 v[234:237], v167 offset:54272
	ds_read_b128 v[238:241], v167 offset:55296
	ds_read_b128 v[242:245], v167 offset:56320
	global_load_lds_dwordx4 v[180:181], off
	v_lshl_add_u64 v[180:181], v[208:209], 0, s[24:25]
	s_add_i32 m0, s38, 0x2000
	s_add_i32 s38, s79, s42
	global_load_lds_dwordx4 v[180:181], off
	v_lshl_add_u64 v[180:181], v[216:217], 0, s[24:25]
	s_mov_b32 m0, s38
	s_nop 0
	global_load_lds_dwordx4 v[180:181], off
	v_lshl_add_u64 v[180:181], v[224:225], 0, s[24:25]
	s_add_i32 m0, s38, 0x2000
	s_nop 0
	global_load_lds_dwordx4 v[180:181], off
	v_lshl_add_u64 v[180:181], v[226:227], 0, s[24:25]
	s_mov_b32 m0, s72
	s_nop 0
	global_load_lds_dwordx4 v[180:181], off
	v_lshl_add_u64 v[180:181], v[246:247], 0, s[24:25]
	s_mov_b32 m0, s73
	s_nop 0
	global_load_lds_dwordx4 v[180:181], off
	s_waitcnt vmcnt(8)
	s_waitcnt lgkmcnt(0)
	s_barrier
	s_setprio 1
	s_waitcnt lgkmcnt(0)
	v_mfma_f32_16x16x32_bf16 v[68:71], v[136:139], v[192:195], v[68:71]
	v_mfma_f32_16x16x32_bf16 v[68:71], v[140:143], v[196:199], v[68:71]
	v_mfma_f32_16x16x32_bf16 v[52:55], v[136:139], v[200:203], v[52:55]
	v_mfma_f32_16x16x32_bf16 v[52:55], v[140:143], v[204:207], v[52:55]
	v_mfma_f32_16x16x32_bf16 v[36:39], v[136:139], v[230:233], v[36:39]
	v_mfma_f32_16x16x32_bf16 v[36:39], v[140:143], v[234:237], v[36:39]
	v_mfma_f32_16x16x32_bf16 v[20:23], v[136:139], v[238:241], v[20:23]
	v_mfma_f32_16x16x32_bf16 v[20:23], v[140:143], v[242:245], v[20:23]
	v_mfma_f32_16x16x32_bf16 v[64:67], v[144:147], v[192:195], v[64:67]
	v_mfma_f32_16x16x32_bf16 v[64:67], v[148:151], v[196:199], v[64:67]
	v_mfma_f32_16x16x32_bf16 v[48:51], v[144:147], v[200:203], v[48:51]
	v_mfma_f32_16x16x32_bf16 v[48:51], v[148:151], v[204:207], v[48:51]
	v_mfma_f32_16x16x32_bf16 v[32:35], v[144:147], v[230:233], v[32:35]
	v_mfma_f32_16x16x32_bf16 v[32:35], v[148:151], v[234:237], v[32:35]
	v_mfma_f32_16x16x32_bf16 v[16:19], v[144:147], v[238:241], v[16:19]
	v_mfma_f32_16x16x32_bf16 v[16:19], v[148:151], v[242:245], v[16:19]
	s_setprio 0
	s_setprio 1
	v_mfma_f32_16x16x32_bf16 v[60:63], v[172:175], v[192:195], v[60:63]
	v_mfma_f32_16x16x32_bf16 v[60:63], v[176:179], v[196:199], v[60:63]
	v_mfma_f32_16x16x32_bf16 v[44:47], v[172:175], v[200:203], v[44:47]
	v_mfma_f32_16x16x32_bf16 v[44:47], v[176:179], v[204:207], v[44:47]
	v_mfma_f32_16x16x32_bf16 v[28:31], v[172:175], v[230:233], v[28:31]
	v_mfma_f32_16x16x32_bf16 v[28:31], v[176:179], v[234:237], v[28:31]
	v_mfma_f32_16x16x32_bf16 v[12:15], v[172:175], v[238:241], v[12:15]
	v_mfma_f32_16x16x32_bf16 v[12:15], v[176:179], v[242:245], v[12:15]
	v_mfma_f32_16x16x32_bf16 v[56:59], v[184:187], v[192:195], v[56:59]
	v_mfma_f32_16x16x32_bf16 v[56:59], v[188:191], v[196:199], v[56:59]
	v_mfma_f32_16x16x32_bf16 v[40:43], v[184:187], v[200:203], v[40:43]
	v_mfma_f32_16x16x32_bf16 v[40:43], v[188:191], v[204:207], v[40:43]
	v_mfma_f32_16x16x32_bf16 v[24:27], v[184:187], v[230:233], v[24:27]
	v_mfma_f32_16x16x32_bf16 v[24:27], v[188:191], v[234:237], v[24:27]
	v_mfma_f32_16x16x32_bf16 v[8:11], v[184:187], v[238:241], v[8:11]
	v_mfma_f32_16x16x32_bf16 v[8:11], v[188:191], v[242:245], v[8:11]
	s_setprio 0
	s_barrier
	s_add_u32 s0, s0, 0x100
	s_addc_u32 s1, s1, 0
	s_add_u32 s40, s40, 0x100
	s_addc_u32 s41, s41, 0
	s_cmp_ge_u32 s78, s9
	s_mov_b32 s38, s78
	s_cbranch_scc0 .LBB0_468

; #define PG8_STAGE(bufoff, gbase, voff) do { _Pragma("unroll") for (int _i = 0; _i < 2; ++_i) \
;         __builtin_amdgcn_global_load_lds((const unsigned*)((const char*)(gbase) + (voff)[_i]), (PG8_LAS unsigned*)(lds + (bufoff) + ldsw + _i * 8192), 16, 0, 0); } while (0)
; #define PG8_LDA(dst, b, h) do { _Pragma("unroll") for (int m = 0; m < 4; ++m) _Pragma("unroll") for (int k = 0; k < 2; ++k) dst[m][k] = *(const PG8_LAS bf16x8*)(lds + PG8_SA(b, h) + aoff + m * 2048 + k * 1024); } while (0)
; #define PG8_LDB(dst, b, h) do { _Pragma("unroll") for (int n = 0; n < 2; ++n) _Pragma("unroll") for (int k = 0; k < 2; ++k) dst[n][k] = *(const PG8_LAS bf16x8*)(lds + PG8_SB(b, h) + boff + n * 2048 + k * 1024); } while (0)
; #define PG8_MMA(ai, bj, At, Bt) do { __builtin_amdgcn_s_setprio(1); _Pragma("unroll") for (int m = 0; m < 4; ++m) _Pragma("unroll") for (int n = 0; n < 2; ++n) _Pragma("unroll") for (int k = 0; k < 2; ++k) \
;         acc[ai][bj][m][n] = __builtin_amdgcn_mfma_f32_16x16x32_bf16(Bt[n][k], At[m][k], acc[ai][bj][m][n], 0, 0, 0); __builtin_amdgcn_s_setprio(0); } while (0)
; #define PG8_WAIT_V(n) asm volatile("s_waitcnt vmcnt(" #n ")" ::: "memory")
; #define PG8_WAIT_L(n) asm volatile("s_waitcnt lgkmcnt(" #n ")" ::: "memory")
; template <class Epi, class Sched, bool ALIGN_EPI = false, bool SP2 = false>
; __device__ __forceinline__ void gemm_phase(PG8_LAS unsigned char* lds, const Gemm g, const Sched& S, const Epi& E) {
;     ...
;             const bool last = (t == nt - 2);
;             const char* a1 = cA + (size_t)(t + 1) * kstep;
;             const char* a2 = last ? nA : cA + (size_t)(t + 2) * kstep; const char* b2 = last ? nB : cB + (size_t)(t + 2) * kstep;
;             const char* a3 = a2 + kstep; const char* b3 = b2 + kstep;
;             if (last && has_next) S.a_ready(nxt);
;             if constexpr (SP2) {
;             PG8_LDB(B0, 0, 0); PG8_LDB(B1, 0, 1); PG8_SCHED; PG8_LDA(At, 0, 0); PG8_STAGE(PG8_SA(1, 1), a1 + hstep, voffA);
;             PG8_WAIT_V(8); PG8_WAIT_L(0); PG8_BAR; PG8_MMA(0, 0, At, B0); PG8_MMA(0, 1, At, B1); PG8_BAR; PG8_SCHED;
;             PG8_LDA(At, 0, 1); PG8_STAGE(PG8_SB(0, 0), b2, voffB); PG8_STAGE(PG8_SB(0, 1), b2 + hstep, voffB); PG8_STAGE(PG8_SA(0, 0), a2, voffA);
;             PG8_WAIT_V(8); PG8_WAIT_L(0); PG8_BAR; PG8_MMA(1, 0, At, B0); PG8_MMA(1, 1, At, B1); PG8_BAR; PG8_SCHED;
.LBB0_501:
	s_add_i32 s80, s4, 2
	s_add_u32 s81, s0, 0x80
	s_addc_u32 s5, s1, 0
	s_cmp_eq_u32 s33, s4
	s_cselect_b32 s5, s23, s5
	s_cselect_b32 s4, s22, s81
	s_cselect_b32 s83, s41, s43
	s_cselect_b32 s82, s40, s42
	s_add_i32 s81, 0, 0x14000
	v_add_u32_e32 v148, s19, v164
	v_add_u32_e32 v162, s81, v164
	ds_read_b128 v[136:139], v148
	ds_read_b128 v[140:143], v148 offset:1024
	ds_read_b128 v[144:147], v148 offset:2048
	ds_read_b128 v[148:151], v148 offset:3072
	ds_read_b128 v[174:177], v162
	ds_read_b128 v[178:181], v162 offset:1024
	ds_read_b128 v[184:187], v162 offset:2048
	ds_read_b128 v[188:191], v162 offset:3072
	v_lshl_add_u64 v[162:163], s[0:1], 0, v[158:159]
	s_add_i32 m0, s45, 0xc000
	ds_read_b128 v[192:195], v170
	ds_read_b128 v[196:199], v170 offset:1024
	ds_read_b128 v[200:203], v170 offset:2048
	ds_read_b128 v[204:207], v170 offset:3072
	ds_read_b128 v[230:233], v170 offset:4096
	ds_read_b128 v[234:237], v170 offset:5120
	ds_read_b128 v[238:241], v170 offset:6144
	ds_read_b128 v[242:245], v170 offset:7168
	global_load_lds_dwordx4 v[162:163], off
	v_lshl_add_u64 v[162:163], s[0:1], 0, v[160:161]
	s_add_i32 m0, s45, 0xe000
	s_nop 0
	global_load_lds_dwordx4 v[162:163], off
	s_waitcnt vmcnt(8)
	s_waitcnt lgkmcnt(0)
	s_barrier
	s_setprio 1
	s_waitcnt lgkmcnt(0)
	v_mfma_f32_16x16x32_bf16 v[132:135], v[136:139], v[192:195], v[132:135]
	v_mfma_f32_16x16x32_bf16 v[132:135], v[140:143], v[196:199], v[132:135]
	v_mfma_f32_16x16x32_bf16 v[116:119], v[136:139], v[200:203], v[116:119]
	v_mfma_f32_16x16x32_bf16 v[116:119], v[140:143], v[204:207], v[116:119]
	v_mfma_f32_16x16x32_bf16 v[100:103], v[136:139], v[230:233], v[100:103]
	v_mfma_f32_16x16x32_bf16 v[100:103], v[140:143], v[234:237], v[100:103]
	v_mfma_f32_16x16x32_bf16 v[84:87], v[136:139], v[238:241], v[84:87]
	v_mfma_f32_16x16x32_bf16 v[84:87], v[140:143], v[242:245], v[84:87]
	v_mfma_f32_16x16x32_bf16 v[128:131], v[144:147], v[192:195], v[128:131]
	v_mfma_f32_16x16x32_bf16 v[128:131], v[148:151], v[196:199], v[128:131]
	v_mfma_f32_16x16x32_bf16 v[112:115], v[144:147], v[200:203], v[112:115]
	v_mfma_f32_16x16x32_bf16 v[112:115], v[148:151], v[204:207], v[112:115]
	v_mfma_f32_16x16x32_bf16 v[96:99], v[144:147], v[230:233], v[96:99]
	v_mfma_f32_16x16x32_bf16 v[96:99], v[148:151], v[234:237], v[96:99]
	v_mfma_f32_16x16x32_bf16 v[80:83], v[144:147], v[238:241], v[80:83]
	v_mfma_f32_16x16x32_bf16 v[80:83], v[148:151], v[242:245], v[80:83]
	s_setprio 0
	s_setprio 1
	v_mfma_f32_16x16x32_bf16 v[124:127], v[174:177], v[192:195], v[124:127]
	v_mfma_f32_16x16x32_bf16 v[124:127], v[178:181], v[196:199], v[124:127]
	v_mfma_f32_16x16x32_bf16 v[108:111], v[174:177], v[200:203], v[108:111]
	v_mfma_f32_16x16x32_bf16 v[108:111], v[178:181], v[204:207], v[108:111]
	v_mfma_f32_16x16x32_bf16 v[92:95], v[174:177], v[230:233], v[92:95]
	v_mfma_f32_16x16x32_bf16 v[92:95], v[178:181], v[234:237], v[92:95]
	v_mfma_f32_16x16x32_bf16 v[76:79], v[174:177], v[238:241], v[76:79]
	v_mfma_f32_16x16x32_bf16 v[76:79], v[178:181], v[242:245], v[76:79]
	v_mfma_f32_16x16x32_bf16 v[120:123], v[184:187], v[192:195], v[120:123]
	v_mfma_f32_16x16x32_bf16 v[120:123], v[188:191], v[196:199], v[120:123]
	v_mfma_f32_16x16x32_bf16 v[104:107], v[184:187], v[200:203], v[104:107]
	v_mfma_f32_16x16x32_bf16 v[104:107], v[188:191], v[204:207], v[104:107]
	v_mfma_f32_16x16x32_bf16 v[88:91], v[184:187], v[230:233], v[88:91]
	v_mfma_f32_16x16x32_bf16 v[88:91], v[188:191], v[234:237], v[88:91]
	v_mfma_f32_16x16x32_bf16 v[72:75], v[184:187], v[238:241], v[72:75]
	v_mfma_f32_16x16x32_bf16 v[72:75], v[188:191], v[242:245], v[72:75]
	s_setprio 0
	s_barrier
	s_add_i32 s84, s19, s44
	v_lshl_add_u64 v[162:163], s[82:83], 0, v[152:153]
	s_mov_b32 m0, s84
	ds_read_b128 v[192:195], v170 offset:16384
	ds_read_b128 v[196:199], v170 offset:17408
	ds_read_b128 v[200:203], v170 offset:18432
	ds_read_b128 v[204:207], v170 offset:19456
	ds_read_b128 v[230:233], v170 offset:20480
	ds_read_b128 v[234:237], v170 offset:21504
	ds_read_b128 v[238:241], v170 offset:22528
	ds_read_b128 v[242:245], v170 offset:23552
	global_load_lds_dwordx4 v[162:163], off
	s_add_i32 m0, s84, 0x2000
	v_lshl_add_u64 v[208:209], s[82:83], 0, v[156:157]
	s_add_u32 s82, s82, s48
	s_addc_u32 s83, s83, s49
	s_add_i32 s81, s81, s44
	global_load_lds_dwordx4 v[208:209], off
	v_lshl_add_u64 v[246:247], s[82:83], 0, v[152:153]
	s_mov_b32 m0, s81
	v_lshl_add_u64 v[248:249], s[82:83], 0, v[156:157]
	global_load_lds_dwordx4 v[246:247], off
	s_add_i32 m0, s81, 0x2000
	v_lshl_add_u64 v[216:217], s[4:5], 0, v[2:3]
	global_load_lds_dwordx4 v[248:249], off
	s_mov_b32 m0, s45
	v_lshl_add_u64 v[224:225], s[4:5], 0, v[154:155]
	global_load_lds_dwordx4 v[216:217], off
	s_mov_b32 m0, s46
	s_nop 0
	global_load_lds_dwordx4 v[224:225], off
	s_waitcnt vmcnt(8)
	s_waitcnt lgkmcnt(0)
	s_barrier
; #define PG8_STAGE(bufoff, gbase, voff) do { _Pragma("unroll") for (int _i = 0; _i < 2; ++_i) \
;         __builtin_amdgcn_global_load_lds((const unsigned*)((const char*)(gbase) + (voff)[_i]), (PG8_LAS unsigned*)(lds + (bufoff) + ldsw + _i * 8192), 16, 0, 0); } while (0)
; #define PG8_LDA(dst, b, h) do { _Pragma("unroll") for (int m = 0; m < 4; ++m) _Pragma("unroll") for (int k = 0; k < 2; ++k) dst[m][k] = *(const PG8_LAS bf16x8*)(lds + PG8_SA(b, h) + aoff + m * 2048 + k * 1024); } while (0)
; #define PG8_LDB(dst, b, h) do { _Pragma("unroll") for (int n = 0; n < 2; ++n) _Pragma("unroll") for (int k = 0; k < 2; ++k) dst[n][k] = *(const PG8_LAS bf16x8*)(lds + PG8_SB(b, h) + boff + n * 2048 + k * 1024); } while (0)
; #define PG8_MMA(ai, bj, At, Bt) do { __builtin_amdgcn_s_setprio(1); _Pragma("unroll") for (int m = 0; m < 4; ++m) _Pragma("unroll") for (int n = 0; n < 2; ++n) _Pragma("unroll") for (int k = 0; k < 2; ++k) \
;         acc[ai][bj][m][n] = __builtin_amdgcn_mfma_f32_16x16x32_bf16(Bt[n][k], At[m][k], acc[ai][bj][m][n], 0, 0, 0); __builtin_amdgcn_s_setprio(0); } while (0)
; #define PG8_WAIT_V(n) asm volatile("s_waitcnt vmcnt(" #n ")" ::: "memory")
; #define PG8_WAIT_L(n) asm volatile("s_waitcnt lgkmcnt(" #n ")" ::: "memory")
; #define PG8_BAR __builtin_amdgcn_s_barrier()
; #define PG8_SCHED __builtin_amdgcn_sched_barrier(0)
; template <class Epi, class Sched, bool ALIGN_EPI = false, bool SP2 = false>
; __device__ __forceinline__ void gemm_phase(PG8_LAS unsigned char* lds, const Gemm g, const Sched& S, const Epi& E) {
;     ...
;             PG8_WAIT_V(8); PG8_WAIT_L(0); PG8_BAR; PG8_MMA(1, 0, At, B0); PG8_MMA(1, 1, At, B1); PG8_BAR; PG8_SCHED;
;             PG8_LDB(B0, 1, 0); PG8_LDB(B1, 1, 1); PG8_SCHED; PG8_LDA(At, 1, 0); PG8_STAGE(PG8_SA(0, 1), a2 + hstep, voffA);
;             PG8_WAIT_V(8); PG8_WAIT_L(0); PG8_BAR; PG8_MMA(0, 0, At, B0); PG8_MMA(0, 1, At, B1); PG8_BAR; PG8_SCHED;
	s_setprio 1
	s_waitcnt lgkmcnt(0)
	v_mfma_f32_16x16x32_bf16 v[68:71], v[136:139], v[192:195], v[68:71]
	v_mfma_f32_16x16x32_bf16 v[68:71], v[140:143], v[196:199], v[68:71]
	v_mfma_f32_16x16x32_bf16 v[52:55], v[136:139], v[200:203], v[52:55]
	v_mfma_f32_16x16x32_bf16 v[52:55], v[140:143], v[204:207], v[52:55]
	v_mfma_f32_16x16x32_bf16 v[36:39], v[136:139], v[230:233], v[36:39]
	v_mfma_f32_16x16x32_bf16 v[36:39], v[140:143], v[234:237], v[36:39]
	v_mfma_f32_16x16x32_bf16 v[20:23], v[136:139], v[238:241], v[20:23]
	v_mfma_f32_16x16x32_bf16 v[20:23], v[140:143], v[242:245], v[20:23]
	v_mfma_f32_16x16x32_bf16 v[64:67], v[144:147], v[192:195], v[64:67]
	v_mfma_f32_16x16x32_bf16 v[64:67], v[148:151], v[196:199], v[64:67]
	v_mfma_f32_16x16x32_bf16 v[48:51], v[144:147], v[200:203], v[48:51]
	v_mfma_f32_16x16x32_bf16 v[48:51], v[148:151], v[204:207], v[48:51]
	v_mfma_f32_16x16x32_bf16 v[32:35], v[144:147], v[230:233], v[32:35]
	v_mfma_f32_16x16x32_bf16 v[32:35], v[148:151], v[234:237], v[32:35]
	v_mfma_f32_16x16x32_bf16 v[16:19], v[144:147], v[238:241], v[16:19]
	v_mfma_f32_16x16x32_bf16 v[16:19], v[148:151], v[242:245], v[16:19]
	s_setprio 0
	s_setprio 1
	v_mfma_f32_16x16x32_bf16 v[60:63], v[174:177], v[192:195], v[60:63]
	v_mfma_f32_16x16x32_bf16 v[60:63], v[178:181], v[196:199], v[60:63]
	v_mfma_f32_16x16x32_bf16 v[44:47], v[174:177], v[200:203], v[44:47]
	v_mfma_f32_16x16x32_bf16 v[44:47], v[178:181], v[204:207], v[44:47]
	v_mfma_f32_16x16x32_bf16 v[28:31], v[174:177], v[230:233], v[28:31]
	v_mfma_f32_16x16x32_bf16 v[28:31], v[178:181], v[234:237], v[28:31]
	v_mfma_f32_16x16x32_bf16 v[12:15], v[174:177], v[238:241], v[12:15]
	v_mfma_f32_16x16x32_bf16 v[12:15], v[178:181], v[242:245], v[12:15]
	v_mfma_f32_16x16x32_bf16 v[56:59], v[184:187], v[192:195], v[56:59]
	v_mfma_f32_16x16x32_bf16 v[56:59], v[188:191], v[196:199], v[56:59]
	v_mfma_f32_16x16x32_bf16 v[40:43], v[184:187], v[200:203], v[40:43]
	v_mfma_f32_16x16x32_bf16 v[40:43], v[188:191], v[204:207], v[40:43]
	v_mfma_f32_16x16x32_bf16 v[24:27], v[184:187], v[230:233], v[24:27]
	v_mfma_f32_16x16x32_bf16 v[24:27], v[188:191], v[234:237], v[24:27]
	v_mfma_f32_16x16x32_bf16 v[8:11], v[184:187], v[238:241], v[8:11]
	v_mfma_f32_16x16x32_bf16 v[8:11], v[188:191], v[242:245], v[8:11]
	s_setprio 0
	s_barrier
	s_add_i32 s81, 0, 0x1c000
	v_add_u32_e32 v148, s91, v164
	v_add_u32_e32 v173, s81, v164
	ds_read_b128 v[136:139], v148
	ds_read_b128 v[140:143], v148 offset:1024
	ds_read_b128 v[144:147], v148 offset:2048
	ds_read_b128 v[148:151], v148 offset:3072
	ds_read_b128 v[174:177], v173
	ds_read_b128 v[178:181], v173 offset:1024
	ds_read_b128 v[184:187], v173 offset:2048
	ds_read_b128 v[188:191], v173 offset:3072
	s_add_u32 s4, s4, s48
	s_addc_u32 s5, s5, s49
	s_mov_b32 m0, s47
	v_lshl_add_u64 v[226:227], s[4:5], 0, v[2:3]
	ds_read_b128 v[192:195], v170 offset:32768
	ds_read_b128 v[196:199], v170 offset:33792
	ds_read_b128 v[200:203], v170 offset:34816
	ds_read_b128 v[204:207], v170 offset:35840
	ds_read_b128 v[230:233], v170 offset:36864
	ds_read_b128 v[234:237], v170 offset:37888
	ds_read_b128 v[238:241], v170 offset:38912
	ds_read_b128 v[242:245], v170 offset:39936
	global_load_lds_dwordx4 v[226:227], off
	v_lshl_add_u64 v[226:227], s[4:5], 0, v[154:155]
	s_mov_b32 m0, s52
	s_nop 0
	global_load_lds_dwordx4 v[226:227], off
	s_waitcnt vmcnt(8)
	s_waitcnt lgkmcnt(0)
	s_barrier
	s_setprio 1
	s_waitcnt lgkmcnt(0)
	v_mfma_f32_16x16x32_bf16 v[132:135], v[136:139], v[192:195], v[132:135]
	v_mfma_f32_16x16x32_bf16 v[132:135], v[140:143], v[196:199], v[132:135]
	v_mfma_f32_16x16x32_bf16 v[116:119], v[136:139], v[200:203], v[116:119]
	v_mfma_f32_16x16x32_bf16 v[116:119], v[140:143], v[204:207], v[116:119]
	v_mfma_f32_16x16x32_bf16 v[100:103], v[136:139], v[230:233], v[100:103]
	v_mfma_f32_16x16x32_bf16 v[100:103], v[140:143], v[234:237], v[100:103]
	v_mfma_f32_16x16x32_bf16 v[84:87], v[136:139], v[238:241], v[84:87]
	v_mfma_f32_16x16x32_bf16 v[84:87], v[140:143], v[242:245], v[84:87]
	v_mfma_f32_16x16x32_bf16 v[128:131], v[144:147], v[192:195], v[128:131]
	v_mfma_f32_16x16x32_bf16 v[128:131], v[148:151], v[196:199], v[128:131]
	v_mfma_f32_16x16x32_bf16 v[112:115], v[144:147], v[200:203], v[112:115]
	v_mfma_f32_16x16x32_bf16 v[112:115], v[148:151], v[204:207], v[112:115]
	v_mfma_f32_16x16x32_bf16 v[96:99], v[144:147], v[230:233], v[96:99]
	v_mfma_f32_16x16x32_bf16 v[96:99], v[148:151], v[234:237], v[96:99]
	v_mfma_f32_16x16x32_bf16 v[80:83], v[144:147], v[238:241], v[80:83]
	v_mfma_f32_16x16x32_bf16 v[80:83], v[148:151], v[242:245], v[80:83]
	s_setprio 0
	s_setprio 1
	v_mfma_f32_16x16x32_bf16 v[124:127], v[174:177], v[192:195], v[124:127]
	v_mfma_f32_16x16x32_bf16 v[124:127], v[178:181], v[196:199], v[124:127]
	v_mfma_f32_16x16x32_bf16 v[108:111], v[174:177], v[200:203], v[108:111]
	v_mfma_f32_16x16x32_bf16 v[108:111], v[178:181], v[204:207], v[108:111]
	v_mfma_f32_16x16x32_bf16 v[92:95], v[174:177], v[230:233], v[92:95]
	v_mfma_f32_16x16x32_bf16 v[92:95], v[178:181], v[234:237], v[92:95]
	v_mfma_f32_16x16x32_bf16 v[76:79], v[174:177], v[238:241], v[76:79]
	v_mfma_f32_16x16x32_bf16 v[76:79], v[178:181], v[242:245], v[76:79]
	v_mfma_f32_16x16x32_bf16 v[120:123], v[184:187], v[192:195], v[120:123]
	v_mfma_f32_16x16x32_bf16 v[120:123], v[188:191], v[196:199], v[120:123]
	v_mfma_f32_16x16x32_bf16 v[104:107], v[184:187], v[200:203], v[104:107]
	v_mfma_f32_16x16x32_bf16 v[104:107], v[188:191], v[204:207], v[104:107]
	v_mfma_f32_16x16x32_bf16 v[88:91], v[184:187], v[230:233], v[88:91]
	v_mfma_f32_16x16x32_bf16 v[88:91], v[188:191], v[234:237], v[88:91]
	v_mfma_f32_16x16x32_bf16 v[72:75], v[184:187], v[238:241], v[72:75]
	v_mfma_f32_16x16x32_bf16 v[72:75], v[188:191], v[242:245], v[72:75]
	s_setprio 0
	s_barrier
; #define PG8_STAGE(bufoff, gbase, voff) do { _Pragma("unroll") for (int _i = 0; _i < 2; ++_i) \
;         __builtin_amdgcn_global_load_lds((const unsigned*)((const char*)(gbase) + (voff)[_i]), (PG8_LAS unsigned*)(lds + (bufoff) + ldsw + _i * 8192), 16, 0, 0); } while (0)
; #define PG8_LDA(dst, b, h) do { _Pragma("unroll") for (int m = 0; m < 4; ++m) _Pragma("unroll") for (int k = 0; k < 2; ++k) dst[m][k] = *(const PG8_LAS bf16x8*)(lds + PG8_SA(b, h) + aoff + m * 2048 + k * 1024); } while (0)
; #define PG8_MMA(ai, bj, At, Bt) do { __builtin_amdgcn_s_setprio(1); _Pragma("unroll") for (int m = 0; m < 4; ++m) _Pragma("unroll") for (int n = 0; n < 2; ++n) _Pragma("unroll") for (int k = 0; k < 2; ++k) \
;         acc[ai][bj][m][n] = __builtin_amdgcn_mfma_f32_16x16x32_bf16(Bt[n][k], At[m][k], acc[ai][bj][m][n], 0, 0, 0); __builtin_amdgcn_s_setprio(0); } while (0)
; #define PG8_WAIT_V(n) asm volatile("s_waitcnt vmcnt(" #n ")" ::: "memory")
; #define PG8_WAIT_L(n) asm volatile("s_waitcnt lgkmcnt(" #n ")" ::: "memory")
; #define PG8_BAR __builtin_amdgcn_s_barrier()
; #define PG8_SCHED __builtin_amdgcn_sched_barrier(0)
; template <class Epi, class Sched, bool ALIGN_EPI = false, bool SP2 = false>
; __device__ __forceinline__ void gemm_phase(PG8_LAS unsigned char* lds, const Gemm g, const Sched& S, const Epi& E) {
;     ...
;         for (int t = 0; t < nt; t += 2) {
;     ...
;             PG8_LDA(At, 1, 1); PG8_STAGE(PG8_SB(1, 0), b3, voffB); PG8_STAGE(PG8_SB(1, 1), b3 + hstep, voffB); PG8_STAGE(PG8_SA(1, 0), a3, voffA);
;             PG8_WAIT_V(8); PG8_WAIT_L(0); PG8_BAR; PG8_MMA(1, 0, At, B0); PG8_MMA(1, 1, At, B1); PG8_BAR; PG8_SCHED;
	s_add_i32 s4, s91, s44
	v_lshl_add_u64 v[162:163], v[162:163], 0, s[24:25]
	s_mov_b32 m0, s4
	ds_read_b128 v[192:195], v170 offset:49152
	ds_read_b128 v[196:199], v170 offset:50176
	ds_read_b128 v[200:203], v170 offset:51200
	ds_read_b128 v[204:207], v170 offset:52224
	ds_read_b128 v[230:233], v170 offset:53248
	ds_read_b128 v[234:237], v170 offset:54272
	ds_read_b128 v[238:241], v170 offset:55296
	ds_read_b128 v[242:245], v170 offset:56320
	global_load_lds_dwordx4 v[162:163], off
	v_lshl_add_u64 v[162:163], v[208:209], 0, s[24:25]
	s_add_i32 m0, s4, 0x2000
	s_add_i32 s4, s81, s44
	global_load_lds_dwordx4 v[162:163], off
	v_lshl_add_u64 v[162:163], v[246:247], 0, s[24:25]
	s_mov_b32 m0, s4
	s_nop 0
	global_load_lds_dwordx4 v[162:163], off
	v_lshl_add_u64 v[162:163], v[248:249], 0, s[24:25]
	s_add_i32 m0, s4, 0x2000
	s_nop 0
	global_load_lds_dwordx4 v[162:163], off
	v_lshl_add_u64 v[162:163], v[216:217], 0, s[24:25]
	s_mov_b32 m0, s53
	s_nop 0
	global_load_lds_dwordx4 v[162:163], off
	v_lshl_add_u64 v[162:163], v[224:225], 0, s[24:25]
	s_mov_b32 m0, s72
	s_nop 0
	global_load_lds_dwordx4 v[162:163], off
	s_waitcnt vmcnt(8)
	s_waitcnt lgkmcnt(0)
	s_barrier
	s_setprio 1
	s_waitcnt lgkmcnt(0)
	v_mfma_f32_16x16x32_bf16 v[68:71], v[136:139], v[192:195], v[68:71]
	v_mfma_f32_16x16x32_bf16 v[68:71], v[140:143], v[196:199], v[68:71]
	v_mfma_f32_16x16x32_bf16 v[52:55], v[136:139], v[200:203], v[52:55]
	v_mfma_f32_16x16x32_bf16 v[52:55], v[140:143], v[204:207], v[52:55]
	v_mfma_f32_16x16x32_bf16 v[36:39], v[136:139], v[230:233], v[36:39]
	v_mfma_f32_16x16x32_bf16 v[36:39], v[140:143], v[234:237], v[36:39]
	v_mfma_f32_16x16x32_bf16 v[20:23], v[136:139], v[238:241], v[20:23]
	v_mfma_f32_16x16x32_bf16 v[20:23], v[140:143], v[242:245], v[20:23]
	v_mfma_f32_16x16x32_bf16 v[64:67], v[144:147], v[192:195], v[64:67]
	v_mfma_f32_16x16x32_bf16 v[64:67], v[148:151], v[196:199], v[64:67]
	v_mfma_f32_16x16x32_bf16 v[48:51], v[144:147], v[200:203], v[48:51]
	v_mfma_f32_16x16x32_bf16 v[48:51], v[148:151], v[204:207], v[48:51]
	v_mfma_f32_16x16x32_bf16 v[32:35], v[144:147], v[230:233], v[32:35]
	v_mfma_f32_16x16x32_bf16 v[32:35], v[148:151], v[234:237], v[32:35]
	v_mfma_f32_16x16x32_bf16 v[16:19], v[144:147], v[238:241], v[16:19]
	v_mfma_f32_16x16x32_bf16 v[16:19], v[148:151], v[242:245], v[16:19]
	s_setprio 0
	s_setprio 1
	v_mfma_f32_16x16x32_bf16 v[60:63], v[174:177], v[192:195], v[60:63]
	v_mfma_f32_16x16x32_bf16 v[60:63], v[178:181], v[196:199], v[60:63]
	v_mfma_f32_16x16x32_bf16 v[44:47], v[174:177], v[200:203], v[44:47]
	v_mfma_f32_16x16x32_bf16 v[44:47], v[178:181], v[204:207], v[44:47]
	v_mfma_f32_16x16x32_bf16 v[28:31], v[174:177], v[230:233], v[28:31]
	v_mfma_f32_16x16x32_bf16 v[28:31], v[178:181], v[234:237], v[28:31]
	v_mfma_f32_16x16x32_bf16 v[12:15], v[174:177], v[238:241], v[12:15]
	v_mfma_f32_16x16x32_bf16 v[12:15], v[178:181], v[242:245], v[12:15]
	v_mfma_f32_16x16x32_bf16 v[56:59], v[184:187], v[192:195], v[56:59]
	v_mfma_f32_16x16x32_bf16 v[56:59], v[188:191], v[196:199], v[56:59]
	v_mfma_f32_16x16x32_bf16 v[40:43], v[184:187], v[200:203], v[40:43]
	v_mfma_f32_16x16x32_bf16 v[40:43], v[188:191], v[204:207], v[40:43]
	v_mfma_f32_16x16x32_bf16 v[24:27], v[184:187], v[230:233], v[24:27]
	v_mfma_f32_16x16x32_bf16 v[24:27], v[188:191], v[234:237], v[24:27]
	v_mfma_f32_16x16x32_bf16 v[8:11], v[184:187], v[238:241], v[8:11]
	v_mfma_f32_16x16x32_bf16 v[8:11], v[188:191], v[242:245], v[8:11]
	s_setprio 0
	s_barrier
	s_add_u32 s0, s0, 0x100
	s_addc_u32 s1, s1, 0
	s_add_u32 s42, s42, 0x100
	s_addc_u32 s43, s43, 0
	s_cmp_ge_u32 s80, s9
	s_mov_b32 s4, s80
	s_cbranch_scc0 .LBB0_501
